# speedup vs baseline: 1.0156x; 1.0054x over previous
; #define LDA(dst, b, h) for (int m = 0; m < 4; ++m) for (int k = 0; k < 2; ++k) \
;     dst[m][k] = *reinterpret_cast<const bf16x8*>((char*)SA(b, h) + lds_byte(wr * 64 + m * 16 + fr, k * 32 + fq * 8))
; #define LDB(dst, b, h) for (int n = 0; n < 2; ++n) for (int k = 0; k < 2; ++k) \
;     dst[n][k] = *reinterpret_cast<const bf16x8*>((char*)SB(b, h) + lds_byte(wc * 32 + n * 16 + fr, k * 32 + fq * 8))
; #define MMA(ai, bj, At, Bt_) do { __builtin_amdgcn_s_setprio(1); \
;     for (int m = 0; m < 4; ++m) for (int n = 0; n < 2; ++n) for (int k = 0; k < 2; ++k) \
;       acc[ai][bj][m][n] = __builtin_amdgcn_mfma_f32_16x16x32_bf16(At[m][k], Bt_[n][k], acc[ai][bj][m][n], 0, 0, 0); \
;     __builtin_amdgcn_s_setprio(0); } while (0)
; #define WAIT_L(n) asm volatile("s_waitcnt lgkmcnt(" #n ")" ::: "memory")
; #define BAR __builtin_amdgcn_s_barrier()
; #define SCHED __builtin_amdgcn_sched_barrier(0)
;     ...
;       LDB(B0, 0, 0); SCHED; LDA(At, 0, 0); STAGE(SA(1, 1), A, brow + HALF, t + 1);
;       WAIT_L(8); BAR; WAIT_L(0); MMA(0, 0, At, B0); BAR; SCHED;
;       LDB(B1, 0, 1); STAGE(SB(0, 0), Bt, bcol, t + 2);
;       BAR; WAIT_L(0); MMA(0, 1, At, B1); BAR;
;       LDA(At, 0, 1); STAGE(SA(0, 0), A, brow, t + 2);
;       BAR; WAIT_L(0); MMA(1, 0, At, B0); BAR; SCHED;
.LBB0_98:
	v_add_u32_e32 v143, s2, v142
	ds_read_b128 v[146:149], v143
	ds_read_b128 v[150:153], v143 offset:1024
	ds_read_b128 v[154:157], v143 offset:2048
	ds_read_b128 v[158:161], v143 offset:3072
	s_add_u32 s66, s55, s4
	s_addc_u32 s67, s57, s5
	s_add_i32 s63, s15, 0xc000
	ds_read_b128 v[162:165], v133
	ds_read_b128 v[184:187], v133 offset:1024
	ds_read_b128 v[188:191], v134
	ds_read_b128 v[192:195], v134 offset:1024
	ds_read_b128 v[196:199], v137
	ds_read_b128 v[200:203], v137 offset:1024
	ds_read_b128 v[204:207], v139
	ds_read_b128 v[208:211], v139 offset:1024
	s_mov_b32 m0, s63
	v_lshl_add_u64 v[144:145], s[66:67], 0, v[0:1]
	s_add_i32 s59, s15, 0xe000
	global_load_lds_dwordx4 v[144:145], off
	v_lshl_add_u64 v[144:145], s[66:67], 0, v[140:141]
	s_mov_b32 m0, s59
	s_nop 0
	global_load_lds_dwordx4 v[144:145], off
	s_waitcnt lgkmcnt(8)
	s_barrier
	s_waitcnt lgkmcnt(0)
	s_waitcnt lgkmcnt(0)
	v_mfma_f32_16x16x32_bf16 v[126:129], v[162:165], v[146:149], v[126:129]
	v_mfma_f32_16x16x32_bf16 v[122:125], v[162:165], v[154:157], v[122:125]
	v_mfma_f32_16x16x32_bf16 v[118:121], v[188:191], v[146:149], v[118:121]
	v_mfma_f32_16x16x32_bf16 v[114:117], v[188:191], v[154:157], v[114:117]
	v_mfma_f32_16x16x32_bf16 v[110:113], v[196:199], v[146:149], v[110:113]
	v_mfma_f32_16x16x32_bf16 v[106:109], v[196:199], v[154:157], v[106:109]
	v_mfma_f32_16x16x32_bf16 v[102:105], v[204:207], v[146:149], v[102:105]
	v_mfma_f32_16x16x32_bf16 v[98:101], v[204:207], v[154:157], v[98:101]
	v_mfma_f32_16x16x32_bf16 v[126:129], v[184:187], v[150:153], v[126:129]
	v_mfma_f32_16x16x32_bf16 v[122:125], v[184:187], v[158:161], v[122:125]
	v_mfma_f32_16x16x32_bf16 v[118:121], v[192:195], v[150:153], v[118:121]
	v_mfma_f32_16x16x32_bf16 v[114:117], v[192:195], v[158:161], v[114:117]
	v_mfma_f32_16x16x32_bf16 v[110:113], v[200:203], v[150:153], v[110:113]
	v_mfma_f32_16x16x32_bf16 v[106:109], v[200:203], v[158:161], v[106:109]
	v_mfma_f32_16x16x32_bf16 v[102:105], v[208:211], v[150:153], v[102:105]
	v_mfma_f32_16x16x32_bf16 v[98:101], v[208:211], v[158:161], v[98:101]
	s_barrier
	s_add_i32 s58, s58, 2
	s_add_u32 s65, s50, s4
	s_addc_u32 s70, s51, s5
	s_add_u32 s66, s65, 0x100
	v_add_u32_e32 v144, s76, v142
	s_addc_u32 s67, s70, 0
	s_mov_b32 m0, s16
	ds_read_b128 v[212:215], v144
	ds_read_b128 v[216:219], v144 offset:1024
	ds_read_b128 v[220:223], v144 offset:2048
	ds_read_b128 v[224:227], v144 offset:3072
	s_nop 0
	v_lshl_add_u64 v[166:167], s[66:67], 0, v[0:1]
	global_load_lds_dwordx4 v[166:167], off
	v_lshl_add_u64 v[166:167], s[66:67], 0, v[140:141]
	s_mov_b32 m0, s17
	s_nop 0
	global_load_lds_dwordx4 v[166:167], off
	s_barrier
	s_waitcnt lgkmcnt(0)
	s_waitcnt lgkmcnt(0)
	v_mfma_f32_16x16x32_bf16 v[94:97], v[162:165], v[212:215], v[94:97]
	v_mfma_f32_16x16x32_bf16 v[90:93], v[162:165], v[220:223], v[90:93]
	v_mfma_f32_16x16x32_bf16 v[86:89], v[188:191], v[212:215], v[86:89]
	v_mfma_f32_16x16x32_bf16 v[82:85], v[188:191], v[220:223], v[82:85]
	v_mfma_f32_16x16x32_bf16 v[78:81], v[196:199], v[212:215], v[78:81]
	v_mfma_f32_16x16x32_bf16 v[74:77], v[196:199], v[220:223], v[74:77]
	v_mfma_f32_16x16x32_bf16 v[70:73], v[204:207], v[212:215], v[70:73]
	v_mfma_f32_16x16x32_bf16 v[66:69], v[204:207], v[220:223], v[66:69]
	v_mfma_f32_16x16x32_bf16 v[94:97], v[184:187], v[216:219], v[94:97]
	v_mfma_f32_16x16x32_bf16 v[90:93], v[184:187], v[224:227], v[90:93]
	v_mfma_f32_16x16x32_bf16 v[86:89], v[192:195], v[216:219], v[86:89]
	v_mfma_f32_16x16x32_bf16 v[82:85], v[192:195], v[224:227], v[82:85]
	v_mfma_f32_16x16x32_bf16 v[78:81], v[200:203], v[216:219], v[78:81]
	v_mfma_f32_16x16x32_bf16 v[74:77], v[200:203], v[224:227], v[74:77]
	v_mfma_f32_16x16x32_bf16 v[70:73], v[208:211], v[216:219], v[70:73]
	v_mfma_f32_16x16x32_bf16 v[66:69], v[208:211], v[224:227], v[66:69]
	s_barrier
	s_add_u32 s71, s44, s4
	s_addc_u32 s72, s45, s5
	s_add_u32 s66, s71, 0x100
	s_addc_u32 s67, s72, 0
	s_mov_b32 m0, s15
	ds_read_b128 v[162:165], v133 offset:16384
	ds_read_b128 v[184:187], v133 offset:17408
	ds_read_b128 v[188:191], v134 offset:16384
	ds_read_b128 v[192:195], v134 offset:17408
	ds_read_b128 v[196:199], v137 offset:16384
	ds_read_b128 v[200:203], v137 offset:17408
	ds_read_b128 v[204:207], v139 offset:16384
	ds_read_b128 v[208:211], v139 offset:17408
	s_nop 0
	v_lshl_add_u64 v[166:167], s[66:67], 0, v[0:1]
	global_load_lds_dwordx4 v[166:167], off
	v_lshl_add_u64 v[166:167], s[66:67], 0, v[140:141]
	s_mov_b32 m0, s18
	s_nop 0
	global_load_lds_dwordx4 v[166:167], off
	s_barrier
	s_waitcnt lgkmcnt(0)
	s_waitcnt lgkmcnt(0)
	v_mfma_f32_16x16x32_bf16 v[62:65], v[162:165], v[146:149], v[62:65]
	v_mfma_f32_16x16x32_bf16 v[58:61], v[162:165], v[154:157], v[58:61]
	v_mfma_f32_16x16x32_bf16 v[54:57], v[188:191], v[146:149], v[54:57]
	v_mfma_f32_16x16x32_bf16 v[50:53], v[188:191], v[154:157], v[50:53]
	v_mfma_f32_16x16x32_bf16 v[46:49], v[196:199], v[146:149], v[46:49]
	v_mfma_f32_16x16x32_bf16 v[42:45], v[196:199], v[154:157], v[42:45]
	v_mfma_f32_16x16x32_bf16 v[38:41], v[204:207], v[146:149], v[38:41]
	v_mfma_f32_16x16x32_bf16 v[34:37], v[204:207], v[154:157], v[34:37]
	v_mfma_f32_16x16x32_bf16 v[62:65], v[184:187], v[150:153], v[62:65]
	v_mfma_f32_16x16x32_bf16 v[58:61], v[184:187], v[158:161], v[58:61]
	v_mfma_f32_16x16x32_bf16 v[54:57], v[192:195], v[150:153], v[54:57]
	v_mfma_f32_16x16x32_bf16 v[50:53], v[192:195], v[158:161], v[50:53]
	v_mfma_f32_16x16x32_bf16 v[46:49], v[200:203], v[150:153], v[46:49]
	v_mfma_f32_16x16x32_bf16 v[42:45], v[200:203], v[158:161], v[42:45]
	v_mfma_f32_16x16x32_bf16 v[38:41], v[208:211], v[150:153], v[38:41]
	v_mfma_f32_16x16x32_bf16 v[34:37], v[208:211], v[158:161], v[34:37]
	s_barrier
; #define LDA(dst, b, h) for (int m = 0; m < 4; ++m) for (int k = 0; k < 2; ++k) \
;     dst[m][k] = *reinterpret_cast<const bf16x8*>((char*)SA(b, h) + lds_byte(wr * 64 + m * 16 + fr, k * 32 + fq * 8))
; #define LDB(dst, b, h) for (int n = 0; n < 2; ++n) for (int k = 0; k < 2; ++k) \
;     dst[n][k] = *reinterpret_cast<const bf16x8*>((char*)SB(b, h) + lds_byte(wc * 32 + n * 16 + fr, k * 32 + fq * 8))
; #define MMA(ai, bj, At, Bt_) do { __builtin_amdgcn_s_setprio(1); \
;     for (int m = 0; m < 4; ++m) for (int n = 0; n < 2; ++n) for (int k = 0; k < 2; ++k) \
;       acc[ai][bj][m][n] = __builtin_amdgcn_mfma_f32_16x16x32_bf16(At[m][k], Bt_[n][k], acc[ai][bj][m][n], 0, 0, 0); \
;     __builtin_amdgcn_s_setprio(0); } while (0)
; #define WAIT_V(n) asm volatile("s_waitcnt vmcnt(" #n ")" ::: "memory")
; #define WAIT_L(n) asm volatile("s_waitcnt lgkmcnt(" #n ")" ::: "memory")
; #define BAR __builtin_amdgcn_s_barrier()
; #define SCHED __builtin_amdgcn_sched_barrier(0)
;     ...
;       STAGE(SB(0, 1), Bt, bcol + HALF, t + 2);
;       WAIT_V(6); BAR; MMA(1, 1, At, B1); BAR;
;       LDB(B0, 1, 0); SCHED; LDA(At, 1, 0); STAGE(SA(0, 1), A, brow + HALF, t + 2);
;       WAIT_L(8); BAR; WAIT_L(0); MMA(0, 0, At, B0); BAR; SCHED;
;       LDB(B1, 1, 1); STAGE(SB(1, 0), Bt, bcol, t + 3);
;       BAR; WAIT_L(0); MMA(0, 1, At, B1); BAR;
;       LDA(At, 1, 1); STAGE(SA(1, 0), A, brow, t + 3);
	s_add_u32 s73, s6, s4
	s_addc_u32 s82, s7, s5
	s_add_u32 s66, s73, 0x160100
	s_addc_u32 s67, s82, 0
	s_mov_b32 m0, s19
	s_nop 0
	v_lshl_add_u64 v[146:147], s[66:67], 0, v[0:1]
	global_load_lds_dwordx4 v[146:147], off
	v_lshl_add_u64 v[146:147], s[66:67], 0, v[140:141]
	s_mov_b32 m0, s21
	s_nop 0
	global_load_lds_dwordx4 v[146:147], off
	s_waitcnt vmcnt(6)
	s_barrier
	v_mfma_f32_16x16x32_bf16 v[30:33], v[162:165], v[212:215], v[30:33]
	v_mfma_f32_16x16x32_bf16 v[26:29], v[162:165], v[220:223], v[26:29]
	v_mfma_f32_16x16x32_bf16 v[22:25], v[188:191], v[212:215], v[22:25]
	v_mfma_f32_16x16x32_bf16 v[18:21], v[188:191], v[220:223], v[18:21]
	v_mfma_f32_16x16x32_bf16 v[14:17], v[196:199], v[212:215], v[14:17]
	v_mfma_f32_16x16x32_bf16 v[10:13], v[196:199], v[220:223], v[10:13]
	v_mfma_f32_16x16x32_bf16 v[6:9], v[204:207], v[212:215], v[6:9]
	v_mfma_f32_16x16x32_bf16 v[2:5], v[204:207], v[220:223], v[2:5]
	v_mfma_f32_16x16x32_bf16 v[30:33], v[184:187], v[216:219], v[30:33]
	v_mfma_f32_16x16x32_bf16 v[26:29], v[184:187], v[224:227], v[26:29]
	v_mfma_f32_16x16x32_bf16 v[22:25], v[192:195], v[216:219], v[22:25]
	v_mfma_f32_16x16x32_bf16 v[18:21], v[192:195], v[224:227], v[18:21]
	v_mfma_f32_16x16x32_bf16 v[14:17], v[200:203], v[216:219], v[14:17]
	v_mfma_f32_16x16x32_bf16 v[10:13], v[200:203], v[224:227], v[10:13]
	v_mfma_f32_16x16x32_bf16 v[6:9], v[208:211], v[216:219], v[6:9]
	v_mfma_f32_16x16x32_bf16 v[2:5], v[208:211], v[224:227], v[2:5]
	s_barrier
	v_add_u32_e32 v145, s77, v142
	ds_read_b128 v[148:151], v145
	ds_read_b128 v[152:155], v145 offset:1024
	ds_read_b128 v[156:159], v145 offset:2048
	ds_read_b128 v[160:163], v145 offset:3072
	s_add_u32 s66, s71, 0x160100
	s_addc_u32 s67, s72, 0
	s_mov_b32 m0, s30
	ds_read_b128 v[164:167], v133 offset:32768
	ds_read_b128 v[184:187], v133 offset:33792
	ds_read_b128 v[188:191], v134 offset:32768
	ds_read_b128 v[192:195], v134 offset:33792
	ds_read_b128 v[196:199], v137 offset:32768
	ds_read_b128 v[200:203], v137 offset:33792
	ds_read_b128 v[204:207], v139 offset:32768
	ds_read_b128 v[208:211], v139 offset:33792
	s_nop 0
	v_lshl_add_u64 v[146:147], s[66:67], 0, v[0:1]
	global_load_lds_dwordx4 v[146:147], off
	v_lshl_add_u64 v[146:147], s[66:67], 0, v[140:141]
	s_mov_b32 m0, s31
	s_nop 0
	global_load_lds_dwordx4 v[146:147], off
	s_waitcnt lgkmcnt(8)
	s_barrier
	s_waitcnt lgkmcnt(0)
	s_waitcnt lgkmcnt(0)
	v_mfma_f32_16x16x32_bf16 v[126:129], v[164:167], v[148:151], v[126:129]
	v_mfma_f32_16x16x32_bf16 v[122:125], v[164:167], v[156:159], v[122:125]
	v_mfma_f32_16x16x32_bf16 v[118:121], v[188:191], v[148:151], v[118:121]
	v_mfma_f32_16x16x32_bf16 v[114:117], v[188:191], v[156:159], v[114:117]
	v_mfma_f32_16x16x32_bf16 v[110:113], v[196:199], v[148:151], v[110:113]
	v_mfma_f32_16x16x32_bf16 v[106:109], v[196:199], v[156:159], v[106:109]
	v_mfma_f32_16x16x32_bf16 v[102:105], v[204:207], v[148:151], v[102:105]
	v_mfma_f32_16x16x32_bf16 v[98:101], v[204:207], v[156:159], v[98:101]
	v_mfma_f32_16x16x32_bf16 v[126:129], v[184:187], v[152:155], v[126:129]
	v_mfma_f32_16x16x32_bf16 v[122:125], v[184:187], v[160:163], v[122:125]
	v_mfma_f32_16x16x32_bf16 v[118:121], v[192:195], v[152:155], v[118:121]
	v_mfma_f32_16x16x32_bf16 v[114:117], v[192:195], v[160:163], v[114:117]
	v_mfma_f32_16x16x32_bf16 v[110:113], v[200:203], v[152:155], v[110:113]
	v_mfma_f32_16x16x32_bf16 v[106:109], v[200:203], v[160:163], v[106:109]
	v_mfma_f32_16x16x32_bf16 v[102:105], v[208:211], v[152:155], v[102:105]
	v_mfma_f32_16x16x32_bf16 v[98:101], v[208:211], v[160:163], v[98:101]
	s_barrier
	s_add_u32 s66, s65, 0x180
	v_add_u32_e32 v146, s78, v142
	s_addc_u32 s67, s70, 0
	s_mov_b32 m0, s34
	ds_read_b128 v[212:215], v146
	ds_read_b128 v[216:219], v146 offset:1024
	ds_read_b128 v[220:223], v146 offset:2048
	ds_read_b128 v[224:227], v146 offset:3072
	s_nop 0
	v_lshl_add_u64 v[228:229], s[66:67], 0, v[0:1]
	global_load_lds_dwordx4 v[228:229], off
	v_lshl_add_u64 v[228:229], s[66:67], 0, v[140:141]
	s_mov_b32 m0, s35
	s_nop 0
	global_load_lds_dwordx4 v[228:229], off
	s_barrier
	s_waitcnt lgkmcnt(0)
	s_waitcnt lgkmcnt(0)
	v_mfma_f32_16x16x32_bf16 v[94:97], v[164:167], v[212:215], v[94:97]
	v_mfma_f32_16x16x32_bf16 v[90:93], v[164:167], v[220:223], v[90:93]
	v_mfma_f32_16x16x32_bf16 v[86:89], v[188:191], v[212:215], v[86:89]
	v_mfma_f32_16x16x32_bf16 v[82:85], v[188:191], v[220:223], v[82:85]
	v_mfma_f32_16x16x32_bf16 v[78:81], v[196:199], v[212:215], v[78:81]
	v_mfma_f32_16x16x32_bf16 v[74:77], v[196:199], v[220:223], v[74:77]
	v_mfma_f32_16x16x32_bf16 v[70:73], v[204:207], v[212:215], v[70:73]
	v_mfma_f32_16x16x32_bf16 v[66:69], v[204:207], v[220:223], v[66:69]
	v_mfma_f32_16x16x32_bf16 v[94:97], v[184:187], v[216:219], v[94:97]
	v_mfma_f32_16x16x32_bf16 v[90:93], v[184:187], v[224:227], v[90:93]
	v_mfma_f32_16x16x32_bf16 v[86:89], v[192:195], v[216:219], v[86:89]
	v_mfma_f32_16x16x32_bf16 v[82:85], v[192:195], v[224:227], v[82:85]
	v_mfma_f32_16x16x32_bf16 v[78:81], v[200:203], v[216:219], v[78:81]
	v_mfma_f32_16x16x32_bf16 v[74:77], v[200:203], v[224:227], v[74:77]
	v_mfma_f32_16x16x32_bf16 v[70:73], v[208:211], v[216:219], v[70:73]
	v_mfma_f32_16x16x32_bf16 v[66:69], v[208:211], v[224:227], v[66:69]
	s_barrier
	s_add_u32 s66, s71, 0x180
	s_addc_u32 s67, s72, 0
	s_mov_b32 m0, s37
	ds_read_b128 v[164:167], v133 offset:49152
	ds_read_b128 v[184:187], v133 offset:50176
	ds_read_b128 v[188:191], v134 offset:49152
	ds_read_b128 v[192:195], v134 offset:50176
	ds_read_b128 v[196:199], v137 offset:49152
	ds_read_b128 v[200:203], v137 offset:50176
	ds_read_b128 v[204:207], v139 offset:49152
	ds_read_b128 v[208:211], v139 offset:50176
	s_nop 0
	v_lshl_add_u64 v[228:229], s[66:67], 0, v[0:1]
	global_load_lds_dwordx4 v[228:229], off
	v_lshl_add_u64 v[228:229], s[66:67], 0, v[140:141]
	s_mov_b32 m0, s38
	s_nop 0
	global_load_lds_dwordx4 v[228:229], off
	s_barrier
; #define LDA(dst, b, h) for (int m = 0; m < 4; ++m) for (int k = 0; k < 2; ++k) \
;     dst[m][k] = *reinterpret_cast<const bf16x8*>((char*)SA(b, h) + lds_byte(wr * 64 + m * 16 + fr, k * 32 + fq * 8))
; #define LDB(dst, b, h) for (int n = 0; n < 2; ++n) for (int k = 0; k < 2; ++k) \
;     dst[n][k] = *reinterpret_cast<const bf16x8*>((char*)SB(b, h) + lds_byte(wc * 32 + n * 16 + fr, k * 32 + fq * 8))
; #define MMA(ai, bj, At, Bt_) do { __builtin_amdgcn_s_setprio(1); \
;     for (int m = 0; m < 4; ++m) for (int n = 0; n < 2; ++n) for (int k = 0; k < 2; ++k) \
;       acc[ai][bj][m][n] = __builtin_amdgcn_mfma_f32_16x16x32_bf16(At[m][k], Bt_[n][k], acc[ai][bj][m][n], 0, 0, 0); \
;     __builtin_amdgcn_s_setprio(0); } while (0)
; #define WAIT_V(n) asm volatile("s_waitcnt vmcnt(" #n ")" ::: "memory")
; #define WAIT_L(n) asm volatile("s_waitcnt lgkmcnt(" #n ")" ::: "memory")
; #define BAR __builtin_amdgcn_s_barrier()
; #define SCHED __builtin_amdgcn_sched_barrier(0)
;     ...
;       LDB(B1, 1, 1); STAGE(SB(1, 0), Bt, bcol, t + 3);
;       BAR; WAIT_L(0); MMA(0, 1, At, B1); BAR;
;       LDA(At, 1, 1); STAGE(SA(1, 0), A, brow, t + 3);
;       BAR; WAIT_L(0); MMA(1, 0, At, B0); BAR; SCHED;
;       STAGE(SB(1, 1), Bt, bcol + HALF, t + 3);
;       WAIT_V(6); BAR; MMA(1, 1, At, B1); BAR;
;     }
;     { LDB(B0, 0, 0); LDA(At, 0, 0); STAGE(SA(1, 1), A, brow + HALF, nt - 1);
;       BAR; WAIT_L(0); MMA(0, 0, At, B0); BAR;
;       LDB(B1, 0, 1); BAR; WAIT_L(0); MMA(0, 1, At, B1); BAR;
	s_waitcnt lgkmcnt(0)
	s_waitcnt lgkmcnt(0)
	v_mfma_f32_16x16x32_bf16 v[62:65], v[164:167], v[148:151], v[62:65]
	v_mfma_f32_16x16x32_bf16 v[58:61], v[164:167], v[156:159], v[58:61]
	v_mfma_f32_16x16x32_bf16 v[54:57], v[188:191], v[148:151], v[54:57]
	v_mfma_f32_16x16x32_bf16 v[50:53], v[188:191], v[156:159], v[50:53]
	v_mfma_f32_16x16x32_bf16 v[46:49], v[196:199], v[148:151], v[46:49]
	v_mfma_f32_16x16x32_bf16 v[42:45], v[196:199], v[156:159], v[42:45]
	v_mfma_f32_16x16x32_bf16 v[38:41], v[204:207], v[148:151], v[38:41]
	v_mfma_f32_16x16x32_bf16 v[34:37], v[204:207], v[156:159], v[34:37]
	v_mfma_f32_16x16x32_bf16 v[62:65], v[184:187], v[152:155], v[62:65]
	v_mfma_f32_16x16x32_bf16 v[58:61], v[184:187], v[160:163], v[58:61]
	v_mfma_f32_16x16x32_bf16 v[54:57], v[192:195], v[152:155], v[54:57]
	v_mfma_f32_16x16x32_bf16 v[50:53], v[192:195], v[160:163], v[50:53]
	v_mfma_f32_16x16x32_bf16 v[46:49], v[200:203], v[152:155], v[46:49]
	v_mfma_f32_16x16x32_bf16 v[42:45], v[200:203], v[160:163], v[42:45]
	v_mfma_f32_16x16x32_bf16 v[38:41], v[208:211], v[152:155], v[38:41]
	v_mfma_f32_16x16x32_bf16 v[34:37], v[208:211], v[160:163], v[34:37]
	s_barrier
	s_add_u32 s66, s73, 0x160180
	s_addc_u32 s67, s82, 0
	s_mov_b32 m0, s41
	s_nop 0
	v_lshl_add_u64 v[148:149], s[66:67], 0, v[0:1]
	global_load_lds_dwordx4 v[148:149], off
	v_lshl_add_u64 v[148:149], s[66:67], 0, v[140:141]
	s_mov_b32 m0, s42
	s_nop 0
	global_load_lds_dwordx4 v[148:149], off
	s_add_u32 s6, s6, 0x100
	s_addc_u32 s7, s7, 0
	s_add_u32 s44, s44, 0x100
	s_addc_u32 s45, s45, 0
	s_add_u32 s50, s50, 0x100
	s_addc_u32 s51, s51, 0
	s_add_u32 s55, s55, 0x100
	s_addc_u32 s57, s57, 0
	s_cmp_ge_u32 s58, s43
	s_waitcnt vmcnt(6)
	s_barrier
	v_mfma_f32_16x16x32_bf16 v[30:33], v[164:167], v[212:215], v[30:33]
	v_mfma_f32_16x16x32_bf16 v[26:29], v[164:167], v[220:223], v[26:29]
	v_mfma_f32_16x16x32_bf16 v[22:25], v[188:191], v[212:215], v[22:25]
	v_mfma_f32_16x16x32_bf16 v[18:21], v[188:191], v[220:223], v[18:21]
	v_mfma_f32_16x16x32_bf16 v[14:17], v[196:199], v[212:215], v[14:17]
	v_mfma_f32_16x16x32_bf16 v[10:13], v[196:199], v[220:223], v[10:13]
	v_mfma_f32_16x16x32_bf16 v[6:9], v[204:207], v[212:215], v[6:9]
	v_mfma_f32_16x16x32_bf16 v[2:5], v[204:207], v[220:223], v[2:5]
	v_mfma_f32_16x16x32_bf16 v[30:33], v[184:187], v[216:219], v[30:33]
	v_mfma_f32_16x16x32_bf16 v[26:29], v[184:187], v[224:227], v[26:29]
	v_mfma_f32_16x16x32_bf16 v[22:25], v[192:195], v[216:219], v[22:25]
	v_mfma_f32_16x16x32_bf16 v[18:21], v[192:195], v[224:227], v[18:21]
	v_mfma_f32_16x16x32_bf16 v[14:17], v[200:203], v[216:219], v[14:17]
	v_mfma_f32_16x16x32_bf16 v[10:13], v[200:203], v[224:227], v[10:13]
	v_mfma_f32_16x16x32_bf16 v[6:9], v[208:211], v[216:219], v[6:9]
	v_mfma_f32_16x16x32_bf16 v[2:5], v[208:211], v[224:227], v[2:5]
	s_barrier
	s_cbranch_scc0 .LBB0_98
	s_add_i32 s4, s48, s14
	s_add_i32 s48, s4, -1
	s_lshl_b64 s[4:5], s[48:49], 7
	s_add_u32 s4, s22, s4
	s_addc_u32 s5, s23, s5
	s_add_u32 s4, s4, s40
	s_addc_u32 s5, s5, s39
	s_mov_b32 m0, s63
	ds_read_b128 v[148:151], v143
	ds_read_b128 v[152:155], v143 offset:1024
	ds_read_b128 v[156:159], v143 offset:2048
	ds_read_b128 v[160:163], v143 offset:3072
	ds_read_b128 v[164:167], v133
	ds_read_b128 v[184:187], v133 offset:1024
	ds_read_b128 v[188:191], v134
	ds_read_b128 v[192:195], v134 offset:1024
	ds_read_b128 v[196:199], v137
	ds_read_b128 v[200:203], v137 offset:1024
	ds_read_b128 v[204:207], v139
	ds_read_b128 v[208:211], v139 offset:1024
	s_nop 0
	v_lshl_add_u64 v[142:143], s[4:5], 0, v[0:1]
	global_load_lds_dwordx4 v[142:143], off
	v_lshl_add_u64 v[140:141], s[4:5], 0, v[140:141]
	s_mov_b32 m0, s59
	s_nop 0
	global_load_lds_dwordx4 v[140:141], off
	s_barrier
	s_waitcnt lgkmcnt(0)
	s_setprio 1
	s_waitcnt lgkmcnt(0)
	v_mfma_f32_16x16x32_bf16 v[126:129], v[164:167], v[148:151], v[126:129]
	v_mfma_f32_16x16x32_bf16 v[122:125], v[164:167], v[156:159], v[122:125]
	v_mfma_f32_16x16x32_bf16 v[118:121], v[188:191], v[148:151], v[118:121]
	v_mfma_f32_16x16x32_bf16 v[110:113], v[196:199], v[148:151], v[110:113]
	v_mfma_f32_16x16x32_bf16 v[106:109], v[196:199], v[156:159], v[106:109]
	v_mfma_f32_16x16x32_bf16 v[102:105], v[204:207], v[148:151], v[102:105]
	v_mfma_f32_16x16x32_bf16 v[98:101], v[204:207], v[156:159], v[98:101]
	v_mfma_f32_16x16x32_bf16 v[126:129], v[184:187], v[152:155], v[126:129]
	v_mfma_f32_16x16x32_bf16 v[122:125], v[184:187], v[160:163], v[122:125]
	v_mfma_f32_16x16x32_bf16 v[118:121], v[192:195], v[152:155], v[118:121]
	v_mfma_f32_16x16x32_bf16 v[114:117], v[188:191], v[156:159], v[114:117]
	v_mfma_f32_16x16x32_bf16 v[110:113], v[200:203], v[152:155], v[110:113]
	v_mfma_f32_16x16x32_bf16 v[106:109], v[200:203], v[160:163], v[106:109]
	v_mfma_f32_16x16x32_bf16 v[102:105], v[208:211], v[152:155], v[102:105]
	v_mfma_f32_16x16x32_bf16 v[98:101], v[208:211], v[160:163], v[98:101]
	v_mfma_f32_16x16x32_bf16 v[140:143], v[192:195], v[160:163], v[114:117]
	s_setprio 0
	s_barrier
	s_nop 0
	ds_read_b128 v[114:117], v144
	ds_read_b128 v[212:215], v144 offset:1024
	ds_read_b128 v[216:219], v144 offset:2048
	ds_read_b128 v[220:223], v144 offset:3072
	s_barrier
; #define LDA(dst, b, h) for (int m = 0; m < 4; ++m) for (int k = 0; k < 2; ++k) \
;     dst[m][k] = *reinterpret_cast<const bf16x8*>((char*)SA(b, h) + lds_byte(wr * 64 + m * 16 + fr, k * 32 + fq * 8))
; #define LDB(dst, b, h) for (int n = 0; n < 2; ++n) for (int k = 0; k < 2; ++k) \
;     dst[n][k] = *reinterpret_cast<const bf16x8*>((char*)SB(b, h) + lds_byte(wc * 32 + n * 16 + fr, k * 32 + fq * 8))
; #define MMA(ai, bj, At, Bt_) do { __builtin_amdgcn_s_setprio(1); \
;     for (int m = 0; m < 4; ++m) for (int n = 0; n < 2; ++n) for (int k = 0; k < 2; ++k) \
;       acc[ai][bj][m][n] = __builtin_amdgcn_mfma_f32_16x16x32_bf16(At[m][k], Bt_[n][k], acc[ai][bj][m][n], 0, 0, 0); \
;     __builtin_amdgcn_s_setprio(0); } while (0)
; #define WAIT_V(n) asm volatile("s_waitcnt vmcnt(" #n ")" ::: "memory")
; #define WAIT_L(n) asm volatile("s_waitcnt lgkmcnt(" #n ")" ::: "memory")
; #define BAR __builtin_amdgcn_s_barrier()
;     ...
;       LDB(B1, 0, 1); BAR; WAIT_L(0); MMA(0, 1, At, B1); BAR;
;       LDA(At, 0, 1); WAIT_V(4); BAR; WAIT_L(0); MMA(1, 0, At, B0); MMA(1, 1, At, B1); BAR; }
;     { LDB(B0, 1, 0); LDA(At, 1, 0); WAIT_V(2); BAR; WAIT_L(0); MMA(0, 0, At, B0); BAR;
	s_waitcnt lgkmcnt(0)
	s_setprio 1
	s_waitcnt lgkmcnt(0)
	v_mfma_f32_16x16x32_bf16 v[90:93], v[164:167], v[216:219], v[90:93]
	v_mfma_f32_16x16x32_bf16 v[86:89], v[188:191], v[114:117], v[86:89]
	v_mfma_f32_16x16x32_bf16 v[94:97], v[164:167], v[114:117], v[94:97]
	v_mfma_f32_16x16x32_bf16 v[90:93], v[184:187], v[220:223], v[90:93]
	v_mfma_f32_16x16x32_bf16 v[86:89], v[192:195], v[212:215], v[86:89]
	v_mfma_f32_16x16x32_bf16 v[82:85], v[188:191], v[216:219], v[82:85]
	v_mfma_f32_16x16x32_bf16 v[78:81], v[196:199], v[114:117], v[78:81]
	v_mfma_f32_16x16x32_bf16 v[74:77], v[196:199], v[216:219], v[74:77]
	v_mfma_f32_16x16x32_bf16 v[70:73], v[204:207], v[114:117], v[70:73]
	v_mfma_f32_16x16x32_bf16 v[66:69], v[204:207], v[216:219], v[66:69]
	v_mfma_f32_16x16x32_bf16 v[224:227], v[184:187], v[212:215], v[94:97]
	v_mfma_f32_16x16x32_bf16 v[164:167], v[192:195], v[220:223], v[82:85]
	v_mfma_f32_16x16x32_bf16 v[184:187], v[200:203], v[212:215], v[78:81]
	v_mfma_f32_16x16x32_bf16 v[188:191], v[200:203], v[220:223], v[74:77]
	v_mfma_f32_16x16x32_bf16 v[192:195], v[208:211], v[212:215], v[70:73]
	v_mfma_f32_16x16x32_bf16 v[196:199], v[208:211], v[220:223], v[66:69]
	s_setprio 0
	s_barrier
	s_nop 0
	ds_read_b128 v[66:69], v133 offset:16384
	ds_read_b128 v[70:73], v133 offset:17408
	ds_read_b128 v[74:77], v134 offset:16384
	ds_read_b128 v[78:81], v134 offset:17408
	ds_read_b128 v[82:85], v137 offset:16384
	ds_read_b128 v[94:97], v137 offset:17408
	ds_read_b128 v[200:203], v139 offset:16384
	ds_read_b128 v[204:207], v139 offset:17408
	s_waitcnt vmcnt(4)
	s_barrier
	s_waitcnt lgkmcnt(0)
	s_setprio 1
	s_waitcnt lgkmcnt(0)
	v_mfma_f32_16x16x32_bf16 v[62:65], v[66:69], v[148:151], v[62:65]
	v_mfma_f32_16x16x32_bf16 v[58:61], v[66:69], v[156:159], v[58:61]
	v_mfma_f32_16x16x32_bf16 v[54:57], v[74:77], v[148:151], v[54:57]
	v_mfma_f32_16x16x32_bf16 v[50:53], v[74:77], v[156:159], v[50:53]
	v_mfma_f32_16x16x32_bf16 v[46:49], v[82:85], v[148:151], v[46:49]
	v_mfma_f32_16x16x32_bf16 v[42:45], v[82:85], v[156:159], v[42:45]
	v_mfma_f32_16x16x32_bf16 v[38:41], v[200:203], v[148:151], v[38:41]
	v_mfma_f32_16x16x32_bf16 v[34:37], v[200:203], v[156:159], v[34:37]
	v_mfma_f32_16x16x32_bf16 v[62:65], v[70:73], v[152:155], v[62:65]
	v_mfma_f32_16x16x32_bf16 v[58:61], v[70:73], v[160:163], v[58:61]
	v_mfma_f32_16x16x32_bf16 v[54:57], v[78:81], v[152:155], v[54:57]
	v_mfma_f32_16x16x32_bf16 v[50:53], v[78:81], v[160:163], v[50:53]
	v_mfma_f32_16x16x32_bf16 v[46:49], v[94:97], v[152:155], v[46:49]
	v_mfma_f32_16x16x32_bf16 v[42:45], v[94:97], v[160:163], v[42:45]
	v_mfma_f32_16x16x32_bf16 v[38:41], v[204:207], v[152:155], v[38:41]
	v_mfma_f32_16x16x32_bf16 v[34:37], v[204:207], v[160:163], v[34:37]
	s_setprio 0
	s_setprio 1
	v_mfma_f32_16x16x32_bf16 v[30:33], v[66:69], v[114:117], v[30:33]
	v_mfma_f32_16x16x32_bf16 v[26:29], v[66:69], v[216:219], v[26:29]
	v_mfma_f32_16x16x32_bf16 v[22:25], v[74:77], v[114:117], v[22:25]
	v_mfma_f32_16x16x32_bf16 v[18:21], v[74:77], v[216:219], v[18:21]
	v_mfma_f32_16x16x32_bf16 v[14:17], v[82:85], v[114:117], v[14:17]
	v_mfma_f32_16x16x32_bf16 v[10:13], v[82:85], v[216:219], v[10:13]
	v_mfma_f32_16x16x32_bf16 v[6:9], v[200:203], v[114:117], v[6:9]
	v_mfma_f32_16x16x32_bf16 v[2:5], v[200:203], v[216:219], v[2:5]
	v_mfma_f32_16x16x32_bf16 v[148:151], v[70:73], v[212:215], v[30:33]
	v_mfma_f32_16x16x32_bf16 v[152:155], v[70:73], v[220:223], v[26:29]
	v_mfma_f32_16x16x32_bf16 v[156:159], v[78:81], v[212:215], v[22:25]
	v_mfma_f32_16x16x32_bf16 v[160:163], v[78:81], v[220:223], v[18:21]
	v_mfma_f32_16x16x32_bf16 v[208:211], v[94:97], v[212:215], v[14:17]
	v_mfma_f32_16x16x32_bf16 v[228:231], v[94:97], v[220:223], v[10:13]
	v_mfma_f32_16x16x32_bf16 v[212:215], v[204:207], v[212:215], v[6:9]
	v_mfma_f32_16x16x32_bf16 v[200:203], v[204:207], v[220:223], v[2:5]
	s_setprio 0
	s_barrier
	ds_read_b128 v[14:17], v145
	ds_read_b128 v[30:33], v145 offset:1024
	ds_read_b128 v[204:207], v145 offset:2048
	ds_read_b128 v[216:219], v145 offset:3072
	ds_read_b128 v[2:5], v133 offset:32768
	ds_read_b128 v[6:9], v133 offset:33792
	ds_read_b128 v[10:13], v134 offset:32768
	ds_read_b128 v[18:21], v134 offset:33792
	ds_read_b128 v[22:25], v137 offset:32768
	ds_read_b128 v[26:29], v137 offset:33792
	ds_read_b128 v[220:223], v139 offset:32768
	ds_read_b128 v[232:235], v139 offset:33792
	s_waitcnt vmcnt(2)
	s_barrier
; #define LDA(dst, b, h) for (int m = 0; m < 4; ++m) for (int k = 0; k < 2; ++k) \
;     dst[m][k] = *reinterpret_cast<const bf16x8*>((char*)SA(b, h) + lds_byte(wr * 64 + m * 16 + fr, k * 32 + fq * 8))
; #define LDB(dst, b, h) for (int n = 0; n < 2; ++n) for (int k = 0; k < 2; ++k) \
;     dst[n][k] = *reinterpret_cast<const bf16x8*>((char*)SB(b, h) + lds_byte(wc * 32 + n * 16 + fr, k * 32 + fq * 8))
; #define MMA(ai, bj, At, Bt_) do { __builtin_amdgcn_s_setprio(1); \
;     for (int m = 0; m < 4; ++m) for (int n = 0; n < 2; ++n) for (int k = 0; k < 2; ++k) \
;       acc[ai][bj][m][n] = __builtin_amdgcn_mfma_f32_16x16x32_bf16(At[m][k], Bt_[n][k], acc[ai][bj][m][n], 0, 0, 0); \
;     __builtin_amdgcn_s_setprio(0); } while (0)
; #define WAIT_V(n) asm volatile("s_waitcnt vmcnt(" #n ")" ::: "memory")
; #define WAIT_L(n) asm volatile("s_waitcnt lgkmcnt(" #n ")" ::: "memory")
; #define BAR __builtin_amdgcn_s_barrier()
;     ...
;     { LDB(B0, 1, 0); LDA(At, 1, 0); WAIT_V(2); BAR; WAIT_L(0); MMA(0, 0, At, B0); BAR;
;       LDB(B1, 1, 1); WAIT_V(0); BAR; WAIT_L(0); MMA(0, 1, At, B1); BAR;
;       LDA(At, 1, 1); BAR; WAIT_L(0); MMA(1, 0, At, B0); MMA(1, 1, At, B1); BAR; }
;     if (wr == 0) BAR;
	s_waitcnt lgkmcnt(0)
	s_setprio 1
	s_waitcnt lgkmcnt(0)
	v_mfma_f32_16x16x32_bf16 v[66:69], v[2:5], v[14:17], v[126:129]
	v_mfma_f32_16x16x32_bf16 v[114:117], v[6:9], v[30:33], v[66:69]
	v_mfma_f32_16x16x32_bf16 v[66:69], v[2:5], v[204:207], v[122:125]
	v_mfma_f32_16x16x32_bf16 v[126:129], v[6:9], v[216:219], v[66:69]
	v_mfma_f32_16x16x32_bf16 v[66:69], v[10:13], v[14:17], v[118:121]
	v_mfma_f32_16x16x32_bf16 v[82:85], v[18:21], v[30:33], v[66:69]
	v_mfma_f32_16x16x32_bf16 v[66:69], v[10:13], v[204:207], v[140:143]
	v_mfma_f32_16x16x32_bf16 v[94:97], v[18:21], v[216:219], v[66:69]
	v_mfma_f32_16x16x32_bf16 v[66:69], v[22:25], v[14:17], v[110:113]
	v_mfma_f32_16x16x32_bf16 v[74:77], v[26:29], v[30:33], v[66:69]
	v_mfma_f32_16x16x32_bf16 v[66:69], v[22:25], v[204:207], v[106:109]
	v_mfma_f32_16x16x32_bf16 v[78:81], v[26:29], v[216:219], v[66:69]
	v_mfma_f32_16x16x32_bf16 v[66:69], v[220:223], v[14:17], v[102:105]
	v_mfma_f32_16x16x32_bf16 v[70:73], v[220:223], v[204:207], v[98:101]
	v_mfma_f32_16x16x32_bf16 v[66:69], v[232:235], v[30:33], v[66:69]
	v_mfma_f32_16x16x32_bf16 v[70:73], v[232:235], v[216:219], v[70:73]
	s_setprio 0
	s_barrier
	ds_read_b128 v[140:143], v146
	ds_read_b128 v[236:239], v146 offset:1024
	ds_read_b128 v[240:243], v146 offset:2048
	ds_read_b128 v[144:147], v146 offset:3072
	s_waitcnt vmcnt(0)
	s_barrier
	s_waitcnt lgkmcnt(0)
	s_setprio 1
	s_waitcnt lgkmcnt(0)
	v_mfma_f32_16x16x32_bf16 v[98:101], v[2:5], v[140:143], v[224:227]
	v_mfma_f32_16x16x32_bf16 v[2:5], v[2:5], v[240:243], v[90:93]
	v_mfma_f32_16x16x32_bf16 v[118:121], v[6:9], v[144:147], v[2:5]
	v_mfma_f32_16x16x32_bf16 v[2:5], v[10:13], v[140:143], v[86:89]
	v_mfma_f32_16x16x32_bf16 v[102:105], v[18:21], v[236:239], v[2:5]
	v_mfma_f32_16x16x32_bf16 v[2:5], v[10:13], v[240:243], v[164:167]
	v_mfma_f32_16x16x32_bf16 v[122:125], v[18:21], v[144:147], v[2:5]
	v_mfma_f32_16x16x32_bf16 v[2:5], v[22:25], v[140:143], v[184:187]
	v_mfma_f32_16x16x32_bf16 v[90:93], v[26:29], v[236:239], v[2:5]
	v_mfma_f32_16x16x32_bf16 v[2:5], v[22:25], v[240:243], v[188:191]
	v_mfma_f32_16x16x32_bf16 v[110:113], v[26:29], v[144:147], v[2:5]
	v_mfma_f32_16x16x32_bf16 v[2:5], v[220:223], v[140:143], v[192:195]
	v_mfma_f32_16x16x32_bf16 v[86:89], v[232:235], v[236:239], v[2:5]
	v_mfma_f32_16x16x32_bf16 v[2:5], v[220:223], v[240:243], v[196:199]
	v_mfma_f32_16x16x32_bf16 v[98:101], v[6:9], v[236:239], v[98:101]
	v_mfma_f32_16x16x32_bf16 v[106:109], v[232:235], v[144:147], v[2:5]
	s_setprio 0
	s_barrier
	ds_read_b128 v[164:167], v133 offset:49152
	ds_read_b128 v[184:187], v133 offset:50176
	ds_read_b128 v[188:191], v134 offset:49152
	ds_read_b128 v[192:195], v134 offset:50176
	ds_read_b128 v[196:199], v137 offset:49152
	ds_read_b128 v[220:223], v137 offset:50176
	ds_read_b128 v[224:227], v139 offset:49152
	ds_read_b128 v[232:235], v139 offset:50176
	s_barrier
	s_waitcnt lgkmcnt(0)
	s_setprio 1
	s_waitcnt lgkmcnt(0)
	v_mfma_f32_16x16x32_bf16 v[6:9], v[164:167], v[204:207], v[58:61]
	v_mfma_f32_16x16x32_bf16 v[10:13], v[188:191], v[204:207], v[50:53]
	v_mfma_f32_16x16x32_bf16 v[2:5], v[164:167], v[14:17], v[62:65]
	v_mfma_f32_16x16x32_bf16 v[18:21], v[184:187], v[216:219], v[6:9]
	v_mfma_f32_16x16x32_bf16 v[6:9], v[188:191], v[14:17], v[54:57]
	v_mfma_f32_16x16x32_bf16 v[22:25], v[192:195], v[216:219], v[10:13]
	v_mfma_f32_16x16x32_bf16 v[10:13], v[196:199], v[14:17], v[46:49]
	v_mfma_f32_16x16x32_bf16 v[14:17], v[224:227], v[14:17], v[38:41]
	v_mfma_f32_16x16x32_bf16 v[2:5], v[184:187], v[30:33], v[2:5]
	v_mfma_f32_16x16x32_bf16 v[6:9], v[192:195], v[30:33], v[6:9]
	v_mfma_f32_16x16x32_bf16 v[10:13], v[220:223], v[30:33], v[10:13]
	v_mfma_f32_16x16x32_bf16 v[26:29], v[196:199], v[204:207], v[42:45]
	v_mfma_f32_16x16x32_bf16 v[14:17], v[232:235], v[30:33], v[14:17]
	v_mfma_f32_16x16x32_bf16 v[30:33], v[224:227], v[204:207], v[34:37]
	v_mfma_f32_16x16x32_bf16 v[26:29], v[220:223], v[216:219], v[26:29]
	v_mfma_f32_16x16x32_bf16 v[30:33], v[232:235], v[216:219], v[30:33]
	s_setprio 0
	s_setprio 1
	v_mfma_f32_16x16x32_bf16 v[38:41], v[164:167], v[240:243], v[152:155]
	v_mfma_f32_16x16x32_bf16 v[42:45], v[188:191], v[240:243], v[160:163]
	v_mfma_f32_16x16x32_bf16 v[46:49], v[196:199], v[240:243], v[228:231]
	v_mfma_f32_16x16x32_bf16 v[34:37], v[164:167], v[140:143], v[148:151]
	v_mfma_f32_16x16x32_bf16 v[50:53], v[184:187], v[144:147], v[38:41]
	v_mfma_f32_16x16x32_bf16 v[38:41], v[188:191], v[140:143], v[156:159]
	v_mfma_f32_16x16x32_bf16 v[54:57], v[192:195], v[144:147], v[42:45]
	v_mfma_f32_16x16x32_bf16 v[42:45], v[196:199], v[140:143], v[208:211]
	v_mfma_f32_16x16x32_bf16 v[58:61], v[220:223], v[144:147], v[46:49]
	v_mfma_f32_16x16x32_bf16 v[46:49], v[224:227], v[140:143], v[212:215]
	v_mfma_f32_16x16x32_bf16 v[62:65], v[224:227], v[240:243], v[200:203]
	v_mfma_f32_16x16x32_bf16 v[34:37], v[184:187], v[236:239], v[34:37]
	v_mfma_f32_16x16x32_bf16 v[38:41], v[192:195], v[236:239], v[38:41]
	v_mfma_f32_16x16x32_bf16 v[42:45], v[220:223], v[236:239], v[42:45]
	v_mfma_f32_16x16x32_bf16 v[46:49], v[232:235], v[236:239], v[46:49]
	v_mfma_f32_16x16x32_bf16 v[62:65], v[232:235], v[144:147], v[62:65]
	s_setprio 0
	v_readlane_b32 s4, v245, 33
	v_readlane_b32 s5, v245, 34
	s_and_b64 vcc, exec, s[4:5]
	s_barrier
	s_cbranch_vccz .LBB0_101
	s_barrier

; #define LDA(dst, b, h) for (int m = 0; m < 4; ++m) for (int k = 0; k < 2; ++k) \
;     dst[m][k] = *reinterpret_cast<const bf16x8*>((char*)SA(b, h) + lds_byte(wr * 64 + m * 16 + fr, k * 32 + fq * 8))
; #define LDB(dst, b, h) for (int n = 0; n < 2; ++n) for (int k = 0; k < 2; ++k) \
;     dst[n][k] = *reinterpret_cast<const bf16x8*>((char*)SB(b, h) + lds_byte(wc * 32 + n * 16 + fr, k * 32 + fq * 8))
; #define MMA(ai, bj, At, Bt_) do { __builtin_amdgcn_s_setprio(1); \
;     for (int m = 0; m < 4; ++m) for (int n = 0; n < 2; ++n) for (int k = 0; k < 2; ++k) \
;       acc[ai][bj][m][n] = __builtin_amdgcn_mfma_f32_16x16x32_bf16(At[m][k], Bt_[n][k], acc[ai][bj][m][n], 0, 0, 0); \
;     __builtin_amdgcn_s_setprio(0); } while (0)
; #define WAIT_V(n) asm volatile("s_waitcnt vmcnt(" #n ")" ::: "memory")
; #define WAIT_L(n) asm volatile("s_waitcnt lgkmcnt(" #n ")" ::: "memory")
; #define BAR __builtin_amdgcn_s_barrier()
; #define SCHED __builtin_amdgcn_sched_barrier(0)
;     ...
;     for (int t = 0; t < nt - 2; t += 2) {
;       LDB(B0, 0, 0); SCHED; LDA(At, 0, 0); STAGE(SA(1, 1), A, brow + HALF, t + 1);
;       WAIT_L(8); BAR; WAIT_L(0); MMA(0, 0, At, B0); BAR; SCHED;
;       LDB(B1, 0, 1); STAGE(SB(0, 0), Bt, bcol, t + 2);
;       BAR; WAIT_L(0); MMA(0, 1, At, B1); BAR;
;       LDA(At, 0, 1); STAGE(SA(0, 0), A, brow, t + 2);
;       BAR; WAIT_L(0); MMA(1, 0, At, B0); BAR; SCHED;
;       STAGE(SB(0, 1), Bt, bcol + HALF, t + 2);
;       WAIT_V(6); BAR; MMA(1, 1, At, B1); BAR;
.LBB0_155:
	v_add_u32_e32 v143, s2, v142
	ds_read_b128 v[146:149], v143
	ds_read_b128 v[150:153], v143 offset:1024
	ds_read_b128 v[154:157], v143 offset:2048
	ds_read_b128 v[158:161], v143 offset:3072
	s_add_u32 s40, s30, s10
	s_addc_u32 s41, s31, s11
	s_add_u32 s42, s40, 0x80080
	s_addc_u32 s43, s41, 0
	s_add_i32 s39, s24, 0xc000
	ds_read_b128 v[162:165], v133
	ds_read_b128 v[184:187], v133 offset:1024
	ds_read_b128 v[188:191], v134
	ds_read_b128 v[192:195], v134 offset:1024
	ds_read_b128 v[196:199], v137
	ds_read_b128 v[200:203], v137 offset:1024
	ds_read_b128 v[204:207], v139
	ds_read_b128 v[208:211], v139 offset:1024
	s_mov_b32 m0, s39
	v_lshl_add_u64 v[144:145], s[42:43], 0, v[0:1]
	s_add_i32 s38, s24, 0xe000
	global_load_lds_dwordx4 v[144:145], off
	v_lshl_add_u64 v[144:145], s[42:43], 0, v[140:141]
	s_mov_b32 m0, s38
	s_nop 0
	global_load_lds_dwordx4 v[144:145], off
	s_waitcnt lgkmcnt(8)
	s_barrier
	s_waitcnt lgkmcnt(0)
	s_waitcnt lgkmcnt(0)
	v_mfma_f32_16x16x32_bf16 v[126:129], v[162:165], v[146:149], v[126:129]
	v_mfma_f32_16x16x32_bf16 v[122:125], v[162:165], v[154:157], v[122:125]
	v_mfma_f32_16x16x32_bf16 v[118:121], v[188:191], v[146:149], v[118:121]
	v_mfma_f32_16x16x32_bf16 v[114:117], v[188:191], v[154:157], v[114:117]
	v_mfma_f32_16x16x32_bf16 v[110:113], v[196:199], v[146:149], v[110:113]
	v_mfma_f32_16x16x32_bf16 v[106:109], v[196:199], v[154:157], v[106:109]
	v_mfma_f32_16x16x32_bf16 v[102:105], v[204:207], v[146:149], v[102:105]
	v_mfma_f32_16x16x32_bf16 v[98:101], v[204:207], v[154:157], v[98:101]
	v_mfma_f32_16x16x32_bf16 v[126:129], v[184:187], v[150:153], v[126:129]
	v_mfma_f32_16x16x32_bf16 v[122:125], v[184:187], v[158:161], v[122:125]
	v_mfma_f32_16x16x32_bf16 v[118:121], v[192:195], v[150:153], v[118:121]
	v_mfma_f32_16x16x32_bf16 v[114:117], v[192:195], v[158:161], v[114:117]
	v_mfma_f32_16x16x32_bf16 v[110:113], v[200:203], v[150:153], v[110:113]
	v_mfma_f32_16x16x32_bf16 v[106:109], v[200:203], v[158:161], v[106:109]
	v_mfma_f32_16x16x32_bf16 v[102:105], v[208:211], v[150:153], v[102:105]
	v_mfma_f32_16x16x32_bf16 v[98:101], v[208:211], v[158:161], v[98:101]
	s_barrier
	s_add_u32 s42, s34, s10
	s_addc_u32 s43, s35, s11
	s_add_u32 s44, s42, 0x100
	v_add_u32_e32 v144, s76, v142
	s_addc_u32 s45, s43, 0
	s_mov_b32 m0, s25
	ds_read_b128 v[212:215], v144
	ds_read_b128 v[216:219], v144 offset:1024
	ds_read_b128 v[220:223], v144 offset:2048
	ds_read_b128 v[224:227], v144 offset:3072
	s_nop 0
	v_lshl_add_u64 v[166:167], s[44:45], 0, v[0:1]
	global_load_lds_dwordx4 v[166:167], off
	v_lshl_add_u64 v[166:167], s[44:45], 0, v[140:141]
	s_mov_b32 m0, s26
	s_nop 0
	global_load_lds_dwordx4 v[166:167], off
	s_barrier
	s_waitcnt lgkmcnt(0)
	s_waitcnt lgkmcnt(0)
	v_mfma_f32_16x16x32_bf16 v[94:97], v[162:165], v[212:215], v[94:97]
	v_mfma_f32_16x16x32_bf16 v[90:93], v[162:165], v[220:223], v[90:93]
	v_mfma_f32_16x16x32_bf16 v[86:89], v[188:191], v[212:215], v[86:89]
	v_mfma_f32_16x16x32_bf16 v[82:85], v[188:191], v[220:223], v[82:85]
	v_mfma_f32_16x16x32_bf16 v[78:81], v[196:199], v[212:215], v[78:81]
	v_mfma_f32_16x16x32_bf16 v[74:77], v[196:199], v[220:223], v[74:77]
	v_mfma_f32_16x16x32_bf16 v[70:73], v[204:207], v[212:215], v[70:73]
	v_mfma_f32_16x16x32_bf16 v[66:69], v[204:207], v[220:223], v[66:69]
	v_mfma_f32_16x16x32_bf16 v[94:97], v[184:187], v[216:219], v[94:97]
	v_mfma_f32_16x16x32_bf16 v[90:93], v[184:187], v[224:227], v[90:93]
	v_mfma_f32_16x16x32_bf16 v[86:89], v[192:195], v[216:219], v[86:89]
	v_mfma_f32_16x16x32_bf16 v[82:85], v[192:195], v[224:227], v[82:85]
	v_mfma_f32_16x16x32_bf16 v[78:81], v[200:203], v[216:219], v[78:81]
	v_mfma_f32_16x16x32_bf16 v[74:77], v[200:203], v[224:227], v[74:77]
	v_mfma_f32_16x16x32_bf16 v[70:73], v[208:211], v[216:219], v[70:73]
	v_mfma_f32_16x16x32_bf16 v[66:69], v[208:211], v[224:227], v[66:69]
	s_barrier
	s_add_u32 s44, s40, 0x100
	s_addc_u32 s45, s41, 0
	s_mov_b32 m0, s24
	ds_read_b128 v[162:165], v133 offset:16384
	ds_read_b128 v[184:187], v133 offset:17408
	ds_read_b128 v[188:191], v134 offset:16384
	ds_read_b128 v[192:195], v134 offset:17408
	ds_read_b128 v[196:199], v137 offset:16384
	ds_read_b128 v[200:203], v137 offset:17408
	ds_read_b128 v[204:207], v139 offset:16384
	ds_read_b128 v[208:211], v139 offset:17408
	s_nop 0
	v_lshl_add_u64 v[166:167], s[44:45], 0, v[0:1]
	global_load_lds_dwordx4 v[166:167], off
	v_lshl_add_u64 v[166:167], s[44:45], 0, v[140:141]
	s_mov_b32 m0, s9
	s_nop 0
	global_load_lds_dwordx4 v[166:167], off
	s_barrier
	s_waitcnt lgkmcnt(0)
	s_waitcnt lgkmcnt(0)
	v_mfma_f32_16x16x32_bf16 v[62:65], v[162:165], v[146:149], v[62:65]
	v_mfma_f32_16x16x32_bf16 v[58:61], v[162:165], v[154:157], v[58:61]
	v_mfma_f32_16x16x32_bf16 v[54:57], v[188:191], v[146:149], v[54:57]
	v_mfma_f32_16x16x32_bf16 v[50:53], v[188:191], v[154:157], v[50:53]
	v_mfma_f32_16x16x32_bf16 v[46:49], v[196:199], v[146:149], v[46:49]
	v_mfma_f32_16x16x32_bf16 v[42:45], v[196:199], v[154:157], v[42:45]
	v_mfma_f32_16x16x32_bf16 v[38:41], v[204:207], v[146:149], v[38:41]
	v_mfma_f32_16x16x32_bf16 v[34:37], v[204:207], v[154:157], v[34:37]
	v_mfma_f32_16x16x32_bf16 v[62:65], v[184:187], v[150:153], v[62:65]
	v_mfma_f32_16x16x32_bf16 v[58:61], v[184:187], v[158:161], v[58:61]
	v_mfma_f32_16x16x32_bf16 v[54:57], v[192:195], v[150:153], v[54:57]
	v_mfma_f32_16x16x32_bf16 v[50:53], v[192:195], v[158:161], v[50:53]
	v_mfma_f32_16x16x32_bf16 v[46:49], v[200:203], v[150:153], v[46:49]
	v_mfma_f32_16x16x32_bf16 v[42:45], v[200:203], v[158:161], v[42:45]
	v_mfma_f32_16x16x32_bf16 v[38:41], v[208:211], v[150:153], v[38:41]
	v_mfma_f32_16x16x32_bf16 v[34:37], v[208:211], v[158:161], v[34:37]
	s_barrier
; #define LDA(dst, b, h) for (int m = 0; m < 4; ++m) for (int k = 0; k < 2; ++k) \
;     dst[m][k] = *reinterpret_cast<const bf16x8*>((char*)SA(b, h) + lds_byte(wr * 64 + m * 16 + fr, k * 32 + fq * 8))
; #define LDB(dst, b, h) for (int n = 0; n < 2; ++n) for (int k = 0; k < 2; ++k) \
;     dst[n][k] = *reinterpret_cast<const bf16x8*>((char*)SB(b, h) + lds_byte(wc * 32 + n * 16 + fr, k * 32 + fq * 8))
; #define MMA(ai, bj, At, Bt_) do { __builtin_amdgcn_s_setprio(1); \
;     for (int m = 0; m < 4; ++m) for (int n = 0; n < 2; ++n) for (int k = 0; k < 2; ++k) \
;       acc[ai][bj][m][n] = __builtin_amdgcn_mfma_f32_16x16x32_bf16(At[m][k], Bt_[n][k], acc[ai][bj][m][n], 0, 0, 0); \
;     __builtin_amdgcn_s_setprio(0); } while (0)
; #define WAIT_V(n) asm volatile("s_waitcnt vmcnt(" #n ")" ::: "memory")
; #define WAIT_L(n) asm volatile("s_waitcnt lgkmcnt(" #n ")" ::: "memory")
; #define BAR __builtin_amdgcn_s_barrier()
; #define SCHED __builtin_amdgcn_sched_barrier(0)
;     ...
;       WAIT_V(6); BAR; MMA(1, 1, At, B1); BAR;
;       LDB(B0, 1, 0); SCHED; LDA(At, 1, 0); STAGE(SA(0, 1), A, brow + HALF, t + 2);
;       WAIT_L(8); BAR; WAIT_L(0); MMA(0, 0, At, B0); BAR; SCHED;
;       LDB(B1, 1, 1); STAGE(SB(1, 0), Bt, bcol, t + 3);
;       BAR; WAIT_L(0); MMA(0, 1, At, B1); BAR;
;       LDA(At, 1, 1); STAGE(SA(1, 0), A, brow, t + 3);
;       BAR; WAIT_L(0); MMA(1, 0, At, B0); BAR; SCHED;
	s_add_u32 s44, s42, 0x80100
	s_addc_u32 s45, s43, 0
	s_mov_b32 m0, s27
	s_nop 0
	v_lshl_add_u64 v[146:147], s[44:45], 0, v[0:1]
	global_load_lds_dwordx4 v[146:147], off
	v_lshl_add_u64 v[146:147], s[44:45], 0, v[140:141]
	s_mov_b32 m0, s28
	s_nop 0
	global_load_lds_dwordx4 v[146:147], off
	s_waitcnt vmcnt(6)
	s_barrier
	v_mfma_f32_16x16x32_bf16 v[30:33], v[162:165], v[212:215], v[30:33]
	v_mfma_f32_16x16x32_bf16 v[26:29], v[162:165], v[220:223], v[26:29]
	v_mfma_f32_16x16x32_bf16 v[22:25], v[188:191], v[212:215], v[22:25]
	v_mfma_f32_16x16x32_bf16 v[18:21], v[188:191], v[220:223], v[18:21]
	v_mfma_f32_16x16x32_bf16 v[14:17], v[196:199], v[212:215], v[14:17]
	v_mfma_f32_16x16x32_bf16 v[10:13], v[196:199], v[220:223], v[10:13]
	v_mfma_f32_16x16x32_bf16 v[6:9], v[204:207], v[212:215], v[6:9]
	v_mfma_f32_16x16x32_bf16 v[2:5], v[204:207], v[220:223], v[2:5]
	v_mfma_f32_16x16x32_bf16 v[30:33], v[184:187], v[216:219], v[30:33]
	v_mfma_f32_16x16x32_bf16 v[26:29], v[184:187], v[224:227], v[26:29]
	v_mfma_f32_16x16x32_bf16 v[22:25], v[192:195], v[216:219], v[22:25]
	v_mfma_f32_16x16x32_bf16 v[18:21], v[192:195], v[224:227], v[18:21]
	v_mfma_f32_16x16x32_bf16 v[14:17], v[200:203], v[216:219], v[14:17]
	v_mfma_f32_16x16x32_bf16 v[10:13], v[200:203], v[224:227], v[10:13]
	v_mfma_f32_16x16x32_bf16 v[6:9], v[208:211], v[216:219], v[6:9]
	v_mfma_f32_16x16x32_bf16 v[2:5], v[208:211], v[224:227], v[2:5]
	s_barrier
	v_add_u32_e32 v145, s77, v142
	ds_read_b128 v[148:151], v145
	ds_read_b128 v[152:155], v145 offset:1024
	ds_read_b128 v[156:159], v145 offset:2048
	ds_read_b128 v[160:163], v145 offset:3072
	s_add_u32 s44, s40, 0x80100
	s_addc_u32 s45, s41, 0
	s_mov_b32 m0, s7
	ds_read_b128 v[164:167], v133 offset:32768
	ds_read_b128 v[184:187], v133 offset:33792
	ds_read_b128 v[188:191], v134 offset:32768
	ds_read_b128 v[192:195], v134 offset:33792
	ds_read_b128 v[196:199], v137 offset:32768
	ds_read_b128 v[200:203], v137 offset:33792
	ds_read_b128 v[204:207], v139 offset:32768
	ds_read_b128 v[208:211], v139 offset:33792
	s_nop 0
	v_lshl_add_u64 v[146:147], s[44:45], 0, v[0:1]
	global_load_lds_dwordx4 v[146:147], off
	v_lshl_add_u64 v[146:147], s[44:45], 0, v[140:141]
	s_mov_b32 m0, s29
	s_nop 0
	global_load_lds_dwordx4 v[146:147], off
	s_waitcnt lgkmcnt(8)
	s_barrier
	s_waitcnt lgkmcnt(0)
	s_waitcnt lgkmcnt(0)
	v_mfma_f32_16x16x32_bf16 v[126:129], v[164:167], v[148:151], v[126:129]
	v_mfma_f32_16x16x32_bf16 v[122:125], v[164:167], v[156:159], v[122:125]
	v_mfma_f32_16x16x32_bf16 v[118:121], v[188:191], v[148:151], v[118:121]
	v_mfma_f32_16x16x32_bf16 v[114:117], v[188:191], v[156:159], v[114:117]
	v_mfma_f32_16x16x32_bf16 v[110:113], v[196:199], v[148:151], v[110:113]
	v_mfma_f32_16x16x32_bf16 v[106:109], v[196:199], v[156:159], v[106:109]
	v_mfma_f32_16x16x32_bf16 v[102:105], v[204:207], v[148:151], v[102:105]
	v_mfma_f32_16x16x32_bf16 v[98:101], v[204:207], v[156:159], v[98:101]
	v_mfma_f32_16x16x32_bf16 v[126:129], v[184:187], v[152:155], v[126:129]
	v_mfma_f32_16x16x32_bf16 v[122:125], v[184:187], v[160:163], v[122:125]
	v_mfma_f32_16x16x32_bf16 v[118:121], v[192:195], v[152:155], v[118:121]
	v_mfma_f32_16x16x32_bf16 v[114:117], v[192:195], v[160:163], v[114:117]
	v_mfma_f32_16x16x32_bf16 v[110:113], v[200:203], v[152:155], v[110:113]
	v_mfma_f32_16x16x32_bf16 v[106:109], v[200:203], v[160:163], v[106:109]
	v_mfma_f32_16x16x32_bf16 v[102:105], v[208:211], v[152:155], v[102:105]
	v_mfma_f32_16x16x32_bf16 v[98:101], v[208:211], v[160:163], v[98:101]
	s_barrier
	s_add_u32 s44, s42, 0x180
	v_add_u32_e32 v146, s78, v142
	s_addc_u32 s45, s43, 0
	s_mov_b32 m0, s12
	ds_read_b128 v[212:215], v146
	ds_read_b128 v[216:219], v146 offset:1024
	ds_read_b128 v[220:223], v146 offset:2048
	ds_read_b128 v[224:227], v146 offset:3072
	s_nop 0
	v_lshl_add_u64 v[228:229], s[44:45], 0, v[0:1]
	global_load_lds_dwordx4 v[228:229], off
	v_lshl_add_u64 v[228:229], s[44:45], 0, v[140:141]
	s_mov_b32 m0, s13
	s_nop 0
	global_load_lds_dwordx4 v[228:229], off
	s_barrier
	s_waitcnt lgkmcnt(0)
	s_waitcnt lgkmcnt(0)
	v_mfma_f32_16x16x32_bf16 v[94:97], v[164:167], v[212:215], v[94:97]
	v_mfma_f32_16x16x32_bf16 v[90:93], v[164:167], v[220:223], v[90:93]
	v_mfma_f32_16x16x32_bf16 v[86:89], v[188:191], v[212:215], v[86:89]
	v_mfma_f32_16x16x32_bf16 v[82:85], v[188:191], v[220:223], v[82:85]
	v_mfma_f32_16x16x32_bf16 v[78:81], v[196:199], v[212:215], v[78:81]
	v_mfma_f32_16x16x32_bf16 v[74:77], v[196:199], v[220:223], v[74:77]
	v_mfma_f32_16x16x32_bf16 v[70:73], v[204:207], v[212:215], v[70:73]
	v_mfma_f32_16x16x32_bf16 v[66:69], v[204:207], v[220:223], v[66:69]
	v_mfma_f32_16x16x32_bf16 v[94:97], v[184:187], v[216:219], v[94:97]
	v_mfma_f32_16x16x32_bf16 v[90:93], v[184:187], v[224:227], v[90:93]
	v_mfma_f32_16x16x32_bf16 v[86:89], v[192:195], v[216:219], v[86:89]
	v_mfma_f32_16x16x32_bf16 v[82:85], v[192:195], v[224:227], v[82:85]
	v_mfma_f32_16x16x32_bf16 v[78:81], v[200:203], v[216:219], v[78:81]
	v_mfma_f32_16x16x32_bf16 v[74:77], v[200:203], v[224:227], v[74:77]
	v_mfma_f32_16x16x32_bf16 v[70:73], v[208:211], v[216:219], v[70:73]
	v_mfma_f32_16x16x32_bf16 v[66:69], v[208:211], v[224:227], v[66:69]
	s_barrier
	s_add_u32 s40, s40, 0x180
	s_addc_u32 s41, s41, 0
	s_mov_b32 m0, s14
	ds_read_b128 v[164:167], v133 offset:49152
	ds_read_b128 v[184:187], v133 offset:50176
	ds_read_b128 v[188:191], v134 offset:49152
	ds_read_b128 v[192:195], v134 offset:50176
	ds_read_b128 v[196:199], v137 offset:49152
	ds_read_b128 v[200:203], v137 offset:50176
	ds_read_b128 v[204:207], v139 offset:49152
	ds_read_b128 v[208:211], v139 offset:50176
	s_nop 0
	v_lshl_add_u64 v[228:229], s[40:41], 0, v[0:1]
	global_load_lds_dwordx4 v[228:229], off
	v_lshl_add_u64 v[228:229], s[40:41], 0, v[140:141]
	s_mov_b32 m0, s15
	s_nop 0
	global_load_lds_dwordx4 v[228:229], off
	s_barrier
; #define LDA(dst, b, h) for (int m = 0; m < 4; ++m) for (int k = 0; k < 2; ++k) \
;     dst[m][k] = *reinterpret_cast<const bf16x8*>((char*)SA(b, h) + lds_byte(wr * 64 + m * 16 + fr, k * 32 + fq * 8))
; #define LDB(dst, b, h) for (int n = 0; n < 2; ++n) for (int k = 0; k < 2; ++k) \
;     dst[n][k] = *reinterpret_cast<const bf16x8*>((char*)SB(b, h) + lds_byte(wc * 32 + n * 16 + fr, k * 32 + fq * 8))
; #define MMA(ai, bj, At, Bt_) do { __builtin_amdgcn_s_setprio(1); \
;     for (int m = 0; m < 4; ++m) for (int n = 0; n < 2; ++n) for (int k = 0; k < 2; ++k) \
;       acc[ai][bj][m][n] = __builtin_amdgcn_mfma_f32_16x16x32_bf16(At[m][k], Bt_[n][k], acc[ai][bj][m][n], 0, 0, 0); \
;     __builtin_amdgcn_s_setprio(0); } while (0)
; #define WAIT_V(n) asm volatile("s_waitcnt vmcnt(" #n ")" ::: "memory")
; #define WAIT_L(n) asm volatile("s_waitcnt lgkmcnt(" #n ")" ::: "memory")
; #define BAR __builtin_amdgcn_s_barrier()
; #define SCHED __builtin_amdgcn_sched_barrier(0)
;     ...
;       BAR; WAIT_L(0); MMA(1, 0, At, B0); BAR; SCHED;
;       STAGE(SB(1, 1), Bt, bcol + HALF, t + 3);
;       WAIT_V(6); BAR; MMA(1, 1, At, B1); BAR;
;     }
;     { LDB(B0, 0, 0); LDA(At, 0, 0); STAGE(SA(1, 1), A, brow + HALF, nt - 1);
;       BAR; WAIT_L(0); MMA(0, 0, At, B0); BAR;
;       LDB(B1, 0, 1); BAR; WAIT_L(0); MMA(0, 1, At, B1); BAR;
;       LDA(At, 0, 1); WAIT_V(4); BAR; WAIT_L(0); MMA(1, 0, At, B0); MMA(1, 1, At, B1); BAR; }
	s_waitcnt lgkmcnt(0)
	s_waitcnt lgkmcnt(0)
	v_mfma_f32_16x16x32_bf16 v[62:65], v[164:167], v[148:151], v[62:65]
	v_mfma_f32_16x16x32_bf16 v[58:61], v[164:167], v[156:159], v[58:61]
	v_mfma_f32_16x16x32_bf16 v[54:57], v[188:191], v[148:151], v[54:57]
	v_mfma_f32_16x16x32_bf16 v[50:53], v[188:191], v[156:159], v[50:53]
	v_mfma_f32_16x16x32_bf16 v[46:49], v[196:199], v[148:151], v[46:49]
	v_mfma_f32_16x16x32_bf16 v[42:45], v[196:199], v[156:159], v[42:45]
	v_mfma_f32_16x16x32_bf16 v[38:41], v[204:207], v[148:151], v[38:41]
	v_mfma_f32_16x16x32_bf16 v[34:37], v[204:207], v[156:159], v[34:37]
	v_mfma_f32_16x16x32_bf16 v[62:65], v[184:187], v[152:155], v[62:65]
	v_mfma_f32_16x16x32_bf16 v[58:61], v[184:187], v[160:163], v[58:61]
	v_mfma_f32_16x16x32_bf16 v[54:57], v[192:195], v[152:155], v[54:57]
	v_mfma_f32_16x16x32_bf16 v[50:53], v[192:195], v[160:163], v[50:53]
	v_mfma_f32_16x16x32_bf16 v[46:49], v[200:203], v[152:155], v[46:49]
	v_mfma_f32_16x16x32_bf16 v[42:45], v[200:203], v[160:163], v[42:45]
	v_mfma_f32_16x16x32_bf16 v[38:41], v[208:211], v[152:155], v[38:41]
	v_mfma_f32_16x16x32_bf16 v[34:37], v[208:211], v[160:163], v[34:37]
	s_barrier
	s_add_u32 s40, s42, 0x80180
	s_addc_u32 s41, s43, 0
	s_mov_b32 m0, s16
	s_nop 0
	v_lshl_add_u64 v[148:149], s[40:41], 0, v[0:1]
	global_load_lds_dwordx4 v[148:149], off
	v_lshl_add_u64 v[148:149], s[40:41], 0, v[140:141]
	s_mov_b32 m0, s17
	s_nop 0
	global_load_lds_dwordx4 v[148:149], off
	s_add_i32 s37, s37, 2
	s_add_u32 s10, s10, 0x100
	s_addc_u32 s11, s11, 0
	s_cmp_gt_u32 s37, 27
	s_waitcnt vmcnt(6)
	s_barrier
	v_mfma_f32_16x16x32_bf16 v[30:33], v[164:167], v[212:215], v[30:33]
	v_mfma_f32_16x16x32_bf16 v[26:29], v[164:167], v[220:223], v[26:29]
	v_mfma_f32_16x16x32_bf16 v[22:25], v[188:191], v[212:215], v[22:25]
	v_mfma_f32_16x16x32_bf16 v[18:21], v[188:191], v[220:223], v[18:21]
	v_mfma_f32_16x16x32_bf16 v[14:17], v[196:199], v[212:215], v[14:17]
	v_mfma_f32_16x16x32_bf16 v[10:13], v[196:199], v[220:223], v[10:13]
	v_mfma_f32_16x16x32_bf16 v[6:9], v[204:207], v[212:215], v[6:9]
	v_mfma_f32_16x16x32_bf16 v[2:5], v[204:207], v[220:223], v[2:5]
	v_mfma_f32_16x16x32_bf16 v[30:33], v[184:187], v[216:219], v[30:33]
	v_mfma_f32_16x16x32_bf16 v[26:29], v[184:187], v[224:227], v[26:29]
	v_mfma_f32_16x16x32_bf16 v[22:25], v[192:195], v[216:219], v[22:25]
	v_mfma_f32_16x16x32_bf16 v[18:21], v[192:195], v[224:227], v[18:21]
	v_mfma_f32_16x16x32_bf16 v[14:17], v[200:203], v[216:219], v[14:17]
	v_mfma_f32_16x16x32_bf16 v[10:13], v[200:203], v[224:227], v[10:13]
	v_mfma_f32_16x16x32_bf16 v[6:9], v[208:211], v[216:219], v[6:9]
	v_mfma_f32_16x16x32_bf16 v[2:5], v[208:211], v[224:227], v[2:5]
	s_barrier
	s_cbranch_scc0 .LBB0_155
	s_add_u32 s4, s4, 0xf80
	s_addc_u32 s5, s5, 0
	s_mov_b32 m0, s39
	ds_read_b128 v[148:151], v143
	ds_read_b128 v[152:155], v143 offset:1024
	ds_read_b128 v[156:159], v143 offset:2048
	ds_read_b128 v[160:163], v143 offset:3072
	ds_read_b128 v[164:167], v133
	ds_read_b128 v[184:187], v133 offset:1024
	ds_read_b128 v[188:191], v134
	ds_read_b128 v[192:195], v134 offset:1024
	ds_read_b128 v[196:199], v137
	ds_read_b128 v[200:203], v137 offset:1024
	ds_read_b128 v[204:207], v139
	ds_read_b128 v[208:211], v139 offset:1024
	s_nop 0
	v_lshl_add_u64 v[142:143], s[4:5], 0, v[0:1]
	global_load_lds_dwordx4 v[142:143], off
	v_lshl_add_u64 v[140:141], s[4:5], 0, v[140:141]
	s_mov_b32 m0, s38
	s_nop 0
	global_load_lds_dwordx4 v[140:141], off
	s_barrier
	s_waitcnt lgkmcnt(0)
	s_setprio 1
	s_waitcnt lgkmcnt(0)
	v_mfma_f32_16x16x32_bf16 v[126:129], v[164:167], v[148:151], v[126:129]
	v_mfma_f32_16x16x32_bf16 v[118:121], v[188:191], v[148:151], v[118:121]
	v_mfma_f32_16x16x32_bf16 v[110:113], v[196:199], v[148:151], v[110:113]
	v_mfma_f32_16x16x32_bf16 v[102:105], v[204:207], v[148:151], v[102:105]
	v_mfma_f32_16x16x32_bf16 v[126:129], v[184:187], v[152:155], v[126:129]
	v_mfma_f32_16x16x32_bf16 v[122:125], v[164:167], v[156:159], v[122:125]
	v_mfma_f32_16x16x32_bf16 v[118:121], v[192:195], v[152:155], v[118:121]
	v_mfma_f32_16x16x32_bf16 v[114:117], v[188:191], v[156:159], v[114:117]
	v_mfma_f32_16x16x32_bf16 v[110:113], v[200:203], v[152:155], v[110:113]
	v_mfma_f32_16x16x32_bf16 v[106:109], v[196:199], v[156:159], v[106:109]
	v_mfma_f32_16x16x32_bf16 v[102:105], v[208:211], v[152:155], v[102:105]
	v_mfma_f32_16x16x32_bf16 v[98:101], v[204:207], v[156:159], v[98:101]
	v_mfma_f32_16x16x32_bf16 v[140:143], v[184:187], v[160:163], v[122:125]
	v_mfma_f32_16x16x32_bf16 v[212:215], v[192:195], v[160:163], v[114:117]
	v_mfma_f32_16x16x32_bf16 v[216:219], v[200:203], v[160:163], v[106:109]
	v_mfma_f32_16x16x32_bf16 v[220:223], v[208:211], v[160:163], v[98:101]
	s_setprio 0
	s_barrier
	s_nop 1
	ds_read_b128 v[98:101], v144
	ds_read_b128 v[106:109], v144 offset:1024
	ds_read_b128 v[114:117], v144 offset:2048
	ds_read_b128 v[122:125], v144 offset:3072
	s_barrier
	s_waitcnt lgkmcnt(0)
	s_setprio 1
	s_waitcnt lgkmcnt(0)
	v_mfma_f32_16x16x32_bf16 v[94:97], v[164:167], v[98:101], v[94:97]
	v_mfma_f32_16x16x32_bf16 v[86:89], v[188:191], v[98:101], v[86:89]
	v_mfma_f32_16x16x32_bf16 v[78:81], v[196:199], v[98:101], v[78:81]
	v_mfma_f32_16x16x32_bf16 v[70:73], v[204:207], v[98:101], v[70:73]
	v_mfma_f32_16x16x32_bf16 v[94:97], v[184:187], v[106:109], v[94:97]
	v_mfma_f32_16x16x32_bf16 v[90:93], v[164:167], v[114:117], v[90:93]
	v_mfma_f32_16x16x32_bf16 v[86:89], v[192:195], v[106:109], v[86:89]
	v_mfma_f32_16x16x32_bf16 v[82:85], v[188:191], v[114:117], v[82:85]
	v_mfma_f32_16x16x32_bf16 v[78:81], v[200:203], v[106:109], v[78:81]
	v_mfma_f32_16x16x32_bf16 v[74:77], v[196:199], v[114:117], v[74:77]
	v_mfma_f32_16x16x32_bf16 v[70:73], v[208:211], v[106:109], v[70:73]
	v_mfma_f32_16x16x32_bf16 v[66:69], v[204:207], v[114:117], v[66:69]
	v_mfma_f32_16x16x32_bf16 v[164:167], v[184:187], v[122:125], v[90:93]
	v_mfma_f32_16x16x32_bf16 v[184:187], v[192:195], v[122:125], v[82:85]
	v_mfma_f32_16x16x32_bf16 v[188:191], v[200:203], v[122:125], v[74:77]
	v_mfma_f32_16x16x32_bf16 v[192:195], v[208:211], v[122:125], v[66:69]
	s_setprio 0
	s_barrier
; #define LDA(dst, b, h) for (int m = 0; m < 4; ++m) for (int k = 0; k < 2; ++k) \
;     dst[m][k] = *reinterpret_cast<const bf16x8*>((char*)SA(b, h) + lds_byte(wr * 64 + m * 16 + fr, k * 32 + fq * 8))
; #define LDB(dst, b, h) for (int n = 0; n < 2; ++n) for (int k = 0; k < 2; ++k) \
;     dst[n][k] = *reinterpret_cast<const bf16x8*>((char*)SB(b, h) + lds_byte(wc * 32 + n * 16 + fr, k * 32 + fq * 8))
; #define MMA(ai, bj, At, Bt_) do { __builtin_amdgcn_s_setprio(1); \
;     for (int m = 0; m < 4; ++m) for (int n = 0; n < 2; ++n) for (int k = 0; k < 2; ++k) \
;       acc[ai][bj][m][n] = __builtin_amdgcn_mfma_f32_16x16x32_bf16(At[m][k], Bt_[n][k], acc[ai][bj][m][n], 0, 0, 0); \
;     __builtin_amdgcn_s_setprio(0); } while (0)
; #define WAIT_V(n) asm volatile("s_waitcnt vmcnt(" #n ")" ::: "memory")
; #define WAIT_L(n) asm volatile("s_waitcnt lgkmcnt(" #n ")" ::: "memory")
; #define BAR __builtin_amdgcn_s_barrier()
;     ...
;       LDA(At, 0, 1); WAIT_V(4); BAR; WAIT_L(0); MMA(1, 0, At, B0); MMA(1, 1, At, B1); BAR; }
;     { LDB(B0, 1, 0); LDA(At, 1, 0); WAIT_V(2); BAR; WAIT_L(0); MMA(0, 0, At, B0); BAR;
	s_nop 1
	ds_read_b128 v[66:69], v133 offset:16384
	ds_read_b128 v[74:77], v133 offset:17408
	ds_read_b128 v[82:85], v134 offset:16384
	ds_read_b128 v[90:93], v134 offset:17408
	ds_read_b128 v[196:199], v137 offset:16384
	ds_read_b128 v[200:203], v137 offset:17408
	ds_read_b128 v[204:207], v139 offset:16384
	ds_read_b128 v[208:211], v139 offset:17408
	s_waitcnt vmcnt(4)
	s_barrier
	s_waitcnt lgkmcnt(0)
	s_setprio 1
	s_waitcnt lgkmcnt(0)
	v_mfma_f32_16x16x32_bf16 v[62:65], v[66:69], v[148:151], v[62:65]
	v_mfma_f32_16x16x32_bf16 v[54:57], v[82:85], v[148:151], v[54:57]
	v_mfma_f32_16x16x32_bf16 v[46:49], v[196:199], v[148:151], v[46:49]
	v_mfma_f32_16x16x32_bf16 v[38:41], v[204:207], v[148:151], v[38:41]
	v_mfma_f32_16x16x32_bf16 v[62:65], v[74:77], v[152:155], v[62:65]
	v_mfma_f32_16x16x32_bf16 v[58:61], v[66:69], v[156:159], v[58:61]
	v_mfma_f32_16x16x32_bf16 v[54:57], v[90:93], v[152:155], v[54:57]
	v_mfma_f32_16x16x32_bf16 v[50:53], v[82:85], v[156:159], v[50:53]
	v_mfma_f32_16x16x32_bf16 v[46:49], v[200:203], v[152:155], v[46:49]
	v_mfma_f32_16x16x32_bf16 v[42:45], v[196:199], v[156:159], v[42:45]
	v_mfma_f32_16x16x32_bf16 v[38:41], v[208:211], v[152:155], v[38:41]
	v_mfma_f32_16x16x32_bf16 v[34:37], v[204:207], v[156:159], v[34:37]
	v_mfma_f32_16x16x32_bf16 v[224:227], v[74:77], v[160:163], v[58:61]
	v_mfma_f32_16x16x32_bf16 v[228:231], v[90:93], v[160:163], v[50:53]
	v_mfma_f32_16x16x32_bf16 v[232:235], v[200:203], v[160:163], v[42:45]
	v_mfma_f32_16x16x32_bf16 v[148:151], v[208:211], v[160:163], v[34:37]
	s_setprio 0
	s_setprio 1
	v_mfma_f32_16x16x32_bf16 v[30:33], v[66:69], v[98:101], v[30:33]
	v_mfma_f32_16x16x32_bf16 v[22:25], v[82:85], v[98:101], v[22:25]
	v_mfma_f32_16x16x32_bf16 v[14:17], v[196:199], v[98:101], v[14:17]
	v_mfma_f32_16x16x32_bf16 v[6:9], v[204:207], v[98:101], v[6:9]
	v_mfma_f32_16x16x32_bf16 v[30:33], v[74:77], v[106:109], v[30:33]
	v_mfma_f32_16x16x32_bf16 v[26:29], v[66:69], v[114:117], v[26:29]
	v_mfma_f32_16x16x32_bf16 v[22:25], v[90:93], v[106:109], v[22:25]
	v_mfma_f32_16x16x32_bf16 v[18:21], v[82:85], v[114:117], v[18:21]
	v_mfma_f32_16x16x32_bf16 v[14:17], v[200:203], v[106:109], v[14:17]
	v_mfma_f32_16x16x32_bf16 v[10:13], v[196:199], v[114:117], v[10:13]
	v_mfma_f32_16x16x32_bf16 v[6:9], v[208:211], v[106:109], v[6:9]
	v_mfma_f32_16x16x32_bf16 v[2:5], v[204:207], v[114:117], v[2:5]
	v_mfma_f32_16x16x32_bf16 v[152:155], v[74:77], v[122:125], v[26:29]
	v_mfma_f32_16x16x32_bf16 v[156:159], v[90:93], v[122:125], v[18:21]
	v_mfma_f32_16x16x32_bf16 v[160:163], v[200:203], v[122:125], v[10:13]
	v_mfma_f32_16x16x32_bf16 v[196:199], v[208:211], v[122:125], v[2:5]
	s_setprio 0
	s_barrier
	s_nop 1
	ds_read_b128 v[2:5], v145
	ds_read_b128 v[10:13], v145 offset:1024
	ds_read_b128 v[200:203], v145 offset:2048
	ds_read_b128 v[204:207], v145 offset:3072
	ds_read_b128 v[18:21], v133 offset:32768
	ds_read_b128 v[26:29], v133 offset:33792
	ds_read_b128 v[34:37], v134 offset:32768
	ds_read_b128 v[42:45], v134 offset:33792
	ds_read_b128 v[50:53], v137 offset:32768
	ds_read_b128 v[58:61], v137 offset:33792
	ds_read_b128 v[208:211], v139 offset:32768
	ds_read_b128 v[236:239], v139 offset:33792
	s_waitcnt vmcnt(2)
	s_barrier
	s_waitcnt lgkmcnt(0)
	s_setprio 1
	s_waitcnt lgkmcnt(0)
	v_mfma_f32_16x16x32_bf16 v[66:69], v[18:21], v[2:5], v[126:129]
	v_mfma_f32_16x16x32_bf16 v[122:125], v[26:29], v[10:13], v[66:69]
	v_mfma_f32_16x16x32_bf16 v[66:69], v[18:21], v[200:203], v[140:143]
	v_mfma_f32_16x16x32_bf16 v[114:117], v[26:29], v[204:207], v[66:69]
	v_mfma_f32_16x16x32_bf16 v[66:69], v[34:37], v[2:5], v[118:121]
	v_mfma_f32_16x16x32_bf16 v[106:109], v[42:45], v[10:13], v[66:69]
	v_mfma_f32_16x16x32_bf16 v[66:69], v[34:37], v[200:203], v[212:215]
	v_mfma_f32_16x16x32_bf16 v[98:101], v[42:45], v[204:207], v[66:69]
	v_mfma_f32_16x16x32_bf16 v[66:69], v[50:53], v[2:5], v[110:113]
	v_mfma_f32_16x16x32_bf16 v[90:93], v[58:61], v[10:13], v[66:69]
	v_mfma_f32_16x16x32_bf16 v[66:69], v[50:53], v[200:203], v[216:219]
	v_mfma_f32_16x16x32_bf16 v[82:85], v[58:61], v[204:207], v[66:69]
	v_mfma_f32_16x16x32_bf16 v[66:69], v[208:211], v[2:5], v[102:105]
	v_mfma_f32_16x16x32_bf16 v[74:77], v[236:239], v[10:13], v[66:69]
	v_mfma_f32_16x16x32_bf16 v[66:69], v[208:211], v[200:203], v[220:223]
	v_mfma_f32_16x16x32_bf16 v[66:69], v[236:239], v[204:207], v[66:69]
	s_setprio 0
	s_barrier
; #define LDA(dst, b, h) for (int m = 0; m < 4; ++m) for (int k = 0; k < 2; ++k) \
;     dst[m][k] = *reinterpret_cast<const bf16x8*>((char*)SA(b, h) + lds_byte(wr * 64 + m * 16 + fr, k * 32 + fq * 8))
; #define LDB(dst, b, h) for (int n = 0; n < 2; ++n) for (int k = 0; k < 2; ++k) \
;     dst[n][k] = *reinterpret_cast<const bf16x8*>((char*)SB(b, h) + lds_byte(wc * 32 + n * 16 + fr, k * 32 + fq * 8))
; #define MMA(ai, bj, At, Bt_) do { __builtin_amdgcn_s_setprio(1); \
;     for (int m = 0; m < 4; ++m) for (int n = 0; n < 2; ++n) for (int k = 0; k < 2; ++k) \
;       acc[ai][bj][m][n] = __builtin_amdgcn_mfma_f32_16x16x32_bf16(At[m][k], Bt_[n][k], acc[ai][bj][m][n], 0, 0, 0); \
;     __builtin_amdgcn_s_setprio(0); } while (0)
; #define WAIT_V(n) asm volatile("s_waitcnt vmcnt(" #n ")" ::: "memory")
; #define WAIT_L(n) asm volatile("s_waitcnt lgkmcnt(" #n ")" ::: "memory")
; #define BAR __builtin_amdgcn_s_barrier()
;     ...
;     { LDB(B0, 1, 0); LDA(At, 1, 0); WAIT_V(2); BAR; WAIT_L(0); MMA(0, 0, At, B0); BAR;
;       LDB(B1, 1, 1); WAIT_V(0); BAR; WAIT_L(0); MMA(0, 1, At, B1); BAR;
;       LDA(At, 1, 1); BAR; WAIT_L(0); MMA(1, 0, At, B0); MMA(1, 1, At, B1); BAR; }
;     if (wr == 0) BAR;
	ds_read_b128 v[140:143], v146
	ds_read_b128 v[212:215], v146 offset:1024
	ds_read_b128 v[216:219], v146 offset:2048
	ds_read_b128 v[144:147], v146 offset:3072
	s_waitcnt vmcnt(0)
	s_barrier
	s_waitcnt lgkmcnt(0)
	s_setprio 1
	s_waitcnt lgkmcnt(0)
	v_mfma_f32_16x16x32_bf16 v[94:97], v[18:21], v[140:143], v[94:97]
	v_mfma_f32_16x16x32_bf16 v[18:21], v[18:21], v[216:219], v[164:167]
	v_mfma_f32_16x16x32_bf16 v[118:121], v[26:29], v[144:147], v[18:21]
	v_mfma_f32_16x16x32_bf16 v[18:21], v[34:37], v[140:143], v[86:89]
	v_mfma_f32_16x16x32_bf16 v[110:113], v[42:45], v[212:215], v[18:21]
	v_mfma_f32_16x16x32_bf16 v[18:21], v[34:37], v[216:219], v[184:187]
	v_mfma_f32_16x16x32_bf16 v[102:105], v[42:45], v[144:147], v[18:21]
	v_mfma_f32_16x16x32_bf16 v[18:21], v[50:53], v[140:143], v[78:81]
	v_mfma_f32_16x16x32_bf16 v[126:129], v[26:29], v[212:215], v[94:97]
	v_mfma_f32_16x16x32_bf16 v[94:97], v[58:61], v[212:215], v[18:21]
	v_mfma_f32_16x16x32_bf16 v[18:21], v[50:53], v[216:219], v[188:191]
	v_mfma_f32_16x16x32_bf16 v[86:89], v[58:61], v[144:147], v[18:21]
	v_mfma_f32_16x16x32_bf16 v[18:21], v[208:211], v[140:143], v[70:73]
	v_mfma_f32_16x16x32_bf16 v[78:81], v[236:239], v[212:215], v[18:21]
	v_mfma_f32_16x16x32_bf16 v[18:21], v[208:211], v[216:219], v[192:195]
	v_mfma_f32_16x16x32_bf16 v[70:73], v[236:239], v[144:147], v[18:21]
	s_setprio 0
	s_barrier
	ds_read_b128 v[164:167], v133 offset:49152
	ds_read_b128 v[184:187], v133 offset:50176
	ds_read_b128 v[188:191], v134 offset:49152
	ds_read_b128 v[192:195], v134 offset:50176
	ds_read_b128 v[208:211], v137 offset:49152
	ds_read_b128 v[220:223], v137 offset:50176
	ds_read_b128 v[236:239], v139 offset:49152
	ds_read_b128 v[240:243], v139 offset:50176
	s_barrier
	s_waitcnt lgkmcnt(0)
	s_setprio 1
	s_waitcnt lgkmcnt(0)
	v_mfma_f32_16x16x32_bf16 v[18:21], v[164:167], v[2:5], v[62:65]
	v_mfma_f32_16x16x32_bf16 v[58:61], v[184:187], v[10:13], v[18:21]
	v_mfma_f32_16x16x32_bf16 v[18:21], v[164:167], v[200:203], v[224:227]
	v_mfma_f32_16x16x32_bf16 v[50:53], v[184:187], v[204:207], v[18:21]
	v_mfma_f32_16x16x32_bf16 v[18:21], v[188:191], v[2:5], v[54:57]
	v_mfma_f32_16x16x32_bf16 v[42:45], v[192:195], v[10:13], v[18:21]
	v_mfma_f32_16x16x32_bf16 v[18:21], v[188:191], v[200:203], v[228:231]
	v_mfma_f32_16x16x32_bf16 v[34:37], v[192:195], v[204:207], v[18:21]
	v_mfma_f32_16x16x32_bf16 v[18:21], v[208:211], v[2:5], v[46:49]
	v_mfma_f32_16x16x32_bf16 v[2:5], v[236:239], v[2:5], v[38:41]
	v_mfma_f32_16x16x32_bf16 v[26:29], v[220:223], v[10:13], v[18:21]
	v_mfma_f32_16x16x32_bf16 v[18:21], v[208:211], v[200:203], v[232:235]
	v_mfma_f32_16x16x32_bf16 v[10:13], v[240:243], v[10:13], v[2:5]
	v_mfma_f32_16x16x32_bf16 v[2:5], v[236:239], v[200:203], v[148:151]
	v_mfma_f32_16x16x32_bf16 v[18:21], v[220:223], v[204:207], v[18:21]
	v_mfma_f32_16x16x32_bf16 v[2:5], v[240:243], v[204:207], v[2:5]
	s_setprio 0
	s_setprio 1
	v_mfma_f32_16x16x32_bf16 v[30:33], v[164:167], v[140:143], v[30:33]
	v_mfma_f32_16x16x32_bf16 v[62:65], v[184:187], v[212:215], v[30:33]
	v_mfma_f32_16x16x32_bf16 v[30:33], v[164:167], v[216:219], v[152:155]
	v_mfma_f32_16x16x32_bf16 v[22:25], v[188:191], v[140:143], v[22:25]
	v_mfma_f32_16x16x32_bf16 v[14:17], v[208:211], v[140:143], v[14:17]
	v_mfma_f32_16x16x32_bf16 v[54:57], v[184:187], v[144:147], v[30:33]
	v_mfma_f32_16x16x32_bf16 v[46:49], v[192:195], v[212:215], v[22:25]
	v_mfma_f32_16x16x32_bf16 v[22:25], v[188:191], v[216:219], v[156:159]
	v_mfma_f32_16x16x32_bf16 v[30:33], v[220:223], v[212:215], v[14:17]
	v_mfma_f32_16x16x32_bf16 v[14:17], v[208:211], v[216:219], v[160:163]
	v_mfma_f32_16x16x32_bf16 v[6:9], v[236:239], v[140:143], v[6:9]
	v_mfma_f32_16x16x32_bf16 v[38:41], v[192:195], v[144:147], v[22:25]
	v_mfma_f32_16x16x32_bf16 v[22:25], v[220:223], v[144:147], v[14:17]
	v_mfma_f32_16x16x32_bf16 v[14:17], v[240:243], v[212:215], v[6:9]
	v_mfma_f32_16x16x32_bf16 v[6:9], v[236:239], v[216:219], v[196:199]
	v_mfma_f32_16x16x32_bf16 v[6:9], v[240:243], v[144:147], v[6:9]
	s_setprio 0
	v_readlane_b32 s4, v245, 33
	v_readlane_b32 s5, v245, 34
	s_and_b64 vcc, exec, s[4:5]
	s_barrier
	s_cbranch_vccz .LBB0_158
	s_barrier

; #define LDA(dst, b, h) for (int m = 0; m < 4; ++m) for (int k = 0; k < 2; ++k) \
;     dst[m][k] = *reinterpret_cast<const bf16x8*>((char*)SA(b, h) + lds_byte(wr * 64 + m * 16 + fr, k * 32 + fq * 8))
; #define LDB(dst, b, h) for (int n = 0; n < 2; ++n) for (int k = 0; k < 2; ++k) \
;     dst[n][k] = *reinterpret_cast<const bf16x8*>((char*)SB(b, h) + lds_byte(wc * 32 + n * 16 + fr, k * 32 + fq * 8))
; #define MMA(ai, bj, At, Bt_) do { __builtin_amdgcn_s_setprio(1); \
;     for (int m = 0; m < 4; ++m) for (int n = 0; n < 2; ++n) for (int k = 0; k < 2; ++k) \
;       acc[ai][bj][m][n] = __builtin_amdgcn_mfma_f32_16x16x32_bf16(At[m][k], Bt_[n][k], acc[ai][bj][m][n], 0, 0, 0); \
;     __builtin_amdgcn_s_setprio(0); } while (0)
; #define WAIT_V(n) asm volatile("s_waitcnt vmcnt(" #n ")" ::: "memory")
; #define WAIT_L(n) asm volatile("s_waitcnt lgkmcnt(" #n ")" ::: "memory")
; #define BAR __builtin_amdgcn_s_barrier()
; #define SCHED __builtin_amdgcn_sched_barrier(0)
;     ...
;     for (int t = 0; t < nt - 2; t += 2) {
;       LDB(B0, 0, 0); SCHED; LDA(At, 0, 0); STAGE(SA(1, 1), A, brow + HALF, t + 1);
;       WAIT_L(8); BAR; WAIT_L(0); MMA(0, 0, At, B0); BAR; SCHED;
;       LDB(B1, 0, 1); STAGE(SB(0, 0), Bt, bcol, t + 2);
;       BAR; WAIT_L(0); MMA(0, 1, At, B1); BAR;
;       LDA(At, 0, 1); STAGE(SA(0, 0), A, brow, t + 2);
;       BAR; WAIT_L(0); MMA(1, 0, At, B0); BAR; SCHED;
;       STAGE(SB(0, 1), Bt, bcol + HALF, t + 2);
;       WAIT_V(6); BAR; MMA(1, 1, At, B1); BAR;
.LBB0_202:
	v_add_u32_e32 v143, s2, v142
	ds_read_b128 v[146:149], v143
	ds_read_b128 v[150:153], v143 offset:1024
	ds_read_b128 v[154:157], v143 offset:2048
	ds_read_b128 v[158:161], v143 offset:3072
	s_add_u32 s66, s50, s16
	s_addc_u32 s67, s51, s17
	s_add_i32 s58, s21, 0xc000
	ds_read_b128 v[162:165], v133
	ds_read_b128 v[184:187], v133 offset:1024
	ds_read_b128 v[188:191], v134
	ds_read_b128 v[192:195], v134 offset:1024
	ds_read_b128 v[196:199], v137
	ds_read_b128 v[200:203], v137 offset:1024
	ds_read_b128 v[204:207], v139
	ds_read_b128 v[208:211], v139 offset:1024
	s_mov_b32 m0, s58
	v_lshl_add_u64 v[144:145], s[66:67], 0, v[0:1]
	s_add_i32 s57, s21, 0xe000
	global_load_lds_dwordx4 v[144:145], off
	v_lshl_add_u64 v[144:145], s[66:67], 0, v[140:141]
	s_mov_b32 m0, s57
	s_nop 0
	global_load_lds_dwordx4 v[144:145], off
	s_waitcnt lgkmcnt(8)
	s_barrier
	s_waitcnt lgkmcnt(0)
	s_waitcnt lgkmcnt(0)
	v_mfma_f32_16x16x32_bf16 v[126:129], v[162:165], v[146:149], v[126:129]
	v_mfma_f32_16x16x32_bf16 v[122:125], v[162:165], v[154:157], v[122:125]
	v_mfma_f32_16x16x32_bf16 v[118:121], v[188:191], v[146:149], v[118:121]
	v_mfma_f32_16x16x32_bf16 v[114:117], v[188:191], v[154:157], v[114:117]
	v_mfma_f32_16x16x32_bf16 v[110:113], v[196:199], v[146:149], v[110:113]
	v_mfma_f32_16x16x32_bf16 v[106:109], v[196:199], v[154:157], v[106:109]
	v_mfma_f32_16x16x32_bf16 v[102:105], v[204:207], v[146:149], v[102:105]
	v_mfma_f32_16x16x32_bf16 v[98:101], v[204:207], v[154:157], v[98:101]
	v_mfma_f32_16x16x32_bf16 v[126:129], v[184:187], v[150:153], v[126:129]
	v_mfma_f32_16x16x32_bf16 v[122:125], v[184:187], v[158:161], v[122:125]
	v_mfma_f32_16x16x32_bf16 v[118:121], v[192:195], v[150:153], v[118:121]
	v_mfma_f32_16x16x32_bf16 v[114:117], v[192:195], v[158:161], v[114:117]
	v_mfma_f32_16x16x32_bf16 v[110:113], v[200:203], v[150:153], v[110:113]
	v_mfma_f32_16x16x32_bf16 v[106:109], v[200:203], v[158:161], v[106:109]
	v_mfma_f32_16x16x32_bf16 v[102:105], v[208:211], v[150:153], v[102:105]
	v_mfma_f32_16x16x32_bf16 v[98:101], v[208:211], v[158:161], v[98:101]
	s_barrier
	s_add_i32 s55, s55, 2
	s_add_u32 s59, s11, s16
	s_addc_u32 s63, s44, s17
	s_add_u32 s66, s59, 0x100
	v_add_u32_e32 v144, s76, v142
	s_addc_u32 s67, s63, 0
	s_mov_b32 m0, s29
	ds_read_b128 v[212:215], v144
	ds_read_b128 v[216:219], v144 offset:1024
	ds_read_b128 v[220:223], v144 offset:2048
	ds_read_b128 v[224:227], v144 offset:3072
	s_nop 0
	v_lshl_add_u64 v[166:167], s[66:67], 0, v[0:1]
	global_load_lds_dwordx4 v[166:167], off
	v_lshl_add_u64 v[166:167], s[66:67], 0, v[140:141]
	s_mov_b32 m0, s30
	s_nop 0
	global_load_lds_dwordx4 v[166:167], off
	s_barrier
	s_waitcnt lgkmcnt(0)
	s_waitcnt lgkmcnt(0)
	v_mfma_f32_16x16x32_bf16 v[94:97], v[162:165], v[212:215], v[94:97]
	v_mfma_f32_16x16x32_bf16 v[90:93], v[162:165], v[220:223], v[90:93]
	v_mfma_f32_16x16x32_bf16 v[86:89], v[188:191], v[212:215], v[86:89]
	v_mfma_f32_16x16x32_bf16 v[82:85], v[188:191], v[220:223], v[82:85]
	v_mfma_f32_16x16x32_bf16 v[78:81], v[196:199], v[212:215], v[78:81]
	v_mfma_f32_16x16x32_bf16 v[74:77], v[196:199], v[220:223], v[74:77]
	v_mfma_f32_16x16x32_bf16 v[70:73], v[204:207], v[212:215], v[70:73]
	v_mfma_f32_16x16x32_bf16 v[66:69], v[204:207], v[220:223], v[66:69]
	v_mfma_f32_16x16x32_bf16 v[94:97], v[184:187], v[216:219], v[94:97]
	v_mfma_f32_16x16x32_bf16 v[90:93], v[184:187], v[224:227], v[90:93]
	v_mfma_f32_16x16x32_bf16 v[86:89], v[192:195], v[216:219], v[86:89]
	v_mfma_f32_16x16x32_bf16 v[82:85], v[192:195], v[224:227], v[82:85]
	v_mfma_f32_16x16x32_bf16 v[78:81], v[200:203], v[216:219], v[78:81]
	v_mfma_f32_16x16x32_bf16 v[74:77], v[200:203], v[224:227], v[74:77]
	v_mfma_f32_16x16x32_bf16 v[70:73], v[208:211], v[216:219], v[70:73]
	v_mfma_f32_16x16x32_bf16 v[66:69], v[208:211], v[224:227], v[66:69]
	s_barrier
	s_add_u32 s65, s13, s16
	s_addc_u32 s70, s45, s17
	s_add_u32 s66, s65, 0x100
	s_addc_u32 s67, s70, 0
	s_mov_b32 m0, s21
	ds_read_b128 v[162:165], v133 offset:16384
	ds_read_b128 v[184:187], v133 offset:17408
	ds_read_b128 v[188:191], v134 offset:16384
	ds_read_b128 v[192:195], v134 offset:17408
	ds_read_b128 v[196:199], v137 offset:16384
	ds_read_b128 v[200:203], v137 offset:17408
	ds_read_b128 v[204:207], v139 offset:16384
	ds_read_b128 v[208:211], v139 offset:17408
	s_nop 0
	v_lshl_add_u64 v[166:167], s[66:67], 0, v[0:1]
	global_load_lds_dwordx4 v[166:167], off
	v_lshl_add_u64 v[166:167], s[66:67], 0, v[140:141]
	s_mov_b32 m0, s31
	s_nop 0
	global_load_lds_dwordx4 v[166:167], off
	s_barrier
	s_waitcnt lgkmcnt(0)
	s_waitcnt lgkmcnt(0)
	v_mfma_f32_16x16x32_bf16 v[62:65], v[162:165], v[146:149], v[62:65]
	v_mfma_f32_16x16x32_bf16 v[58:61], v[162:165], v[154:157], v[58:61]
	v_mfma_f32_16x16x32_bf16 v[54:57], v[188:191], v[146:149], v[54:57]
	v_mfma_f32_16x16x32_bf16 v[50:53], v[188:191], v[154:157], v[50:53]
	v_mfma_f32_16x16x32_bf16 v[46:49], v[196:199], v[146:149], v[46:49]
	v_mfma_f32_16x16x32_bf16 v[42:45], v[196:199], v[154:157], v[42:45]
	v_mfma_f32_16x16x32_bf16 v[38:41], v[204:207], v[146:149], v[38:41]
	v_mfma_f32_16x16x32_bf16 v[34:37], v[204:207], v[154:157], v[34:37]
	v_mfma_f32_16x16x32_bf16 v[62:65], v[184:187], v[150:153], v[62:65]
	v_mfma_f32_16x16x32_bf16 v[58:61], v[184:187], v[158:161], v[58:61]
	v_mfma_f32_16x16x32_bf16 v[54:57], v[192:195], v[150:153], v[54:57]
	v_mfma_f32_16x16x32_bf16 v[50:53], v[192:195], v[158:161], v[50:53]
	v_mfma_f32_16x16x32_bf16 v[46:49], v[200:203], v[150:153], v[46:49]
	v_mfma_f32_16x16x32_bf16 v[42:45], v[200:203], v[158:161], v[42:45]
	v_mfma_f32_16x16x32_bf16 v[38:41], v[208:211], v[150:153], v[38:41]
	v_mfma_f32_16x16x32_bf16 v[34:37], v[208:211], v[158:161], v[34:37]
	s_barrier
; #define LDA(dst, b, h) for (int m = 0; m < 4; ++m) for (int k = 0; k < 2; ++k) \
;     dst[m][k] = *reinterpret_cast<const bf16x8*>((char*)SA(b, h) + lds_byte(wr * 64 + m * 16 + fr, k * 32 + fq * 8))
; #define LDB(dst, b, h) for (int n = 0; n < 2; ++n) for (int k = 0; k < 2; ++k) \
;     dst[n][k] = *reinterpret_cast<const bf16x8*>((char*)SB(b, h) + lds_byte(wc * 32 + n * 16 + fr, k * 32 + fq * 8))
; #define MMA(ai, bj, At, Bt_) do { __builtin_amdgcn_s_setprio(1); \
;     for (int m = 0; m < 4; ++m) for (int n = 0; n < 2; ++n) for (int k = 0; k < 2; ++k) \
;       acc[ai][bj][m][n] = __builtin_amdgcn_mfma_f32_16x16x32_bf16(At[m][k], Bt_[n][k], acc[ai][bj][m][n], 0, 0, 0); \
;     __builtin_amdgcn_s_setprio(0); } while (0)
; #define WAIT_V(n) asm volatile("s_waitcnt vmcnt(" #n ")" ::: "memory")
; #define WAIT_L(n) asm volatile("s_waitcnt lgkmcnt(" #n ")" ::: "memory")
; #define BAR __builtin_amdgcn_s_barrier()
; #define SCHED __builtin_amdgcn_sched_barrier(0)
;     ...
;       WAIT_V(6); BAR; MMA(1, 1, At, B1); BAR;
;       LDB(B0, 1, 0); SCHED; LDA(At, 1, 0); STAGE(SA(0, 1), A, brow + HALF, t + 2);
;       WAIT_L(8); BAR; WAIT_L(0); MMA(0, 0, At, B0); BAR; SCHED;
;       LDB(B1, 1, 1); STAGE(SB(1, 0), Bt, bcol, t + 3);
;       BAR; WAIT_L(0); MMA(0, 1, At, B1); BAR;
;       LDA(At, 1, 1); STAGE(SA(1, 0), A, brow, t + 3);
;       BAR; WAIT_L(0); MMA(1, 0, At, B0); BAR; SCHED;
	s_add_u32 s66, s59, 0x80100
	s_addc_u32 s67, s63, 0
	s_mov_b32 m0, s34
	s_nop 0
	v_lshl_add_u64 v[146:147], s[66:67], 0, v[0:1]
	global_load_lds_dwordx4 v[146:147], off
	v_lshl_add_u64 v[146:147], s[66:67], 0, v[140:141]
	s_mov_b32 m0, s35
	s_nop 0
	global_load_lds_dwordx4 v[146:147], off
	s_waitcnt vmcnt(6)
	s_barrier
	v_mfma_f32_16x16x32_bf16 v[30:33], v[162:165], v[212:215], v[30:33]
	v_mfma_f32_16x16x32_bf16 v[26:29], v[162:165], v[220:223], v[26:29]
	v_mfma_f32_16x16x32_bf16 v[22:25], v[188:191], v[212:215], v[22:25]
	v_mfma_f32_16x16x32_bf16 v[18:21], v[188:191], v[220:223], v[18:21]
	v_mfma_f32_16x16x32_bf16 v[14:17], v[196:199], v[212:215], v[14:17]
	v_mfma_f32_16x16x32_bf16 v[10:13], v[196:199], v[220:223], v[10:13]
	v_mfma_f32_16x16x32_bf16 v[6:9], v[204:207], v[212:215], v[6:9]
	v_mfma_f32_16x16x32_bf16 v[2:5], v[204:207], v[220:223], v[2:5]
	v_mfma_f32_16x16x32_bf16 v[30:33], v[184:187], v[216:219], v[30:33]
	v_mfma_f32_16x16x32_bf16 v[26:29], v[184:187], v[224:227], v[26:29]
	v_mfma_f32_16x16x32_bf16 v[22:25], v[192:195], v[216:219], v[22:25]
	v_mfma_f32_16x16x32_bf16 v[18:21], v[192:195], v[224:227], v[18:21]
	v_mfma_f32_16x16x32_bf16 v[14:17], v[200:203], v[216:219], v[14:17]
	v_mfma_f32_16x16x32_bf16 v[10:13], v[200:203], v[224:227], v[10:13]
	v_mfma_f32_16x16x32_bf16 v[6:9], v[208:211], v[216:219], v[6:9]
	v_mfma_f32_16x16x32_bf16 v[2:5], v[208:211], v[224:227], v[2:5]
	s_barrier
	v_add_u32_e32 v145, s77, v142
	ds_read_b128 v[148:151], v145
	ds_read_b128 v[152:155], v145 offset:1024
	ds_read_b128 v[156:159], v145 offset:2048
	ds_read_b128 v[160:163], v145 offset:3072
	s_add_u32 s66, s65, 0x80100
	s_addc_u32 s67, s70, 0
	s_mov_b32 m0, s37
	ds_read_b128 v[164:167], v133 offset:32768
	ds_read_b128 v[184:187], v133 offset:33792
	ds_read_b128 v[188:191], v134 offset:32768
	ds_read_b128 v[192:195], v134 offset:33792
	ds_read_b128 v[196:199], v137 offset:32768
	ds_read_b128 v[200:203], v137 offset:33792
	ds_read_b128 v[204:207], v139 offset:32768
	ds_read_b128 v[208:211], v139 offset:33792
	s_nop 0
	v_lshl_add_u64 v[146:147], s[66:67], 0, v[0:1]
	global_load_lds_dwordx4 v[146:147], off
	v_lshl_add_u64 v[146:147], s[66:67], 0, v[140:141]
	s_mov_b32 m0, s38
	s_nop 0
	global_load_lds_dwordx4 v[146:147], off
	s_waitcnt lgkmcnt(8)
	s_barrier
	s_waitcnt lgkmcnt(0)
	s_waitcnt lgkmcnt(0)
	v_mfma_f32_16x16x32_bf16 v[126:129], v[164:167], v[148:151], v[126:129]
	v_mfma_f32_16x16x32_bf16 v[122:125], v[164:167], v[156:159], v[122:125]
	v_mfma_f32_16x16x32_bf16 v[118:121], v[188:191], v[148:151], v[118:121]
	v_mfma_f32_16x16x32_bf16 v[114:117], v[188:191], v[156:159], v[114:117]
	v_mfma_f32_16x16x32_bf16 v[110:113], v[196:199], v[148:151], v[110:113]
	v_mfma_f32_16x16x32_bf16 v[106:109], v[196:199], v[156:159], v[106:109]
	v_mfma_f32_16x16x32_bf16 v[102:105], v[204:207], v[148:151], v[102:105]
	v_mfma_f32_16x16x32_bf16 v[98:101], v[204:207], v[156:159], v[98:101]
	v_mfma_f32_16x16x32_bf16 v[126:129], v[184:187], v[152:155], v[126:129]
	v_mfma_f32_16x16x32_bf16 v[122:125], v[184:187], v[160:163], v[122:125]
	v_mfma_f32_16x16x32_bf16 v[118:121], v[192:195], v[152:155], v[118:121]
	v_mfma_f32_16x16x32_bf16 v[114:117], v[192:195], v[160:163], v[114:117]
	v_mfma_f32_16x16x32_bf16 v[110:113], v[200:203], v[152:155], v[110:113]
	v_mfma_f32_16x16x32_bf16 v[106:109], v[200:203], v[160:163], v[106:109]
	v_mfma_f32_16x16x32_bf16 v[102:105], v[208:211], v[152:155], v[102:105]
	v_mfma_f32_16x16x32_bf16 v[98:101], v[208:211], v[160:163], v[98:101]
	s_barrier
	s_add_u32 s66, s59, 0x180
	v_add_u32_e32 v146, s78, v142
	s_addc_u32 s67, s63, 0
	s_mov_b32 m0, s39
	ds_read_b128 v[212:215], v146
	ds_read_b128 v[216:219], v146 offset:1024
	ds_read_b128 v[220:223], v146 offset:2048
	ds_read_b128 v[224:227], v146 offset:3072
	s_nop 0
	v_lshl_add_u64 v[228:229], s[66:67], 0, v[0:1]
	global_load_lds_dwordx4 v[228:229], off
	v_lshl_add_u64 v[228:229], s[66:67], 0, v[140:141]
	s_mov_b32 m0, s40
	s_nop 0
	global_load_lds_dwordx4 v[228:229], off
	s_barrier
	s_waitcnt lgkmcnt(0)
	s_waitcnt lgkmcnt(0)
	v_mfma_f32_16x16x32_bf16 v[94:97], v[164:167], v[212:215], v[94:97]
	v_mfma_f32_16x16x32_bf16 v[90:93], v[164:167], v[220:223], v[90:93]
	v_mfma_f32_16x16x32_bf16 v[86:89], v[188:191], v[212:215], v[86:89]
	v_mfma_f32_16x16x32_bf16 v[82:85], v[188:191], v[220:223], v[82:85]
	v_mfma_f32_16x16x32_bf16 v[78:81], v[196:199], v[212:215], v[78:81]
	v_mfma_f32_16x16x32_bf16 v[74:77], v[196:199], v[220:223], v[74:77]
	v_mfma_f32_16x16x32_bf16 v[70:73], v[204:207], v[212:215], v[70:73]
	v_mfma_f32_16x16x32_bf16 v[66:69], v[204:207], v[220:223], v[66:69]
	v_mfma_f32_16x16x32_bf16 v[94:97], v[184:187], v[216:219], v[94:97]
	v_mfma_f32_16x16x32_bf16 v[90:93], v[184:187], v[224:227], v[90:93]
	v_mfma_f32_16x16x32_bf16 v[86:89], v[192:195], v[216:219], v[86:89]
	v_mfma_f32_16x16x32_bf16 v[82:85], v[192:195], v[224:227], v[82:85]
	v_mfma_f32_16x16x32_bf16 v[78:81], v[200:203], v[216:219], v[78:81]
	v_mfma_f32_16x16x32_bf16 v[74:77], v[200:203], v[224:227], v[74:77]
	v_mfma_f32_16x16x32_bf16 v[70:73], v[208:211], v[216:219], v[70:73]
	v_mfma_f32_16x16x32_bf16 v[66:69], v[208:211], v[224:227], v[66:69]
	s_barrier
	s_add_u32 s66, s65, 0x180
	s_addc_u32 s67, s70, 0
	s_mov_b32 m0, s41
	ds_read_b128 v[164:167], v133 offset:49152
	ds_read_b128 v[184:187], v133 offset:50176
	ds_read_b128 v[188:191], v134 offset:49152
	ds_read_b128 v[192:195], v134 offset:50176
	ds_read_b128 v[196:199], v137 offset:49152
	ds_read_b128 v[200:203], v137 offset:50176
	ds_read_b128 v[204:207], v139 offset:49152
	ds_read_b128 v[208:211], v139 offset:50176
	s_nop 0
	v_lshl_add_u64 v[228:229], s[66:67], 0, v[0:1]
	global_load_lds_dwordx4 v[228:229], off
	v_lshl_add_u64 v[228:229], s[66:67], 0, v[140:141]
	s_mov_b32 m0, s42
	s_nop 0
	global_load_lds_dwordx4 v[228:229], off
	s_barrier
; #define LDA(dst, b, h) for (int m = 0; m < 4; ++m) for (int k = 0; k < 2; ++k) \
;     dst[m][k] = *reinterpret_cast<const bf16x8*>((char*)SA(b, h) + lds_byte(wr * 64 + m * 16 + fr, k * 32 + fq * 8))
; #define LDB(dst, b, h) for (int n = 0; n < 2; ++n) for (int k = 0; k < 2; ++k) \
;     dst[n][k] = *reinterpret_cast<const bf16x8*>((char*)SB(b, h) + lds_byte(wc * 32 + n * 16 + fr, k * 32 + fq * 8))
; #define MMA(ai, bj, At, Bt_) do { __builtin_amdgcn_s_setprio(1); \
;     for (int m = 0; m < 4; ++m) for (int n = 0; n < 2; ++n) for (int k = 0; k < 2; ++k) \
;       acc[ai][bj][m][n] = __builtin_amdgcn_mfma_f32_16x16x32_bf16(At[m][k], Bt_[n][k], acc[ai][bj][m][n], 0, 0, 0); \
;     __builtin_amdgcn_s_setprio(0); } while (0)
; #define WAIT_V(n) asm volatile("s_waitcnt vmcnt(" #n ")" ::: "memory")
; #define WAIT_L(n) asm volatile("s_waitcnt lgkmcnt(" #n ")" ::: "memory")
; #define BAR __builtin_amdgcn_s_barrier()
; #define SCHED __builtin_amdgcn_sched_barrier(0)
;     ...
;       BAR; WAIT_L(0); MMA(1, 0, At, B0); BAR; SCHED;
;       STAGE(SB(1, 1), Bt, bcol + HALF, t + 3);
;       WAIT_V(6); BAR; MMA(1, 1, At, B1); BAR;
;     }
;     { LDB(B0, 0, 0); LDA(At, 0, 0); STAGE(SA(1, 1), A, brow + HALF, nt - 1);
;       BAR; WAIT_L(0); MMA(0, 0, At, B0); BAR;
;       LDB(B1, 0, 1); BAR; WAIT_L(0); MMA(0, 1, At, B1); BAR;
	s_waitcnt lgkmcnt(0)
	s_waitcnt lgkmcnt(0)
	v_mfma_f32_16x16x32_bf16 v[62:65], v[164:167], v[148:151], v[62:65]
	v_mfma_f32_16x16x32_bf16 v[58:61], v[164:167], v[156:159], v[58:61]
	v_mfma_f32_16x16x32_bf16 v[54:57], v[188:191], v[148:151], v[54:57]
	v_mfma_f32_16x16x32_bf16 v[50:53], v[188:191], v[156:159], v[50:53]
	v_mfma_f32_16x16x32_bf16 v[46:49], v[196:199], v[148:151], v[46:49]
	v_mfma_f32_16x16x32_bf16 v[42:45], v[196:199], v[156:159], v[42:45]
	v_mfma_f32_16x16x32_bf16 v[38:41], v[204:207], v[148:151], v[38:41]
	v_mfma_f32_16x16x32_bf16 v[34:37], v[204:207], v[156:159], v[34:37]
	v_mfma_f32_16x16x32_bf16 v[62:65], v[184:187], v[152:155], v[62:65]
	v_mfma_f32_16x16x32_bf16 v[58:61], v[184:187], v[160:163], v[58:61]
	v_mfma_f32_16x16x32_bf16 v[54:57], v[192:195], v[152:155], v[54:57]
	v_mfma_f32_16x16x32_bf16 v[50:53], v[192:195], v[160:163], v[50:53]
	v_mfma_f32_16x16x32_bf16 v[46:49], v[200:203], v[152:155], v[46:49]
	v_mfma_f32_16x16x32_bf16 v[42:45], v[200:203], v[160:163], v[42:45]
	v_mfma_f32_16x16x32_bf16 v[38:41], v[208:211], v[152:155], v[38:41]
	v_mfma_f32_16x16x32_bf16 v[34:37], v[208:211], v[160:163], v[34:37]
	s_barrier
	s_add_u32 s66, s59, 0x80180
	s_addc_u32 s67, s63, 0
	s_mov_b32 m0, s18
	s_nop 0
	v_lshl_add_u64 v[148:149], s[66:67], 0, v[0:1]
	global_load_lds_dwordx4 v[148:149], off
	v_lshl_add_u64 v[148:149], s[66:67], 0, v[140:141]
	s_mov_b32 m0, s19
	s_nop 0
	global_load_lds_dwordx4 v[148:149], off
	s_add_u32 s11, s11, 0x100
	s_addc_u32 s44, s44, 0
	s_add_u32 s13, s13, 0x100
	s_addc_u32 s45, s45, 0
	s_add_u32 s50, s50, 0x100
	s_addc_u32 s51, s51, 0
	s_cmp_ge_u32 s55, s43
	s_waitcnt vmcnt(6)
	s_barrier
	v_mfma_f32_16x16x32_bf16 v[30:33], v[164:167], v[212:215], v[30:33]
	v_mfma_f32_16x16x32_bf16 v[26:29], v[164:167], v[220:223], v[26:29]
	v_mfma_f32_16x16x32_bf16 v[22:25], v[188:191], v[212:215], v[22:25]
	v_mfma_f32_16x16x32_bf16 v[18:21], v[188:191], v[220:223], v[18:21]
	v_mfma_f32_16x16x32_bf16 v[14:17], v[196:199], v[212:215], v[14:17]
	v_mfma_f32_16x16x32_bf16 v[10:13], v[196:199], v[220:223], v[10:13]
	v_mfma_f32_16x16x32_bf16 v[6:9], v[204:207], v[212:215], v[6:9]
	v_mfma_f32_16x16x32_bf16 v[2:5], v[204:207], v[220:223], v[2:5]
	v_mfma_f32_16x16x32_bf16 v[30:33], v[184:187], v[216:219], v[30:33]
	v_mfma_f32_16x16x32_bf16 v[26:29], v[184:187], v[224:227], v[26:29]
	v_mfma_f32_16x16x32_bf16 v[22:25], v[192:195], v[216:219], v[22:25]
	v_mfma_f32_16x16x32_bf16 v[18:21], v[192:195], v[224:227], v[18:21]
	v_mfma_f32_16x16x32_bf16 v[14:17], v[200:203], v[216:219], v[14:17]
	v_mfma_f32_16x16x32_bf16 v[10:13], v[200:203], v[224:227], v[10:13]
	v_mfma_f32_16x16x32_bf16 v[6:9], v[208:211], v[216:219], v[6:9]
	v_mfma_f32_16x16x32_bf16 v[2:5], v[208:211], v[224:227], v[2:5]
	s_barrier
	s_cbranch_scc0 .LBB0_202
	s_add_i32 s11, s48, s20
	s_add_i32 s48, s11, -1
	s_lshl_b64 s[16:17], s[48:49], 7
	s_add_u32 s11, s74, s16
	s_addc_u32 s13, s75, s17
	s_add_u32 s4, s11, s4
	s_addc_u32 s5, s13, s5
	s_mov_b32 m0, s58
	ds_read_b128 v[148:151], v143
	ds_read_b128 v[152:155], v143 offset:1024
	ds_read_b128 v[156:159], v143 offset:2048
	ds_read_b128 v[160:163], v143 offset:3072
	ds_read_b128 v[164:167], v133
	ds_read_b128 v[184:187], v133 offset:1024
	ds_read_b128 v[188:191], v134
	ds_read_b128 v[192:195], v134 offset:1024
	ds_read_b128 v[196:199], v137
	ds_read_b128 v[200:203], v137 offset:1024
	ds_read_b128 v[204:207], v139
	ds_read_b128 v[208:211], v139 offset:1024
	s_nop 0
	v_lshl_add_u64 v[142:143], s[4:5], 0, v[0:1]
	global_load_lds_dwordx4 v[142:143], off
	v_lshl_add_u64 v[140:141], s[4:5], 0, v[140:141]
	s_mov_b32 m0, s57
	s_nop 0
	global_load_lds_dwordx4 v[140:141], off
	s_barrier
	s_waitcnt lgkmcnt(0)
	s_setprio 1
	s_waitcnt lgkmcnt(0)
	v_mfma_f32_16x16x32_bf16 v[126:129], v[164:167], v[148:151], v[126:129]
	v_mfma_f32_16x16x32_bf16 v[122:125], v[164:167], v[156:159], v[122:125]
	v_mfma_f32_16x16x32_bf16 v[118:121], v[188:191], v[148:151], v[118:121]
	v_mfma_f32_16x16x32_bf16 v[110:113], v[196:199], v[148:151], v[110:113]
	v_mfma_f32_16x16x32_bf16 v[106:109], v[196:199], v[156:159], v[106:109]
	v_mfma_f32_16x16x32_bf16 v[102:105], v[204:207], v[148:151], v[102:105]
	v_mfma_f32_16x16x32_bf16 v[98:101], v[204:207], v[156:159], v[98:101]
	v_mfma_f32_16x16x32_bf16 v[126:129], v[184:187], v[152:155], v[126:129]
	v_mfma_f32_16x16x32_bf16 v[122:125], v[184:187], v[160:163], v[122:125]
	v_mfma_f32_16x16x32_bf16 v[118:121], v[192:195], v[152:155], v[118:121]
	v_mfma_f32_16x16x32_bf16 v[114:117], v[188:191], v[156:159], v[114:117]
	v_mfma_f32_16x16x32_bf16 v[110:113], v[200:203], v[152:155], v[110:113]
	v_mfma_f32_16x16x32_bf16 v[106:109], v[200:203], v[160:163], v[106:109]
	v_mfma_f32_16x16x32_bf16 v[102:105], v[208:211], v[152:155], v[102:105]
	v_mfma_f32_16x16x32_bf16 v[98:101], v[208:211], v[160:163], v[98:101]
	v_mfma_f32_16x16x32_bf16 v[140:143], v[192:195], v[160:163], v[114:117]
	s_setprio 0
	s_barrier
	s_nop 0
	ds_read_b128 v[114:117], v144
	ds_read_b128 v[212:215], v144 offset:1024
	ds_read_b128 v[216:219], v144 offset:2048
	ds_read_b128 v[220:223], v144 offset:3072
	s_barrier
; #define LDA(dst, b, h) for (int m = 0; m < 4; ++m) for (int k = 0; k < 2; ++k) \
;     dst[m][k] = *reinterpret_cast<const bf16x8*>((char*)SA(b, h) + lds_byte(wr * 64 + m * 16 + fr, k * 32 + fq * 8))
; #define LDB(dst, b, h) for (int n = 0; n < 2; ++n) for (int k = 0; k < 2; ++k) \
;     dst[n][k] = *reinterpret_cast<const bf16x8*>((char*)SB(b, h) + lds_byte(wc * 32 + n * 16 + fr, k * 32 + fq * 8))
; #define MMA(ai, bj, At, Bt_) do { __builtin_amdgcn_s_setprio(1); \
;     for (int m = 0; m < 4; ++m) for (int n = 0; n < 2; ++n) for (int k = 0; k < 2; ++k) \
;       acc[ai][bj][m][n] = __builtin_amdgcn_mfma_f32_16x16x32_bf16(At[m][k], Bt_[n][k], acc[ai][bj][m][n], 0, 0, 0); \
;     __builtin_amdgcn_s_setprio(0); } while (0)
; #define WAIT_V(n) asm volatile("s_waitcnt vmcnt(" #n ")" ::: "memory")
; #define WAIT_L(n) asm volatile("s_waitcnt lgkmcnt(" #n ")" ::: "memory")
; #define BAR __builtin_amdgcn_s_barrier()
;     ...
;       LDB(B1, 0, 1); BAR; WAIT_L(0); MMA(0, 1, At, B1); BAR;
;       LDA(At, 0, 1); WAIT_V(4); BAR; WAIT_L(0); MMA(1, 0, At, B0); MMA(1, 1, At, B1); BAR; }
;     { LDB(B0, 1, 0); LDA(At, 1, 0); WAIT_V(2); BAR; WAIT_L(0); MMA(0, 0, At, B0); BAR;
	s_waitcnt lgkmcnt(0)
	s_setprio 1
	s_waitcnt lgkmcnt(0)
	v_mfma_f32_16x16x32_bf16 v[90:93], v[164:167], v[216:219], v[90:93]
	v_mfma_f32_16x16x32_bf16 v[86:89], v[188:191], v[114:117], v[86:89]
	v_mfma_f32_16x16x32_bf16 v[94:97], v[164:167], v[114:117], v[94:97]
	v_mfma_f32_16x16x32_bf16 v[90:93], v[184:187], v[220:223], v[90:93]
	v_mfma_f32_16x16x32_bf16 v[86:89], v[192:195], v[212:215], v[86:89]
	v_mfma_f32_16x16x32_bf16 v[82:85], v[188:191], v[216:219], v[82:85]
	v_mfma_f32_16x16x32_bf16 v[78:81], v[196:199], v[114:117], v[78:81]
	v_mfma_f32_16x16x32_bf16 v[74:77], v[196:199], v[216:219], v[74:77]
	v_mfma_f32_16x16x32_bf16 v[70:73], v[204:207], v[114:117], v[70:73]
	v_mfma_f32_16x16x32_bf16 v[66:69], v[204:207], v[216:219], v[66:69]
	v_mfma_f32_16x16x32_bf16 v[224:227], v[184:187], v[212:215], v[94:97]
	v_mfma_f32_16x16x32_bf16 v[164:167], v[192:195], v[220:223], v[82:85]
	v_mfma_f32_16x16x32_bf16 v[184:187], v[200:203], v[212:215], v[78:81]
	v_mfma_f32_16x16x32_bf16 v[188:191], v[200:203], v[220:223], v[74:77]
	v_mfma_f32_16x16x32_bf16 v[192:195], v[208:211], v[212:215], v[70:73]
	v_mfma_f32_16x16x32_bf16 v[196:199], v[208:211], v[220:223], v[66:69]
	s_setprio 0
	s_barrier
	s_nop 0
	ds_read_b128 v[66:69], v133 offset:16384
	ds_read_b128 v[70:73], v133 offset:17408
	ds_read_b128 v[74:77], v134 offset:16384
	ds_read_b128 v[78:81], v134 offset:17408
	ds_read_b128 v[82:85], v137 offset:16384
	ds_read_b128 v[94:97], v137 offset:17408
	ds_read_b128 v[200:203], v139 offset:16384
	ds_read_b128 v[204:207], v139 offset:17408
	s_waitcnt vmcnt(4)
	s_barrier
	s_waitcnt lgkmcnt(0)
	s_setprio 1
	s_waitcnt lgkmcnt(0)
	v_mfma_f32_16x16x32_bf16 v[62:65], v[66:69], v[148:151], v[62:65]
	v_mfma_f32_16x16x32_bf16 v[58:61], v[66:69], v[156:159], v[58:61]
	v_mfma_f32_16x16x32_bf16 v[54:57], v[74:77], v[148:151], v[54:57]
	v_mfma_f32_16x16x32_bf16 v[50:53], v[74:77], v[156:159], v[50:53]
	v_mfma_f32_16x16x32_bf16 v[46:49], v[82:85], v[148:151], v[46:49]
	v_mfma_f32_16x16x32_bf16 v[42:45], v[82:85], v[156:159], v[42:45]
	v_mfma_f32_16x16x32_bf16 v[38:41], v[200:203], v[148:151], v[38:41]
	v_mfma_f32_16x16x32_bf16 v[34:37], v[200:203], v[156:159], v[34:37]
	v_mfma_f32_16x16x32_bf16 v[62:65], v[70:73], v[152:155], v[62:65]
	v_mfma_f32_16x16x32_bf16 v[58:61], v[70:73], v[160:163], v[58:61]
	v_mfma_f32_16x16x32_bf16 v[54:57], v[78:81], v[152:155], v[54:57]
	v_mfma_f32_16x16x32_bf16 v[50:53], v[78:81], v[160:163], v[50:53]
	v_mfma_f32_16x16x32_bf16 v[46:49], v[94:97], v[152:155], v[46:49]
	v_mfma_f32_16x16x32_bf16 v[42:45], v[94:97], v[160:163], v[42:45]
	v_mfma_f32_16x16x32_bf16 v[38:41], v[204:207], v[152:155], v[38:41]
	v_mfma_f32_16x16x32_bf16 v[34:37], v[204:207], v[160:163], v[34:37]
	s_setprio 0
	s_setprio 1
	v_mfma_f32_16x16x32_bf16 v[30:33], v[66:69], v[114:117], v[30:33]
	v_mfma_f32_16x16x32_bf16 v[26:29], v[66:69], v[216:219], v[26:29]
	v_mfma_f32_16x16x32_bf16 v[22:25], v[74:77], v[114:117], v[22:25]
	v_mfma_f32_16x16x32_bf16 v[18:21], v[74:77], v[216:219], v[18:21]
	v_mfma_f32_16x16x32_bf16 v[14:17], v[82:85], v[114:117], v[14:17]
	v_mfma_f32_16x16x32_bf16 v[10:13], v[82:85], v[216:219], v[10:13]
	v_mfma_f32_16x16x32_bf16 v[6:9], v[200:203], v[114:117], v[6:9]
	v_mfma_f32_16x16x32_bf16 v[2:5], v[200:203], v[216:219], v[2:5]
	v_mfma_f32_16x16x32_bf16 v[148:151], v[70:73], v[212:215], v[30:33]
	v_mfma_f32_16x16x32_bf16 v[152:155], v[70:73], v[220:223], v[26:29]
	v_mfma_f32_16x16x32_bf16 v[156:159], v[78:81], v[212:215], v[22:25]
	v_mfma_f32_16x16x32_bf16 v[160:163], v[78:81], v[220:223], v[18:21]
	v_mfma_f32_16x16x32_bf16 v[208:211], v[94:97], v[212:215], v[14:17]
	v_mfma_f32_16x16x32_bf16 v[228:231], v[94:97], v[220:223], v[10:13]
	v_mfma_f32_16x16x32_bf16 v[212:215], v[204:207], v[212:215], v[6:9]
	v_mfma_f32_16x16x32_bf16 v[200:203], v[204:207], v[220:223], v[2:5]
	s_setprio 0
	s_barrier
	ds_read_b128 v[14:17], v145
	ds_read_b128 v[30:33], v145 offset:1024
	ds_read_b128 v[204:207], v145 offset:2048
	ds_read_b128 v[216:219], v145 offset:3072
	ds_read_b128 v[2:5], v133 offset:32768
	ds_read_b128 v[6:9], v133 offset:33792
	ds_read_b128 v[10:13], v134 offset:32768
	ds_read_b128 v[18:21], v134 offset:33792
	ds_read_b128 v[22:25], v137 offset:32768
	ds_read_b128 v[26:29], v137 offset:33792
	ds_read_b128 v[220:223], v139 offset:32768
	ds_read_b128 v[232:235], v139 offset:33792
	s_waitcnt vmcnt(2)
	s_barrier
; #define LDA(dst, b, h) for (int m = 0; m < 4; ++m) for (int k = 0; k < 2; ++k) \
;     dst[m][k] = *reinterpret_cast<const bf16x8*>((char*)SA(b, h) + lds_byte(wr * 64 + m * 16 + fr, k * 32 + fq * 8))
; #define LDB(dst, b, h) for (int n = 0; n < 2; ++n) for (int k = 0; k < 2; ++k) \
;     dst[n][k] = *reinterpret_cast<const bf16x8*>((char*)SB(b, h) + lds_byte(wc * 32 + n * 16 + fr, k * 32 + fq * 8))
; #define MMA(ai, bj, At, Bt_) do { __builtin_amdgcn_s_setprio(1); \
;     for (int m = 0; m < 4; ++m) for (int n = 0; n < 2; ++n) for (int k = 0; k < 2; ++k) \
;       acc[ai][bj][m][n] = __builtin_amdgcn_mfma_f32_16x16x32_bf16(At[m][k], Bt_[n][k], acc[ai][bj][m][n], 0, 0, 0); \
;     __builtin_amdgcn_s_setprio(0); } while (0)
; #define WAIT_V(n) asm volatile("s_waitcnt vmcnt(" #n ")" ::: "memory")
; #define WAIT_L(n) asm volatile("s_waitcnt lgkmcnt(" #n ")" ::: "memory")
; #define BAR __builtin_amdgcn_s_barrier()
;     ...
;     { LDB(B0, 1, 0); LDA(At, 1, 0); WAIT_V(2); BAR; WAIT_L(0); MMA(0, 0, At, B0); BAR;
;       LDB(B1, 1, 1); WAIT_V(0); BAR; WAIT_L(0); MMA(0, 1, At, B1); BAR;
;       LDA(At, 1, 1); BAR; WAIT_L(0); MMA(1, 0, At, B0); MMA(1, 1, At, B1); BAR; }
;     if (wr == 0) BAR;
	s_waitcnt lgkmcnt(0)
	s_setprio 1
	s_waitcnt lgkmcnt(0)
	v_mfma_f32_16x16x32_bf16 v[66:69], v[2:5], v[14:17], v[126:129]
	v_mfma_f32_16x16x32_bf16 v[114:117], v[6:9], v[30:33], v[66:69]
	v_mfma_f32_16x16x32_bf16 v[66:69], v[2:5], v[204:207], v[122:125]
	v_mfma_f32_16x16x32_bf16 v[126:129], v[6:9], v[216:219], v[66:69]
	v_mfma_f32_16x16x32_bf16 v[66:69], v[10:13], v[14:17], v[118:121]
	v_mfma_f32_16x16x32_bf16 v[82:85], v[18:21], v[30:33], v[66:69]
	v_mfma_f32_16x16x32_bf16 v[66:69], v[10:13], v[204:207], v[140:143]
	v_mfma_f32_16x16x32_bf16 v[94:97], v[18:21], v[216:219], v[66:69]
	v_mfma_f32_16x16x32_bf16 v[66:69], v[22:25], v[14:17], v[110:113]
	v_mfma_f32_16x16x32_bf16 v[74:77], v[26:29], v[30:33], v[66:69]
	v_mfma_f32_16x16x32_bf16 v[66:69], v[22:25], v[204:207], v[106:109]
	v_mfma_f32_16x16x32_bf16 v[78:81], v[26:29], v[216:219], v[66:69]
	v_mfma_f32_16x16x32_bf16 v[66:69], v[220:223], v[14:17], v[102:105]
	v_mfma_f32_16x16x32_bf16 v[70:73], v[220:223], v[204:207], v[98:101]
	v_mfma_f32_16x16x32_bf16 v[66:69], v[232:235], v[30:33], v[66:69]
	v_mfma_f32_16x16x32_bf16 v[70:73], v[232:235], v[216:219], v[70:73]
	s_setprio 0
	s_barrier
	ds_read_b128 v[140:143], v146
	ds_read_b128 v[236:239], v146 offset:1024
	ds_read_b128 v[240:243], v146 offset:2048
	ds_read_b128 v[144:147], v146 offset:3072
	s_waitcnt vmcnt(0)
	s_barrier
	s_waitcnt lgkmcnt(0)
	s_setprio 1
	s_waitcnt lgkmcnt(0)
	v_mfma_f32_16x16x32_bf16 v[98:101], v[2:5], v[140:143], v[224:227]
	v_mfma_f32_16x16x32_bf16 v[2:5], v[2:5], v[240:243], v[90:93]
	v_mfma_f32_16x16x32_bf16 v[118:121], v[6:9], v[144:147], v[2:5]
	v_mfma_f32_16x16x32_bf16 v[2:5], v[10:13], v[140:143], v[86:89]
	v_mfma_f32_16x16x32_bf16 v[102:105], v[18:21], v[236:239], v[2:5]
	v_mfma_f32_16x16x32_bf16 v[2:5], v[10:13], v[240:243], v[164:167]
	v_mfma_f32_16x16x32_bf16 v[122:125], v[18:21], v[144:147], v[2:5]
	v_mfma_f32_16x16x32_bf16 v[2:5], v[22:25], v[140:143], v[184:187]
	v_mfma_f32_16x16x32_bf16 v[90:93], v[26:29], v[236:239], v[2:5]
	v_mfma_f32_16x16x32_bf16 v[2:5], v[22:25], v[240:243], v[188:191]
	v_mfma_f32_16x16x32_bf16 v[110:113], v[26:29], v[144:147], v[2:5]
	v_mfma_f32_16x16x32_bf16 v[2:5], v[220:223], v[140:143], v[192:195]
	v_mfma_f32_16x16x32_bf16 v[86:89], v[232:235], v[236:239], v[2:5]
	v_mfma_f32_16x16x32_bf16 v[2:5], v[220:223], v[240:243], v[196:199]
	v_mfma_f32_16x16x32_bf16 v[98:101], v[6:9], v[236:239], v[98:101]
	v_mfma_f32_16x16x32_bf16 v[106:109], v[232:235], v[144:147], v[2:5]
	s_setprio 0
	s_barrier
	ds_read_b128 v[164:167], v133 offset:49152
	ds_read_b128 v[184:187], v133 offset:50176
	ds_read_b128 v[188:191], v134 offset:49152
	ds_read_b128 v[192:195], v134 offset:50176
	ds_read_b128 v[196:199], v137 offset:49152
	ds_read_b128 v[220:223], v137 offset:50176
	ds_read_b128 v[224:227], v139 offset:49152
	ds_read_b128 v[232:235], v139 offset:50176
	s_barrier
	s_waitcnt lgkmcnt(0)
	s_setprio 1
	s_waitcnt lgkmcnt(0)
	v_mfma_f32_16x16x32_bf16 v[6:9], v[164:167], v[204:207], v[58:61]
	v_mfma_f32_16x16x32_bf16 v[10:13], v[188:191], v[204:207], v[50:53]
	v_mfma_f32_16x16x32_bf16 v[2:5], v[164:167], v[14:17], v[62:65]
	v_mfma_f32_16x16x32_bf16 v[18:21], v[184:187], v[216:219], v[6:9]
	v_mfma_f32_16x16x32_bf16 v[6:9], v[188:191], v[14:17], v[54:57]
	v_mfma_f32_16x16x32_bf16 v[22:25], v[192:195], v[216:219], v[10:13]
	v_mfma_f32_16x16x32_bf16 v[10:13], v[196:199], v[14:17], v[46:49]
	v_mfma_f32_16x16x32_bf16 v[14:17], v[224:227], v[14:17], v[38:41]
	v_mfma_f32_16x16x32_bf16 v[2:5], v[184:187], v[30:33], v[2:5]
	v_mfma_f32_16x16x32_bf16 v[6:9], v[192:195], v[30:33], v[6:9]
	v_mfma_f32_16x16x32_bf16 v[10:13], v[220:223], v[30:33], v[10:13]
	v_mfma_f32_16x16x32_bf16 v[26:29], v[196:199], v[204:207], v[42:45]
	v_mfma_f32_16x16x32_bf16 v[14:17], v[232:235], v[30:33], v[14:17]
	v_mfma_f32_16x16x32_bf16 v[30:33], v[224:227], v[204:207], v[34:37]
	v_mfma_f32_16x16x32_bf16 v[26:29], v[220:223], v[216:219], v[26:29]
	v_mfma_f32_16x16x32_bf16 v[30:33], v[232:235], v[216:219], v[30:33]
	s_setprio 0
	s_setprio 1
	v_mfma_f32_16x16x32_bf16 v[38:41], v[164:167], v[240:243], v[152:155]
	v_mfma_f32_16x16x32_bf16 v[42:45], v[188:191], v[240:243], v[160:163]
	v_mfma_f32_16x16x32_bf16 v[46:49], v[196:199], v[240:243], v[228:231]
	v_mfma_f32_16x16x32_bf16 v[34:37], v[164:167], v[140:143], v[148:151]
	v_mfma_f32_16x16x32_bf16 v[50:53], v[184:187], v[144:147], v[38:41]
	v_mfma_f32_16x16x32_bf16 v[38:41], v[188:191], v[140:143], v[156:159]
	v_mfma_f32_16x16x32_bf16 v[54:57], v[192:195], v[144:147], v[42:45]
	v_mfma_f32_16x16x32_bf16 v[42:45], v[196:199], v[140:143], v[208:211]
	v_mfma_f32_16x16x32_bf16 v[58:61], v[220:223], v[144:147], v[46:49]
	v_mfma_f32_16x16x32_bf16 v[46:49], v[224:227], v[140:143], v[212:215]
	v_mfma_f32_16x16x32_bf16 v[62:65], v[224:227], v[240:243], v[200:203]
	v_mfma_f32_16x16x32_bf16 v[34:37], v[184:187], v[236:239], v[34:37]
	v_mfma_f32_16x16x32_bf16 v[38:41], v[192:195], v[236:239], v[38:41]
	v_mfma_f32_16x16x32_bf16 v[42:45], v[220:223], v[236:239], v[42:45]
	v_mfma_f32_16x16x32_bf16 v[46:49], v[232:235], v[236:239], v[46:49]
	v_mfma_f32_16x16x32_bf16 v[62:65], v[232:235], v[144:147], v[62:65]
	s_setprio 0
	v_readlane_b32 s4, v245, 33
	v_readlane_b32 s5, v245, 34
	s_and_b64 vcc, exec, s[4:5]
	s_barrier
	s_cbranch_vccz .LBB0_205
	s_barrier

; #define LDA(dst, b, h) for (int m = 0; m < 4; ++m) for (int k = 0; k < 2; ++k) \
;     dst[m][k] = *reinterpret_cast<const bf16x8*>((char*)SA(b, h) + lds_byte(wr * 64 + m * 16 + fr, k * 32 + fq * 8))
; #define LDB(dst, b, h) for (int n = 0; n < 2; ++n) for (int k = 0; k < 2; ++k) \
;     dst[n][k] = *reinterpret_cast<const bf16x8*>((char*)SB(b, h) + lds_byte(wc * 32 + n * 16 + fr, k * 32 + fq * 8))
; #define MMA(ai, bj, At, Bt_) do { __builtin_amdgcn_s_setprio(1); \
;     for (int m = 0; m < 4; ++m) for (int n = 0; n < 2; ++n) for (int k = 0; k < 2; ++k) \
;       acc[ai][bj][m][n] = __builtin_amdgcn_mfma_f32_16x16x32_bf16(At[m][k], Bt_[n][k], acc[ai][bj][m][n], 0, 0, 0); \
;     __builtin_amdgcn_s_setprio(0); } while (0)
; #define WAIT_V(n) asm volatile("s_waitcnt vmcnt(" #n ")" ::: "memory")
; #define WAIT_L(n) asm volatile("s_waitcnt lgkmcnt(" #n ")" ::: "memory")
; #define BAR __builtin_amdgcn_s_barrier()
; #define SCHED __builtin_amdgcn_sched_barrier(0)
;     ...
;     for (int t = 0; t < nt - 2; t += 2) {
;       LDB(B0, 0, 0); SCHED; LDA(At, 0, 0); STAGE(SA(1, 1), A, brow + HALF, t + 1);
;       WAIT_L(8); BAR; WAIT_L(0); MMA(0, 0, At, B0); BAR; SCHED;
;       LDB(B1, 0, 1); STAGE(SB(0, 0), Bt, bcol, t + 2);
;       BAR; WAIT_L(0); MMA(0, 1, At, B1); BAR;
;       LDA(At, 0, 1); STAGE(SA(0, 0), A, brow, t + 2);
;       BAR; WAIT_L(0); MMA(1, 0, At, B0); BAR; SCHED;
;       STAGE(SB(0, 1), Bt, bcol + HALF, t + 2);
;       WAIT_V(6); BAR; MMA(1, 1, At, B1); BAR;
.LBB0_418:
	v_add_u32_e32 v143, s2, v142
	ds_read_b128 v[146:149], v143
	ds_read_b128 v[150:153], v143 offset:1024
	ds_read_b128 v[154:157], v143 offset:2048
	ds_read_b128 v[158:161], v143 offset:3072
	s_add_u32 s42, s30, s6
	s_addc_u32 s43, s31, s7
	s_add_u32 s44, s42, 0x80080
	s_addc_u32 s45, s43, 0
	s_add_i32 s41, s15, 0xc000
	ds_read_b128 v[162:165], v133
	ds_read_b128 v[184:187], v133 offset:1024
	ds_read_b128 v[188:191], v134
	ds_read_b128 v[192:195], v134 offset:1024
	ds_read_b128 v[196:199], v137
	ds_read_b128 v[200:203], v137 offset:1024
	ds_read_b128 v[204:207], v139
	ds_read_b128 v[208:211], v139 offset:1024
	s_mov_b32 m0, s41
	v_lshl_add_u64 v[144:145], s[44:45], 0, v[0:1]
	s_add_i32 s37, s15, 0xe000
	global_load_lds_dwordx4 v[144:145], off
	v_lshl_add_u64 v[144:145], s[44:45], 0, v[140:141]
	s_mov_b32 m0, s37
	s_nop 0
	global_load_lds_dwordx4 v[144:145], off
	s_waitcnt lgkmcnt(8)
	s_barrier
	s_waitcnt lgkmcnt(0)
	s_waitcnt lgkmcnt(0)
	v_mfma_f32_16x16x32_bf16 v[126:129], v[162:165], v[146:149], v[126:129]
	v_mfma_f32_16x16x32_bf16 v[122:125], v[162:165], v[154:157], v[122:125]
	v_mfma_f32_16x16x32_bf16 v[118:121], v[188:191], v[146:149], v[118:121]
	v_mfma_f32_16x16x32_bf16 v[114:117], v[188:191], v[154:157], v[114:117]
	v_mfma_f32_16x16x32_bf16 v[110:113], v[196:199], v[146:149], v[110:113]
	v_mfma_f32_16x16x32_bf16 v[106:109], v[196:199], v[154:157], v[106:109]
	v_mfma_f32_16x16x32_bf16 v[102:105], v[204:207], v[146:149], v[102:105]
	v_mfma_f32_16x16x32_bf16 v[98:101], v[204:207], v[154:157], v[98:101]
	v_mfma_f32_16x16x32_bf16 v[126:129], v[184:187], v[150:153], v[126:129]
	v_mfma_f32_16x16x32_bf16 v[122:125], v[184:187], v[158:161], v[122:125]
	v_mfma_f32_16x16x32_bf16 v[118:121], v[192:195], v[150:153], v[118:121]
	v_mfma_f32_16x16x32_bf16 v[114:117], v[192:195], v[158:161], v[114:117]
	v_mfma_f32_16x16x32_bf16 v[110:113], v[200:203], v[150:153], v[110:113]
	v_mfma_f32_16x16x32_bf16 v[106:109], v[200:203], v[158:161], v[106:109]
	v_mfma_f32_16x16x32_bf16 v[102:105], v[208:211], v[150:153], v[102:105]
	v_mfma_f32_16x16x32_bf16 v[98:101], v[208:211], v[158:161], v[98:101]
	s_barrier
	s_add_u32 s44, s34, s6
	s_addc_u32 s45, s35, s7
	s_add_u32 s50, s44, 0x100
	v_add_u32_e32 v144, s76, v142
	s_addc_u32 s51, s45, 0
	s_mov_b32 m0, s23
	ds_read_b128 v[212:215], v144
	ds_read_b128 v[216:219], v144 offset:1024
	ds_read_b128 v[220:223], v144 offset:2048
	ds_read_b128 v[224:227], v144 offset:3072
	s_nop 0
	v_lshl_add_u64 v[166:167], s[50:51], 0, v[0:1]
	global_load_lds_dwordx4 v[166:167], off
	v_lshl_add_u64 v[166:167], s[50:51], 0, v[140:141]
	s_mov_b32 m0, s26
	s_nop 0
	global_load_lds_dwordx4 v[166:167], off
	s_barrier
	s_waitcnt lgkmcnt(0)
	s_waitcnt lgkmcnt(0)
	v_mfma_f32_16x16x32_bf16 v[94:97], v[162:165], v[212:215], v[94:97]
	v_mfma_f32_16x16x32_bf16 v[90:93], v[162:165], v[220:223], v[90:93]
	v_mfma_f32_16x16x32_bf16 v[86:89], v[188:191], v[212:215], v[86:89]
	v_mfma_f32_16x16x32_bf16 v[82:85], v[188:191], v[220:223], v[82:85]
	v_mfma_f32_16x16x32_bf16 v[78:81], v[196:199], v[212:215], v[78:81]
	v_mfma_f32_16x16x32_bf16 v[74:77], v[196:199], v[220:223], v[74:77]
	v_mfma_f32_16x16x32_bf16 v[70:73], v[204:207], v[212:215], v[70:73]
	v_mfma_f32_16x16x32_bf16 v[66:69], v[204:207], v[220:223], v[66:69]
	v_mfma_f32_16x16x32_bf16 v[94:97], v[184:187], v[216:219], v[94:97]
	v_mfma_f32_16x16x32_bf16 v[90:93], v[184:187], v[224:227], v[90:93]
	v_mfma_f32_16x16x32_bf16 v[86:89], v[192:195], v[216:219], v[86:89]
	v_mfma_f32_16x16x32_bf16 v[82:85], v[192:195], v[224:227], v[82:85]
	v_mfma_f32_16x16x32_bf16 v[78:81], v[200:203], v[216:219], v[78:81]
	v_mfma_f32_16x16x32_bf16 v[74:77], v[200:203], v[224:227], v[74:77]
	v_mfma_f32_16x16x32_bf16 v[70:73], v[208:211], v[216:219], v[70:73]
	v_mfma_f32_16x16x32_bf16 v[66:69], v[208:211], v[224:227], v[66:69]
	s_barrier
	s_add_u32 s50, s42, 0x100
	s_addc_u32 s51, s43, 0
	s_mov_b32 m0, s15
	ds_read_b128 v[162:165], v133 offset:16384
	ds_read_b128 v[184:187], v133 offset:17408
	ds_read_b128 v[188:191], v134 offset:16384
	ds_read_b128 v[192:195], v134 offset:17408
	ds_read_b128 v[196:199], v137 offset:16384
	ds_read_b128 v[200:203], v137 offset:17408
	ds_read_b128 v[204:207], v139 offset:16384
	ds_read_b128 v[208:211], v139 offset:17408
	s_nop 0
	v_lshl_add_u64 v[166:167], s[50:51], 0, v[0:1]
	global_load_lds_dwordx4 v[166:167], off
	v_lshl_add_u64 v[166:167], s[50:51], 0, v[140:141]
	s_mov_b32 m0, s25
	s_nop 0
	global_load_lds_dwordx4 v[166:167], off
	s_barrier
	s_waitcnt lgkmcnt(0)
	s_waitcnt lgkmcnt(0)
	v_mfma_f32_16x16x32_bf16 v[62:65], v[162:165], v[146:149], v[62:65]
	v_mfma_f32_16x16x32_bf16 v[58:61], v[162:165], v[154:157], v[58:61]
	v_mfma_f32_16x16x32_bf16 v[54:57], v[188:191], v[146:149], v[54:57]
	v_mfma_f32_16x16x32_bf16 v[50:53], v[188:191], v[154:157], v[50:53]
	v_mfma_f32_16x16x32_bf16 v[46:49], v[196:199], v[146:149], v[46:49]
	v_mfma_f32_16x16x32_bf16 v[42:45], v[196:199], v[154:157], v[42:45]
	v_mfma_f32_16x16x32_bf16 v[38:41], v[204:207], v[146:149], v[38:41]
	v_mfma_f32_16x16x32_bf16 v[34:37], v[204:207], v[154:157], v[34:37]
	v_mfma_f32_16x16x32_bf16 v[62:65], v[184:187], v[150:153], v[62:65]
	v_mfma_f32_16x16x32_bf16 v[58:61], v[184:187], v[158:161], v[58:61]
	v_mfma_f32_16x16x32_bf16 v[54:57], v[192:195], v[150:153], v[54:57]
	v_mfma_f32_16x16x32_bf16 v[50:53], v[192:195], v[158:161], v[50:53]
	v_mfma_f32_16x16x32_bf16 v[46:49], v[200:203], v[150:153], v[46:49]
	v_mfma_f32_16x16x32_bf16 v[42:45], v[200:203], v[158:161], v[42:45]
	v_mfma_f32_16x16x32_bf16 v[38:41], v[208:211], v[150:153], v[38:41]
	v_mfma_f32_16x16x32_bf16 v[34:37], v[208:211], v[158:161], v[34:37]
	s_barrier
; #define LDA(dst, b, h) for (int m = 0; m < 4; ++m) for (int k = 0; k < 2; ++k) \
;     dst[m][k] = *reinterpret_cast<const bf16x8*>((char*)SA(b, h) + lds_byte(wr * 64 + m * 16 + fr, k * 32 + fq * 8))
; #define LDB(dst, b, h) for (int n = 0; n < 2; ++n) for (int k = 0; k < 2; ++k) \
;     dst[n][k] = *reinterpret_cast<const bf16x8*>((char*)SB(b, h) + lds_byte(wc * 32 + n * 16 + fr, k * 32 + fq * 8))
; #define MMA(ai, bj, At, Bt_) do { __builtin_amdgcn_s_setprio(1); \
;     for (int m = 0; m < 4; ++m) for (int n = 0; n < 2; ++n) for (int k = 0; k < 2; ++k) \
;       acc[ai][bj][m][n] = __builtin_amdgcn_mfma_f32_16x16x32_bf16(At[m][k], Bt_[n][k], acc[ai][bj][m][n], 0, 0, 0); \
;     __builtin_amdgcn_s_setprio(0); } while (0)
; #define WAIT_V(n) asm volatile("s_waitcnt vmcnt(" #n ")" ::: "memory")
; #define WAIT_L(n) asm volatile("s_waitcnt lgkmcnt(" #n ")" ::: "memory")
; #define BAR __builtin_amdgcn_s_barrier()
; #define SCHED __builtin_amdgcn_sched_barrier(0)
;     ...
;       WAIT_V(6); BAR; MMA(1, 1, At, B1); BAR;
;       LDB(B0, 1, 0); SCHED; LDA(At, 1, 0); STAGE(SA(0, 1), A, brow + HALF, t + 2);
;       WAIT_L(8); BAR; WAIT_L(0); MMA(0, 0, At, B0); BAR; SCHED;
;       LDB(B1, 1, 1); STAGE(SB(1, 0), Bt, bcol, t + 3);
;       BAR; WAIT_L(0); MMA(0, 1, At, B1); BAR;
;       LDA(At, 1, 1); STAGE(SA(1, 0), A, brow, t + 3);
;       BAR; WAIT_L(0); MMA(1, 0, At, B0); BAR; SCHED;
	s_add_u32 s50, s44, 0x80100
	s_addc_u32 s51, s45, 0
	s_mov_b32 m0, s27
	s_nop 0
	v_lshl_add_u64 v[146:147], s[50:51], 0, v[0:1]
	global_load_lds_dwordx4 v[146:147], off
	v_lshl_add_u64 v[146:147], s[50:51], 0, v[140:141]
	s_mov_b32 m0, s28
	s_nop 0
	global_load_lds_dwordx4 v[146:147], off
	s_waitcnt vmcnt(6)
	s_barrier
	v_mfma_f32_16x16x32_bf16 v[30:33], v[162:165], v[212:215], v[30:33]
	v_mfma_f32_16x16x32_bf16 v[26:29], v[162:165], v[220:223], v[26:29]
	v_mfma_f32_16x16x32_bf16 v[22:25], v[188:191], v[212:215], v[22:25]
	v_mfma_f32_16x16x32_bf16 v[18:21], v[188:191], v[220:223], v[18:21]
	v_mfma_f32_16x16x32_bf16 v[14:17], v[196:199], v[212:215], v[14:17]
	v_mfma_f32_16x16x32_bf16 v[10:13], v[196:199], v[220:223], v[10:13]
	v_mfma_f32_16x16x32_bf16 v[6:9], v[204:207], v[212:215], v[6:9]
	v_mfma_f32_16x16x32_bf16 v[2:5], v[204:207], v[220:223], v[2:5]
	v_mfma_f32_16x16x32_bf16 v[30:33], v[184:187], v[216:219], v[30:33]
	v_mfma_f32_16x16x32_bf16 v[26:29], v[184:187], v[224:227], v[26:29]
	v_mfma_f32_16x16x32_bf16 v[22:25], v[192:195], v[216:219], v[22:25]
	v_mfma_f32_16x16x32_bf16 v[18:21], v[192:195], v[224:227], v[18:21]
	v_mfma_f32_16x16x32_bf16 v[14:17], v[200:203], v[216:219], v[14:17]
	v_mfma_f32_16x16x32_bf16 v[10:13], v[200:203], v[224:227], v[10:13]
	v_mfma_f32_16x16x32_bf16 v[6:9], v[208:211], v[216:219], v[6:9]
	v_mfma_f32_16x16x32_bf16 v[2:5], v[208:211], v[224:227], v[2:5]
	s_barrier
	v_add_u32_e32 v145, s77, v142
	ds_read_b128 v[148:151], v145
	ds_read_b128 v[152:155], v145 offset:1024
	ds_read_b128 v[156:159], v145 offset:2048
	ds_read_b128 v[160:163], v145 offset:3072
	s_add_u32 s50, s42, 0x80100
	s_addc_u32 s51, s43, 0
	s_mov_b32 m0, s17
	ds_read_b128 v[164:167], v133 offset:32768
	ds_read_b128 v[184:187], v133 offset:33792
	ds_read_b128 v[188:191], v134 offset:32768
	ds_read_b128 v[192:195], v134 offset:33792
	ds_read_b128 v[196:199], v137 offset:32768
	ds_read_b128 v[200:203], v137 offset:33792
	ds_read_b128 v[204:207], v139 offset:32768
	ds_read_b128 v[208:211], v139 offset:33792
	s_nop 0
	v_lshl_add_u64 v[146:147], s[50:51], 0, v[0:1]
	global_load_lds_dwordx4 v[146:147], off
	v_lshl_add_u64 v[146:147], s[50:51], 0, v[140:141]
	s_mov_b32 m0, s29
	s_nop 0
	global_load_lds_dwordx4 v[146:147], off
	s_waitcnt lgkmcnt(8)
	s_barrier
	s_waitcnt lgkmcnt(0)
	s_waitcnt lgkmcnt(0)
	v_mfma_f32_16x16x32_bf16 v[126:129], v[164:167], v[148:151], v[126:129]
	v_mfma_f32_16x16x32_bf16 v[122:125], v[164:167], v[156:159], v[122:125]
	v_mfma_f32_16x16x32_bf16 v[118:121], v[188:191], v[148:151], v[118:121]
	v_mfma_f32_16x16x32_bf16 v[114:117], v[188:191], v[156:159], v[114:117]
	v_mfma_f32_16x16x32_bf16 v[110:113], v[196:199], v[148:151], v[110:113]
	v_mfma_f32_16x16x32_bf16 v[106:109], v[196:199], v[156:159], v[106:109]
	v_mfma_f32_16x16x32_bf16 v[102:105], v[204:207], v[148:151], v[102:105]
	v_mfma_f32_16x16x32_bf16 v[98:101], v[204:207], v[156:159], v[98:101]
	v_mfma_f32_16x16x32_bf16 v[126:129], v[184:187], v[152:155], v[126:129]
	v_mfma_f32_16x16x32_bf16 v[122:125], v[184:187], v[160:163], v[122:125]
	v_mfma_f32_16x16x32_bf16 v[118:121], v[192:195], v[152:155], v[118:121]
	v_mfma_f32_16x16x32_bf16 v[114:117], v[192:195], v[160:163], v[114:117]
	v_mfma_f32_16x16x32_bf16 v[110:113], v[200:203], v[152:155], v[110:113]
	v_mfma_f32_16x16x32_bf16 v[106:109], v[200:203], v[160:163], v[106:109]
	v_mfma_f32_16x16x32_bf16 v[102:105], v[208:211], v[152:155], v[102:105]
	v_mfma_f32_16x16x32_bf16 v[98:101], v[208:211], v[160:163], v[98:101]
	s_barrier
	s_add_u32 s50, s44, 0x180
	v_add_u32_e32 v146, s78, v142
	s_addc_u32 s51, s45, 0
	s_mov_b32 m0, s8
	ds_read_b128 v[212:215], v146
	ds_read_b128 v[216:219], v146 offset:1024
	ds_read_b128 v[220:223], v146 offset:2048
	ds_read_b128 v[224:227], v146 offset:3072
	s_nop 0
	v_lshl_add_u64 v[228:229], s[50:51], 0, v[0:1]
	global_load_lds_dwordx4 v[228:229], off
	v_lshl_add_u64 v[228:229], s[50:51], 0, v[140:141]
	s_mov_b32 m0, s9
	s_nop 0
	global_load_lds_dwordx4 v[228:229], off
	s_barrier
	s_waitcnt lgkmcnt(0)
	s_waitcnt lgkmcnt(0)
	v_mfma_f32_16x16x32_bf16 v[94:97], v[164:167], v[212:215], v[94:97]
	v_mfma_f32_16x16x32_bf16 v[90:93], v[164:167], v[220:223], v[90:93]
	v_mfma_f32_16x16x32_bf16 v[86:89], v[188:191], v[212:215], v[86:89]
	v_mfma_f32_16x16x32_bf16 v[82:85], v[188:191], v[220:223], v[82:85]
	v_mfma_f32_16x16x32_bf16 v[78:81], v[196:199], v[212:215], v[78:81]
	v_mfma_f32_16x16x32_bf16 v[74:77], v[196:199], v[220:223], v[74:77]
	v_mfma_f32_16x16x32_bf16 v[70:73], v[204:207], v[212:215], v[70:73]
	v_mfma_f32_16x16x32_bf16 v[66:69], v[204:207], v[220:223], v[66:69]
	v_mfma_f32_16x16x32_bf16 v[94:97], v[184:187], v[216:219], v[94:97]
	v_mfma_f32_16x16x32_bf16 v[90:93], v[184:187], v[224:227], v[90:93]
	v_mfma_f32_16x16x32_bf16 v[86:89], v[192:195], v[216:219], v[86:89]
	v_mfma_f32_16x16x32_bf16 v[82:85], v[192:195], v[224:227], v[82:85]
	v_mfma_f32_16x16x32_bf16 v[78:81], v[200:203], v[216:219], v[78:81]
	v_mfma_f32_16x16x32_bf16 v[74:77], v[200:203], v[224:227], v[74:77]
	v_mfma_f32_16x16x32_bf16 v[70:73], v[208:211], v[216:219], v[70:73]
	v_mfma_f32_16x16x32_bf16 v[66:69], v[208:211], v[224:227], v[66:69]
	s_barrier
	s_add_u32 s42, s42, 0x180
	s_addc_u32 s43, s43, 0
	s_mov_b32 m0, s18
	ds_read_b128 v[164:167], v133 offset:49152
	ds_read_b128 v[184:187], v133 offset:50176
	ds_read_b128 v[188:191], v134 offset:49152
	ds_read_b128 v[192:195], v134 offset:50176
	ds_read_b128 v[196:199], v137 offset:49152
	ds_read_b128 v[200:203], v137 offset:50176
	ds_read_b128 v[204:207], v139 offset:49152
	ds_read_b128 v[208:211], v139 offset:50176
	s_nop 0
	v_lshl_add_u64 v[228:229], s[42:43], 0, v[0:1]
	global_load_lds_dwordx4 v[228:229], off
	v_lshl_add_u64 v[228:229], s[42:43], 0, v[140:141]
	s_mov_b32 m0, s19
	s_nop 0
	global_load_lds_dwordx4 v[228:229], off
	s_barrier
; #define LDA(dst, b, h) for (int m = 0; m < 4; ++m) for (int k = 0; k < 2; ++k) \
;     dst[m][k] = *reinterpret_cast<const bf16x8*>((char*)SA(b, h) + lds_byte(wr * 64 + m * 16 + fr, k * 32 + fq * 8))
; #define LDB(dst, b, h) for (int n = 0; n < 2; ++n) for (int k = 0; k < 2; ++k) \
;     dst[n][k] = *reinterpret_cast<const bf16x8*>((char*)SB(b, h) + lds_byte(wc * 32 + n * 16 + fr, k * 32 + fq * 8))
; #define MMA(ai, bj, At, Bt_) do { __builtin_amdgcn_s_setprio(1); \
;     for (int m = 0; m < 4; ++m) for (int n = 0; n < 2; ++n) for (int k = 0; k < 2; ++k) \
;       acc[ai][bj][m][n] = __builtin_amdgcn_mfma_f32_16x16x32_bf16(At[m][k], Bt_[n][k], acc[ai][bj][m][n], 0, 0, 0); \
;     __builtin_amdgcn_s_setprio(0); } while (0)
; #define WAIT_V(n) asm volatile("s_waitcnt vmcnt(" #n ")" ::: "memory")
; #define WAIT_L(n) asm volatile("s_waitcnt lgkmcnt(" #n ")" ::: "memory")
; #define BAR __builtin_amdgcn_s_barrier()
; #define SCHED __builtin_amdgcn_sched_barrier(0)
;     ...
;       BAR; WAIT_L(0); MMA(1, 0, At, B0); BAR; SCHED;
;       STAGE(SB(1, 1), Bt, bcol + HALF, t + 3);
;       WAIT_V(6); BAR; MMA(1, 1, At, B1); BAR;
;     }
;     { LDB(B0, 0, 0); LDA(At, 0, 0); STAGE(SA(1, 1), A, brow + HALF, nt - 1);
;       BAR; WAIT_L(0); MMA(0, 0, At, B0); BAR;
;       LDB(B1, 0, 1); BAR; WAIT_L(0); MMA(0, 1, At, B1); BAR;
;       LDA(At, 0, 1); WAIT_V(4); BAR; WAIT_L(0); MMA(1, 0, At, B0); MMA(1, 1, At, B1); BAR; }
	s_waitcnt lgkmcnt(0)
	s_waitcnt lgkmcnt(0)
	v_mfma_f32_16x16x32_bf16 v[62:65], v[164:167], v[148:151], v[62:65]
	v_mfma_f32_16x16x32_bf16 v[58:61], v[164:167], v[156:159], v[58:61]
	v_mfma_f32_16x16x32_bf16 v[54:57], v[188:191], v[148:151], v[54:57]
	v_mfma_f32_16x16x32_bf16 v[50:53], v[188:191], v[156:159], v[50:53]
	v_mfma_f32_16x16x32_bf16 v[46:49], v[196:199], v[148:151], v[46:49]
	v_mfma_f32_16x16x32_bf16 v[42:45], v[196:199], v[156:159], v[42:45]
	v_mfma_f32_16x16x32_bf16 v[38:41], v[204:207], v[148:151], v[38:41]
	v_mfma_f32_16x16x32_bf16 v[34:37], v[204:207], v[156:159], v[34:37]
	v_mfma_f32_16x16x32_bf16 v[62:65], v[184:187], v[152:155], v[62:65]
	v_mfma_f32_16x16x32_bf16 v[58:61], v[184:187], v[160:163], v[58:61]
	v_mfma_f32_16x16x32_bf16 v[54:57], v[192:195], v[152:155], v[54:57]
	v_mfma_f32_16x16x32_bf16 v[50:53], v[192:195], v[160:163], v[50:53]
	v_mfma_f32_16x16x32_bf16 v[46:49], v[200:203], v[152:155], v[46:49]
	v_mfma_f32_16x16x32_bf16 v[42:45], v[200:203], v[160:163], v[42:45]
	v_mfma_f32_16x16x32_bf16 v[38:41], v[208:211], v[152:155], v[38:41]
	v_mfma_f32_16x16x32_bf16 v[34:37], v[208:211], v[160:163], v[34:37]
	s_barrier
	s_add_u32 s42, s44, 0x80180
	s_addc_u32 s43, s45, 0
	s_mov_b32 m0, s20
	s_nop 0
	v_lshl_add_u64 v[148:149], s[42:43], 0, v[0:1]
	global_load_lds_dwordx4 v[148:149], off
	v_lshl_add_u64 v[148:149], s[42:43], 0, v[140:141]
	s_mov_b32 m0, s21
	s_nop 0
	global_load_lds_dwordx4 v[148:149], off
	s_add_i32 s36, s36, 2
	s_add_u32 s6, s6, 0x100
	s_addc_u32 s7, s7, 0
	s_cmp_gt_u32 s36, 27
	s_waitcnt vmcnt(6)
	s_barrier
	v_mfma_f32_16x16x32_bf16 v[30:33], v[164:167], v[212:215], v[30:33]
	v_mfma_f32_16x16x32_bf16 v[26:29], v[164:167], v[220:223], v[26:29]
	v_mfma_f32_16x16x32_bf16 v[22:25], v[188:191], v[212:215], v[22:25]
	v_mfma_f32_16x16x32_bf16 v[18:21], v[188:191], v[220:223], v[18:21]
	v_mfma_f32_16x16x32_bf16 v[14:17], v[196:199], v[212:215], v[14:17]
	v_mfma_f32_16x16x32_bf16 v[10:13], v[196:199], v[220:223], v[10:13]
	v_mfma_f32_16x16x32_bf16 v[6:9], v[204:207], v[212:215], v[6:9]
	v_mfma_f32_16x16x32_bf16 v[2:5], v[204:207], v[220:223], v[2:5]
	v_mfma_f32_16x16x32_bf16 v[30:33], v[184:187], v[216:219], v[30:33]
	v_mfma_f32_16x16x32_bf16 v[26:29], v[184:187], v[224:227], v[26:29]
	v_mfma_f32_16x16x32_bf16 v[22:25], v[192:195], v[216:219], v[22:25]
	v_mfma_f32_16x16x32_bf16 v[18:21], v[192:195], v[224:227], v[18:21]
	v_mfma_f32_16x16x32_bf16 v[14:17], v[200:203], v[216:219], v[14:17]
	v_mfma_f32_16x16x32_bf16 v[10:13], v[200:203], v[224:227], v[10:13]
	v_mfma_f32_16x16x32_bf16 v[6:9], v[208:211], v[216:219], v[6:9]
	v_mfma_f32_16x16x32_bf16 v[2:5], v[208:211], v[224:227], v[2:5]
	s_barrier
	s_cbranch_scc0 .LBB0_418
	s_add_u32 s4, s4, 0xf80
	s_addc_u32 s5, s5, 0
	s_mov_b32 m0, s41
	ds_read_b128 v[148:151], v143
	ds_read_b128 v[152:155], v143 offset:1024
	ds_read_b128 v[156:159], v143 offset:2048
	ds_read_b128 v[160:163], v143 offset:3072
	ds_read_b128 v[164:167], v133
	ds_read_b128 v[184:187], v133 offset:1024
	ds_read_b128 v[188:191], v134
	ds_read_b128 v[192:195], v134 offset:1024
	ds_read_b128 v[196:199], v137
	ds_read_b128 v[200:203], v137 offset:1024
	ds_read_b128 v[204:207], v139
	ds_read_b128 v[208:211], v139 offset:1024
	s_nop 0
	v_lshl_add_u64 v[142:143], s[4:5], 0, v[0:1]
	global_load_lds_dwordx4 v[142:143], off
	v_lshl_add_u64 v[140:141], s[4:5], 0, v[140:141]
	s_mov_b32 m0, s37
	s_nop 0
	global_load_lds_dwordx4 v[140:141], off
	s_barrier
	s_waitcnt lgkmcnt(0)
	s_setprio 1
	s_waitcnt lgkmcnt(0)
	v_mfma_f32_16x16x32_bf16 v[126:129], v[164:167], v[148:151], v[126:129]
	v_mfma_f32_16x16x32_bf16 v[122:125], v[164:167], v[156:159], v[122:125]
	v_mfma_f32_16x16x32_bf16 v[118:121], v[188:191], v[148:151], v[118:121]
	v_mfma_f32_16x16x32_bf16 v[110:113], v[196:199], v[148:151], v[110:113]
	v_mfma_f32_16x16x32_bf16 v[106:109], v[196:199], v[156:159], v[106:109]
	v_mfma_f32_16x16x32_bf16 v[102:105], v[204:207], v[148:151], v[102:105]
	v_mfma_f32_16x16x32_bf16 v[98:101], v[204:207], v[156:159], v[98:101]
	v_mfma_f32_16x16x32_bf16 v[126:129], v[184:187], v[152:155], v[126:129]
	v_mfma_f32_16x16x32_bf16 v[122:125], v[184:187], v[160:163], v[122:125]
	v_mfma_f32_16x16x32_bf16 v[118:121], v[192:195], v[152:155], v[118:121]
	v_mfma_f32_16x16x32_bf16 v[114:117], v[188:191], v[156:159], v[114:117]
	v_mfma_f32_16x16x32_bf16 v[110:113], v[200:203], v[152:155], v[110:113]
	v_mfma_f32_16x16x32_bf16 v[106:109], v[200:203], v[160:163], v[106:109]
	v_mfma_f32_16x16x32_bf16 v[102:105], v[208:211], v[152:155], v[102:105]
	v_mfma_f32_16x16x32_bf16 v[98:101], v[208:211], v[160:163], v[98:101]
	v_mfma_f32_16x16x32_bf16 v[140:143], v[192:195], v[160:163], v[114:117]
	s_setprio 0
	s_barrier
	s_nop 0
	ds_read_b128 v[114:117], v144
	ds_read_b128 v[212:215], v144 offset:1024
	ds_read_b128 v[216:219], v144 offset:2048
	ds_read_b128 v[220:223], v144 offset:3072
	s_barrier
	s_waitcnt lgkmcnt(0)
	s_setprio 1
	s_waitcnt lgkmcnt(0)
	v_mfma_f32_16x16x32_bf16 v[90:93], v[164:167], v[216:219], v[90:93]
	v_mfma_f32_16x16x32_bf16 v[86:89], v[188:191], v[114:117], v[86:89]
	v_mfma_f32_16x16x32_bf16 v[94:97], v[164:167], v[114:117], v[94:97]
	v_mfma_f32_16x16x32_bf16 v[90:93], v[184:187], v[220:223], v[90:93]
	v_mfma_f32_16x16x32_bf16 v[86:89], v[192:195], v[212:215], v[86:89]
	v_mfma_f32_16x16x32_bf16 v[82:85], v[188:191], v[216:219], v[82:85]
	v_mfma_f32_16x16x32_bf16 v[78:81], v[196:199], v[114:117], v[78:81]
	v_mfma_f32_16x16x32_bf16 v[74:77], v[196:199], v[216:219], v[74:77]
	v_mfma_f32_16x16x32_bf16 v[70:73], v[204:207], v[114:117], v[70:73]
	v_mfma_f32_16x16x32_bf16 v[66:69], v[204:207], v[216:219], v[66:69]
	v_mfma_f32_16x16x32_bf16 v[224:227], v[184:187], v[212:215], v[94:97]
	v_mfma_f32_16x16x32_bf16 v[164:167], v[192:195], v[220:223], v[82:85]
	v_mfma_f32_16x16x32_bf16 v[184:187], v[200:203], v[212:215], v[78:81]
	v_mfma_f32_16x16x32_bf16 v[188:191], v[200:203], v[220:223], v[74:77]
	v_mfma_f32_16x16x32_bf16 v[192:195], v[208:211], v[212:215], v[70:73]
	v_mfma_f32_16x16x32_bf16 v[196:199], v[208:211], v[220:223], v[66:69]
	s_setprio 0
	s_barrier
; #define LDA(dst, b, h) for (int m = 0; m < 4; ++m) for (int k = 0; k < 2; ++k) \
;     dst[m][k] = *reinterpret_cast<const bf16x8*>((char*)SA(b, h) + lds_byte(wr * 64 + m * 16 + fr, k * 32 + fq * 8))
; #define LDB(dst, b, h) for (int n = 0; n < 2; ++n) for (int k = 0; k < 2; ++k) \
;     dst[n][k] = *reinterpret_cast<const bf16x8*>((char*)SB(b, h) + lds_byte(wc * 32 + n * 16 + fr, k * 32 + fq * 8))
; #define MMA(ai, bj, At, Bt_) do { __builtin_amdgcn_s_setprio(1); \
;     for (int m = 0; m < 4; ++m) for (int n = 0; n < 2; ++n) for (int k = 0; k < 2; ++k) \
;       acc[ai][bj][m][n] = __builtin_amdgcn_mfma_f32_16x16x32_bf16(At[m][k], Bt_[n][k], acc[ai][bj][m][n], 0, 0, 0); \
;     __builtin_amdgcn_s_setprio(0); } while (0)
; #define WAIT_V(n) asm volatile("s_waitcnt vmcnt(" #n ")" ::: "memory")
; #define WAIT_L(n) asm volatile("s_waitcnt lgkmcnt(" #n ")" ::: "memory")
; #define BAR __builtin_amdgcn_s_barrier()
;     ...
;       LDA(At, 0, 1); WAIT_V(4); BAR; WAIT_L(0); MMA(1, 0, At, B0); MMA(1, 1, At, B1); BAR; }
;     { LDB(B0, 1, 0); LDA(At, 1, 0); WAIT_V(2); BAR; WAIT_L(0); MMA(0, 0, At, B0); BAR;
	s_nop 0
	ds_read_b128 v[66:69], v133 offset:16384
	ds_read_b128 v[70:73], v133 offset:17408
	ds_read_b128 v[74:77], v134 offset:16384
	ds_read_b128 v[78:81], v134 offset:17408
	ds_read_b128 v[82:85], v137 offset:16384
	ds_read_b128 v[94:97], v137 offset:17408
	ds_read_b128 v[200:203], v139 offset:16384
	ds_read_b128 v[204:207], v139 offset:17408
	s_waitcnt vmcnt(4)
	s_barrier
	s_waitcnt lgkmcnt(0)
	s_setprio 1
	s_waitcnt lgkmcnt(0)
	v_mfma_f32_16x16x32_bf16 v[62:65], v[66:69], v[148:151], v[62:65]
	v_mfma_f32_16x16x32_bf16 v[58:61], v[66:69], v[156:159], v[58:61]
	v_mfma_f32_16x16x32_bf16 v[54:57], v[74:77], v[148:151], v[54:57]
	v_mfma_f32_16x16x32_bf16 v[50:53], v[74:77], v[156:159], v[50:53]
	v_mfma_f32_16x16x32_bf16 v[46:49], v[82:85], v[148:151], v[46:49]
	v_mfma_f32_16x16x32_bf16 v[42:45], v[82:85], v[156:159], v[42:45]
	v_mfma_f32_16x16x32_bf16 v[38:41], v[200:203], v[148:151], v[38:41]
	v_mfma_f32_16x16x32_bf16 v[34:37], v[200:203], v[156:159], v[34:37]
	v_mfma_f32_16x16x32_bf16 v[62:65], v[70:73], v[152:155], v[62:65]
	v_mfma_f32_16x16x32_bf16 v[58:61], v[70:73], v[160:163], v[58:61]
	v_mfma_f32_16x16x32_bf16 v[54:57], v[78:81], v[152:155], v[54:57]
	v_mfma_f32_16x16x32_bf16 v[50:53], v[78:81], v[160:163], v[50:53]
	v_mfma_f32_16x16x32_bf16 v[46:49], v[94:97], v[152:155], v[46:49]
	v_mfma_f32_16x16x32_bf16 v[42:45], v[94:97], v[160:163], v[42:45]
	v_mfma_f32_16x16x32_bf16 v[38:41], v[204:207], v[152:155], v[38:41]
	v_mfma_f32_16x16x32_bf16 v[34:37], v[204:207], v[160:163], v[34:37]
	s_setprio 0
	s_setprio 1
	v_mfma_f32_16x16x32_bf16 v[30:33], v[66:69], v[114:117], v[30:33]
	v_mfma_f32_16x16x32_bf16 v[26:29], v[66:69], v[216:219], v[26:29]
	v_mfma_f32_16x16x32_bf16 v[22:25], v[74:77], v[114:117], v[22:25]
	v_mfma_f32_16x16x32_bf16 v[18:21], v[74:77], v[216:219], v[18:21]
	v_mfma_f32_16x16x32_bf16 v[14:17], v[82:85], v[114:117], v[14:17]
	v_mfma_f32_16x16x32_bf16 v[10:13], v[82:85], v[216:219], v[10:13]
	v_mfma_f32_16x16x32_bf16 v[6:9], v[200:203], v[114:117], v[6:9]
	v_mfma_f32_16x16x32_bf16 v[2:5], v[200:203], v[216:219], v[2:5]
	v_mfma_f32_16x16x32_bf16 v[148:151], v[70:73], v[212:215], v[30:33]
	v_mfma_f32_16x16x32_bf16 v[152:155], v[70:73], v[220:223], v[26:29]
	v_mfma_f32_16x16x32_bf16 v[156:159], v[78:81], v[212:215], v[22:25]
	v_mfma_f32_16x16x32_bf16 v[160:163], v[78:81], v[220:223], v[18:21]
	v_mfma_f32_16x16x32_bf16 v[208:211], v[94:97], v[212:215], v[14:17]
	v_mfma_f32_16x16x32_bf16 v[228:231], v[94:97], v[220:223], v[10:13]
	v_mfma_f32_16x16x32_bf16 v[212:215], v[204:207], v[212:215], v[6:9]
	v_mfma_f32_16x16x32_bf16 v[200:203], v[204:207], v[220:223], v[2:5]
	s_setprio 0
	s_barrier
	ds_read_b128 v[14:17], v145
	ds_read_b128 v[30:33], v145 offset:1024
	ds_read_b128 v[204:207], v145 offset:2048
	ds_read_b128 v[216:219], v145 offset:3072
	ds_read_b128 v[2:5], v133 offset:32768
	ds_read_b128 v[6:9], v133 offset:33792
	ds_read_b128 v[10:13], v134 offset:32768
	ds_read_b128 v[18:21], v134 offset:33792
	ds_read_b128 v[22:25], v137 offset:32768
	ds_read_b128 v[26:29], v137 offset:33792
	ds_read_b128 v[220:223], v139 offset:32768
	ds_read_b128 v[232:235], v139 offset:33792
	s_waitcnt vmcnt(2)
	s_barrier
	s_waitcnt lgkmcnt(0)
	s_setprio 1
	s_waitcnt lgkmcnt(0)
	v_mfma_f32_16x16x32_bf16 v[66:69], v[2:5], v[14:17], v[126:129]
	v_mfma_f32_16x16x32_bf16 v[114:117], v[6:9], v[30:33], v[66:69]
	v_mfma_f32_16x16x32_bf16 v[66:69], v[2:5], v[204:207], v[122:125]
	v_mfma_f32_16x16x32_bf16 v[126:129], v[6:9], v[216:219], v[66:69]
	v_mfma_f32_16x16x32_bf16 v[66:69], v[10:13], v[14:17], v[118:121]
	v_mfma_f32_16x16x32_bf16 v[82:85], v[18:21], v[30:33], v[66:69]
	v_mfma_f32_16x16x32_bf16 v[66:69], v[10:13], v[204:207], v[140:143]
	v_mfma_f32_16x16x32_bf16 v[94:97], v[18:21], v[216:219], v[66:69]
	v_mfma_f32_16x16x32_bf16 v[66:69], v[22:25], v[14:17], v[110:113]
	v_mfma_f32_16x16x32_bf16 v[74:77], v[26:29], v[30:33], v[66:69]
	v_mfma_f32_16x16x32_bf16 v[66:69], v[22:25], v[204:207], v[106:109]
	v_mfma_f32_16x16x32_bf16 v[78:81], v[26:29], v[216:219], v[66:69]
	v_mfma_f32_16x16x32_bf16 v[66:69], v[220:223], v[14:17], v[102:105]
	v_mfma_f32_16x16x32_bf16 v[70:73], v[220:223], v[204:207], v[98:101]
	v_mfma_f32_16x16x32_bf16 v[66:69], v[232:235], v[30:33], v[66:69]
	v_mfma_f32_16x16x32_bf16 v[70:73], v[232:235], v[216:219], v[70:73]
	s_setprio 0
	s_barrier
; #define LDA(dst, b, h) for (int m = 0; m < 4; ++m) for (int k = 0; k < 2; ++k) \
;     dst[m][k] = *reinterpret_cast<const bf16x8*>((char*)SA(b, h) + lds_byte(wr * 64 + m * 16 + fr, k * 32 + fq * 8))
; #define LDB(dst, b, h) for (int n = 0; n < 2; ++n) for (int k = 0; k < 2; ++k) \
;     dst[n][k] = *reinterpret_cast<const bf16x8*>((char*)SB(b, h) + lds_byte(wc * 32 + n * 16 + fr, k * 32 + fq * 8))
; #define MMA(ai, bj, At, Bt_) do { __builtin_amdgcn_s_setprio(1); \
;     for (int m = 0; m < 4; ++m) for (int n = 0; n < 2; ++n) for (int k = 0; k < 2; ++k) \
;       acc[ai][bj][m][n] = __builtin_amdgcn_mfma_f32_16x16x32_bf16(At[m][k], Bt_[n][k], acc[ai][bj][m][n], 0, 0, 0); \
;     __builtin_amdgcn_s_setprio(0); } while (0)
; #define WAIT_V(n) asm volatile("s_waitcnt vmcnt(" #n ")" ::: "memory")
; #define WAIT_L(n) asm volatile("s_waitcnt lgkmcnt(" #n ")" ::: "memory")
; #define BAR __builtin_amdgcn_s_barrier()
;     ...
;     { LDB(B0, 1, 0); LDA(At, 1, 0); WAIT_V(2); BAR; WAIT_L(0); MMA(0, 0, At, B0); BAR;
;       LDB(B1, 1, 1); WAIT_V(0); BAR; WAIT_L(0); MMA(0, 1, At, B1); BAR;
;       LDA(At, 1, 1); BAR; WAIT_L(0); MMA(1, 0, At, B0); MMA(1, 1, At, B1); BAR; }
;     if (wr == 0) BAR;
	ds_read_b128 v[140:143], v146
	ds_read_b128 v[236:239], v146 offset:1024
	ds_read_b128 v[240:243], v146 offset:2048
	ds_read_b128 v[144:147], v146 offset:3072
	s_waitcnt vmcnt(0)
	s_barrier
	s_waitcnt lgkmcnt(0)
	s_setprio 1
	s_waitcnt lgkmcnt(0)
	v_mfma_f32_16x16x32_bf16 v[98:101], v[2:5], v[140:143], v[224:227]
	v_mfma_f32_16x16x32_bf16 v[2:5], v[2:5], v[240:243], v[90:93]
	v_mfma_f32_16x16x32_bf16 v[118:121], v[6:9], v[144:147], v[2:5]
	v_mfma_f32_16x16x32_bf16 v[2:5], v[10:13], v[140:143], v[86:89]
	v_mfma_f32_16x16x32_bf16 v[102:105], v[18:21], v[236:239], v[2:5]
	v_mfma_f32_16x16x32_bf16 v[2:5], v[10:13], v[240:243], v[164:167]
	v_mfma_f32_16x16x32_bf16 v[122:125], v[18:21], v[144:147], v[2:5]
	v_mfma_f32_16x16x32_bf16 v[2:5], v[22:25], v[140:143], v[184:187]
	v_mfma_f32_16x16x32_bf16 v[90:93], v[26:29], v[236:239], v[2:5]
	v_mfma_f32_16x16x32_bf16 v[2:5], v[22:25], v[240:243], v[188:191]
	v_mfma_f32_16x16x32_bf16 v[110:113], v[26:29], v[144:147], v[2:5]
	v_mfma_f32_16x16x32_bf16 v[2:5], v[220:223], v[140:143], v[192:195]
	v_mfma_f32_16x16x32_bf16 v[86:89], v[232:235], v[236:239], v[2:5]
	v_mfma_f32_16x16x32_bf16 v[2:5], v[220:223], v[240:243], v[196:199]
	v_mfma_f32_16x16x32_bf16 v[98:101], v[6:9], v[236:239], v[98:101]
	v_mfma_f32_16x16x32_bf16 v[106:109], v[232:235], v[144:147], v[2:5]
	s_setprio 0
	s_barrier
	ds_read_b128 v[164:167], v133 offset:49152
	ds_read_b128 v[184:187], v133 offset:50176
	ds_read_b128 v[188:191], v134 offset:49152
	ds_read_b128 v[192:195], v134 offset:50176
	ds_read_b128 v[196:199], v137 offset:49152
	ds_read_b128 v[220:223], v137 offset:50176
	ds_read_b128 v[224:227], v139 offset:49152
	ds_read_b128 v[232:235], v139 offset:50176
	s_barrier
	s_waitcnt lgkmcnt(0)
	s_setprio 1
	s_waitcnt lgkmcnt(0)
	v_mfma_f32_16x16x32_bf16 v[6:9], v[164:167], v[204:207], v[58:61]
	v_mfma_f32_16x16x32_bf16 v[10:13], v[188:191], v[204:207], v[50:53]
	v_mfma_f32_16x16x32_bf16 v[2:5], v[164:167], v[14:17], v[62:65]
	v_mfma_f32_16x16x32_bf16 v[18:21], v[184:187], v[216:219], v[6:9]
	v_mfma_f32_16x16x32_bf16 v[6:9], v[188:191], v[14:17], v[54:57]
	v_mfma_f32_16x16x32_bf16 v[22:25], v[192:195], v[216:219], v[10:13]
	v_mfma_f32_16x16x32_bf16 v[10:13], v[196:199], v[14:17], v[46:49]
	v_mfma_f32_16x16x32_bf16 v[14:17], v[224:227], v[14:17], v[38:41]
	v_mfma_f32_16x16x32_bf16 v[2:5], v[184:187], v[30:33], v[2:5]
	v_mfma_f32_16x16x32_bf16 v[6:9], v[192:195], v[30:33], v[6:9]
	v_mfma_f32_16x16x32_bf16 v[10:13], v[220:223], v[30:33], v[10:13]
	v_mfma_f32_16x16x32_bf16 v[26:29], v[196:199], v[204:207], v[42:45]
	v_mfma_f32_16x16x32_bf16 v[14:17], v[232:235], v[30:33], v[14:17]
	v_mfma_f32_16x16x32_bf16 v[30:33], v[224:227], v[204:207], v[34:37]
	v_mfma_f32_16x16x32_bf16 v[26:29], v[220:223], v[216:219], v[26:29]
	v_mfma_f32_16x16x32_bf16 v[30:33], v[232:235], v[216:219], v[30:33]
	s_setprio 0
	s_setprio 1
	v_mfma_f32_16x16x32_bf16 v[38:41], v[164:167], v[240:243], v[152:155]
	v_mfma_f32_16x16x32_bf16 v[42:45], v[188:191], v[240:243], v[160:163]
	v_mfma_f32_16x16x32_bf16 v[46:49], v[196:199], v[240:243], v[228:231]
	v_mfma_f32_16x16x32_bf16 v[34:37], v[164:167], v[140:143], v[148:151]
	v_mfma_f32_16x16x32_bf16 v[50:53], v[184:187], v[144:147], v[38:41]
	v_mfma_f32_16x16x32_bf16 v[38:41], v[188:191], v[140:143], v[156:159]
	v_mfma_f32_16x16x32_bf16 v[54:57], v[192:195], v[144:147], v[42:45]
	v_mfma_f32_16x16x32_bf16 v[42:45], v[196:199], v[140:143], v[208:211]
	v_mfma_f32_16x16x32_bf16 v[58:61], v[220:223], v[144:147], v[46:49]
	v_mfma_f32_16x16x32_bf16 v[46:49], v[224:227], v[140:143], v[212:215]
	v_mfma_f32_16x16x32_bf16 v[62:65], v[224:227], v[240:243], v[200:203]
	v_mfma_f32_16x16x32_bf16 v[34:37], v[184:187], v[236:239], v[34:37]
	v_mfma_f32_16x16x32_bf16 v[38:41], v[192:195], v[236:239], v[38:41]
	v_mfma_f32_16x16x32_bf16 v[42:45], v[220:223], v[236:239], v[42:45]
	v_mfma_f32_16x16x32_bf16 v[46:49], v[232:235], v[236:239], v[46:49]
	v_mfma_f32_16x16x32_bf16 v[62:65], v[232:235], v[144:147], v[62:65]
	s_setprio 0
	v_readlane_b32 s4, v245, 33
	v_readlane_b32 s5, v245, 34
	s_and_b64 vcc, exec, s[4:5]
	s_barrier
	s_cbranch_vccz .LBB0_421
	s_barrier
